# K-loop MFMA segments: s_setprio 0/1 flip every 8 MFMAs (was every 16) so the partner half's load segment gets issue windows
# baseline (speedup 1.0000x reference)
; #define PG8_STAGE(bufoff, gbase, voff) do { _Pragma("unroll") for (int _i = 0; _i < 2; ++_i) \
;         __builtin_amdgcn_global_load_lds((const unsigned*)((const char*)(gbase) + (voff)[_i]), (LAS unsigned*)(lds + (bufoff) + ldsw + _i * 8192), 16, 0, 0); } while (0)
; #define PG8_LDA(dst, b, h) do { _Pragma("unroll") for (int m = 0; m < 4; ++m) _Pragma("unroll") for (int k = 0; k < 2; ++k) dst[m][k] = *(const LAS bf16x8*)(lds + PG8_SA(b, h) + aoff + m * 2048 + k * 1024); } while (0)
; #define PG8_LDB(dst, b, h) do { _Pragma("unroll") for (int n = 0; n < 2; ++n) _Pragma("unroll") for (int k = 0; k < 2; ++k) dst[n][k] = *(const LAS bf16x8*)(lds + PG8_SB(b, h) + boff + n * 2048 + k * 1024); } while (0)
; #define PG8_WAIT_V(n) asm volatile("s_waitcnt vmcnt(" #n ")" ::: "memory")
; #define PG8_WAIT_L(n) asm volatile("s_waitcnt lgkmcnt(" #n ")" ::: "memory")
; #define PG8_BAR __builtin_amdgcn_s_barrier()
; #define PG8_SCHED __builtin_amdgcn_sched_barrier(0)
; template <class Epi, bool ALIGN_EPI = PG8_ALIGN, bool SP2 = PG8_SP2>
; __device__ __forceinline__ void gemm_phase(LAS unsigned char* lds, const Gemm g, const StaticOrder& S, const Epi& E) {
;     ...
;         const bool has_next = S.next(ui + 1, nxt);
;         const char* nA = has_next ? (const char*)g.A + (size_t)nxt.pm * tstepA : cA; const char* nB = has_next ? (const char*)g.Bt + (size_t)nxt.pn * tstepB : cB;
;         for (int t = 0; t < nt; t += 2) {
;             const bool last = (t == nt - 2);
;             const char* a1 = cA + (size_t)(t + 1) * kstepA;
;             const char* a2 = last ? nA : cA + (size_t)(t + 2) * kstepA; const char* b2 = last ? nB : cB + (size_t)(t + 2) * kstepB;
;             const char* a3 = a2 + kstepA; const char* b3 = b2 + kstepB;
;             if constexpr (SP2) {
;             PG8_LDB(B0, 0, 0); PG8_LDB(B1, 0, 1); PG8_SCHED; PG8_LDA(At, 0, 0); PG8_STAGE(PG8_SA(1, 1), a1 + hstepA, voffA);
;             PG8_WAIT_V(8); PG8_WAIT_L(0); PG8_BAR; PG8_MMA(0, 0, At, B0); PG8_MMA(0, 1, At, B1); PG8_BAR; PG8_SCHED;
;             PG8_LDA(At, 0, 1); PG8_STAGE(PG8_SB(0, 0), b2, voffB); PG8_STAGE(PG8_SB(0, 1), b2 + hstepB, voffB); PG8_STAGE(PG8_SA(0, 0), a2, voffA);
;             PG8_WAIT_V(8); PG8_WAIT_L(0); PG8_BAR; PG8_MMA(1, 0, At, B0); PG8_MMA(1, 1, At, B1); PG8_BAR; PG8_SCHED;
.LBB0_139:
	s_cmp_eq_u32 s40, -2
	s_cbranch_scc1 .Lfirst_iter_u139
	s_add_u32 s22, s4, 0xfffc0080
	s_addc_u32 s23, s5, -1
	s_add_i32 s41, 0, 0x10000
	s_cmp_eq_u32 s40, 12
	s_cselect_b32 s25, s17, s23
	s_cselect_b32 s24, s36, s22
	v_add_u32_e32 v0, s41, v143
	s_cselect_b32 s23, s15, s39
	s_cselect_b32 s22, s37, s38
	s_add_i32 s44, 0, 0x14000
	ds_read_b128 v[138:141], v0
	ds_read_b128 v[146:149], v0 offset:1024
	ds_read_b128 v[150:153], v0 offset:2048
	ds_read_b128 v[154:157], v0 offset:3072
	v_add_u32_e32 v0, s44, v143
	ds_read_b128 v[158:161], v0
	ds_read_b128 v[164:167], v0 offset:1024
	ds_read_b128 v[170:173], v0 offset:2048
	ds_read_b128 v[174:177], v0 offset:3072
	v_lshl_add_u64 v[190:191], s[4:5], 0, v[134:135]
	s_add_i32 m0, s26, 0xc000
	ds_read_b128 v[178:181], v145
	ds_read_b128 v[182:185], v145 offset:1024
	ds_read_b128 v[186:189], v145 offset:2048
	ds_read_b128 v[194:197], v145 offset:3072
	ds_read_b128 v[206:209], v145 offset:4096
	ds_read_b128 v[210:213], v145 offset:5120
	ds_read_b128 v[214:217], v145 offset:6144
	ds_read_b128 v[218:221], v145 offset:7168
	global_load_lds_dwordx4 v[190:191], off
	v_lshl_add_u64 v[190:191], s[4:5], 0, v[136:137]
	s_add_i32 m0, s26, 0xe000
	s_nop 0
	global_load_lds_dwordx4 v[190:191], off
	s_waitcnt vmcnt(8)
	s_waitcnt lgkmcnt(0)
	s_barrier
	s_setprio 1
	s_waitcnt lgkmcnt(0)
	v_mfma_f32_16x16x32_bf16 v[126:129], v[138:141], v[178:181], v[126:129]
	v_mfma_f32_16x16x32_bf16 v[122:125], v[150:153], v[178:181], v[122:125]
	v_mfma_f32_16x16x32_bf16 v[110:113], v[138:141], v[186:189], v[110:113]
	v_mfma_f32_16x16x32_bf16 v[106:109], v[150:153], v[186:189], v[106:109]
	v_mfma_f32_16x16x32_bf16 v[94:97], v[138:141], v[206:209], v[94:97]
	v_mfma_f32_16x16x32_bf16 v[90:93], v[150:153], v[206:209], v[90:93]
	v_mfma_f32_16x16x32_bf16 v[78:81], v[138:141], v[214:217], v[78:81]
	v_mfma_f32_16x16x32_bf16 v[74:77], v[150:153], v[214:217], v[74:77]
	s_setprio 0
	s_setprio 1
	v_mfma_f32_16x16x32_bf16 v[126:129], v[146:149], v[182:185], v[126:129]
	v_mfma_f32_16x16x32_bf16 v[122:125], v[154:157], v[182:185], v[122:125]
	v_mfma_f32_16x16x32_bf16 v[110:113], v[146:149], v[194:197], v[110:113]
	v_mfma_f32_16x16x32_bf16 v[106:109], v[154:157], v[194:197], v[106:109]
	v_mfma_f32_16x16x32_bf16 v[94:97], v[146:149], v[210:213], v[94:97]
	v_mfma_f32_16x16x32_bf16 v[90:93], v[154:157], v[210:213], v[90:93]
	v_mfma_f32_16x16x32_bf16 v[78:81], v[146:149], v[218:221], v[78:81]
	v_mfma_f32_16x16x32_bf16 v[74:77], v[154:157], v[218:221], v[74:77]
	s_setprio 0
	s_setprio 1
	v_mfma_f32_16x16x32_bf16 v[118:121], v[158:161], v[178:181], v[118:121]
	v_mfma_f32_16x16x32_bf16 v[114:117], v[170:173], v[178:181], v[114:117]
	v_mfma_f32_16x16x32_bf16 v[102:105], v[158:161], v[186:189], v[102:105]
	v_mfma_f32_16x16x32_bf16 v[98:101], v[170:173], v[186:189], v[98:101]
	v_mfma_f32_16x16x32_bf16 v[86:89], v[158:161], v[206:209], v[86:89]
	v_mfma_f32_16x16x32_bf16 v[82:85], v[170:173], v[206:209], v[82:85]
	v_mfma_f32_16x16x32_bf16 v[70:73], v[158:161], v[214:217], v[70:73]
	v_mfma_f32_16x16x32_bf16 v[66:69], v[170:173], v[214:217], v[66:69]
	s_setprio 0
	s_setprio 1
	v_mfma_f32_16x16x32_bf16 v[118:121], v[164:167], v[182:185], v[118:121]
	v_mfma_f32_16x16x32_bf16 v[114:117], v[174:177], v[182:185], v[114:117]
	v_mfma_f32_16x16x32_bf16 v[102:105], v[164:167], v[194:197], v[102:105]
	v_mfma_f32_16x16x32_bf16 v[98:101], v[174:177], v[194:197], v[98:101]
	v_mfma_f32_16x16x32_bf16 v[86:89], v[164:167], v[210:213], v[86:89]
	v_mfma_f32_16x16x32_bf16 v[82:85], v[174:177], v[210:213], v[82:85]
	v_mfma_f32_16x16x32_bf16 v[70:73], v[164:167], v[218:221], v[70:73]
	v_mfma_f32_16x16x32_bf16 v[66:69], v[174:177], v[218:221], v[66:69]
	s_setprio 0
	s_barrier
	s_add_i32 s41, s41, s3
	v_lshl_add_u64 v[190:191], s[22:23], 0, v[132:133]
	s_mov_b32 m0, s41
	ds_read_b128 v[178:181], v145 offset:16384
	ds_read_b128 v[182:185], v145 offset:17408
	ds_read_b128 v[186:189], v145 offset:18432
	ds_read_b128 v[194:197], v145 offset:19456
	ds_read_b128 v[206:209], v145 offset:20480
	ds_read_b128 v[210:213], v145 offset:21504
	ds_read_b128 v[214:217], v145 offset:22528
	ds_read_b128 v[218:221], v145 offset:23552
	global_load_lds_dwordx4 v[190:191], off
	s_add_i32 m0, s41, 0x2000
	s_add_u32 s42, s22, 0x40000
	v_lshl_add_u64 v[202:203], s[22:23], 0, v[130:131]
	s_addc_u32 s43, s23, 0
	s_add_i32 s41, s44, s3
	global_load_lds_dwordx4 v[202:203], off
	v_lshl_add_u64 v[204:205], s[42:43], 0, v[132:133]
	s_mov_b32 m0, s41
	v_lshl_add_u64 v[222:223], s[24:25], 0, v[130:131]
	global_load_lds_dwordx4 v[204:205], off
	v_lshl_add_u64 v[204:205], s[42:43], 0, v[130:131]
	s_add_i32 m0, s41, 0x2000
	s_nop 0
	global_load_lds_dwordx4 v[204:205], off
	v_lshl_add_u64 v[204:205], s[24:25], 0, v[132:133]
	s_mov_b32 m0, s26
	s_nop 0
	global_load_lds_dwordx4 v[204:205], off
	s_mov_b32 m0, s27
	s_nop 0
	global_load_lds_dwordx4 v[222:223], off
	s_waitcnt vmcnt(8)
	s_waitcnt lgkmcnt(0)
	s_barrier
; #define PG8_STAGE(bufoff, gbase, voff) do { _Pragma("unroll") for (int _i = 0; _i < 2; ++_i) \
;         __builtin_amdgcn_global_load_lds((const unsigned*)((const char*)(gbase) + (voff)[_i]), (LAS unsigned*)(lds + (bufoff) + ldsw + _i * 8192), 16, 0, 0); } while (0)
; #define PG8_LDA(dst, b, h) do { _Pragma("unroll") for (int m = 0; m < 4; ++m) _Pragma("unroll") for (int k = 0; k < 2; ++k) dst[m][k] = *(const LAS bf16x8*)(lds + PG8_SA(b, h) + aoff + m * 2048 + k * 1024); } while (0)
; #define PG8_LDB(dst, b, h) do { _Pragma("unroll") for (int n = 0; n < 2; ++n) _Pragma("unroll") for (int k = 0; k < 2; ++k) dst[n][k] = *(const LAS bf16x8*)(lds + PG8_SB(b, h) + boff + n * 2048 + k * 1024); } while (0)
; #define PG8_MMA(ai, bj, At, Bt) do { __builtin_amdgcn_s_setprio(1); _Pragma("unroll") for (int m = 0; m < 4; ++m) _Pragma("unroll") for (int n = 0; n < 2; ++n) _Pragma("unroll") for (int k = 0; k < 2; ++k) \
;         acc[ai][bj][m][n] = __builtin_amdgcn_mfma_f32_16x16x32_bf16(Bt[n][k], At[m][k], acc[ai][bj][m][n], 0, 0, 0); __builtin_amdgcn_s_setprio(0); } while (0)
; #define PG8_WAIT_V(n) asm volatile("s_waitcnt vmcnt(" #n ")" ::: "memory")
; #define PG8_WAIT_L(n) asm volatile("s_waitcnt lgkmcnt(" #n ")" ::: "memory")
; #define PG8_BAR __builtin_amdgcn_s_barrier()
; #define PG8_SCHED __builtin_amdgcn_sched_barrier(0)
; template <class Epi, bool ALIGN_EPI = PG8_ALIGN, bool SP2 = PG8_SP2>
; __device__ __forceinline__ void gemm_phase(LAS unsigned char* lds, const Gemm g, const StaticOrder& S, const Epi& E) {
;     ...
;             PG8_WAIT_V(8); PG8_WAIT_L(0); PG8_BAR; PG8_MMA(1, 0, At, B0); PG8_MMA(1, 1, At, B1); PG8_BAR; PG8_SCHED;
;             PG8_LDB(B0, 1, 0); PG8_LDB(B1, 1, 1); PG8_SCHED; PG8_LDA(At, 1, 0); PG8_STAGE(PG8_SA(0, 1), a2 + hstepA, voffA);
;             PG8_WAIT_V(8); PG8_WAIT_L(0); PG8_BAR; PG8_MMA(0, 0, At, B0); PG8_MMA(0, 1, At, B1); PG8_BAR; PG8_SCHED;
	s_setprio 1
	s_waitcnt lgkmcnt(0)
	v_mfma_f32_16x16x32_bf16 v[62:65], v[138:141], v[178:181], v[62:65]
	v_mfma_f32_16x16x32_bf16 v[58:61], v[150:153], v[178:181], v[58:61]
	v_mfma_f32_16x16x32_bf16 v[46:49], v[138:141], v[186:189], v[46:49]
	v_mfma_f32_16x16x32_bf16 v[42:45], v[150:153], v[186:189], v[42:45]
	v_mfma_f32_16x16x32_bf16 v[30:33], v[138:141], v[206:209], v[30:33]
	v_mfma_f32_16x16x32_bf16 v[26:29], v[150:153], v[206:209], v[26:29]
	v_mfma_f32_16x16x32_bf16 v[14:17], v[138:141], v[214:217], v[14:17]
	v_mfma_f32_16x16x32_bf16 v[10:13], v[150:153], v[214:217], v[10:13]
	s_setprio 0
	s_setprio 1
	v_mfma_f32_16x16x32_bf16 v[62:65], v[146:149], v[182:185], v[62:65]
	v_mfma_f32_16x16x32_bf16 v[58:61], v[154:157], v[182:185], v[58:61]
	v_mfma_f32_16x16x32_bf16 v[46:49], v[146:149], v[194:197], v[46:49]
	v_mfma_f32_16x16x32_bf16 v[42:45], v[154:157], v[194:197], v[42:45]
	v_mfma_f32_16x16x32_bf16 v[30:33], v[146:149], v[210:213], v[30:33]
	v_mfma_f32_16x16x32_bf16 v[26:29], v[154:157], v[210:213], v[26:29]
	v_mfma_f32_16x16x32_bf16 v[14:17], v[146:149], v[218:221], v[14:17]
	v_mfma_f32_16x16x32_bf16 v[10:13], v[154:157], v[218:221], v[10:13]
	s_setprio 0
	s_setprio 1
	v_mfma_f32_16x16x32_bf16 v[54:57], v[158:161], v[178:181], v[54:57]
	v_mfma_f32_16x16x32_bf16 v[50:53], v[170:173], v[178:181], v[50:53]
	v_mfma_f32_16x16x32_bf16 v[38:41], v[158:161], v[186:189], v[38:41]
	v_mfma_f32_16x16x32_bf16 v[34:37], v[170:173], v[186:189], v[34:37]
	v_mfma_f32_16x16x32_bf16 v[22:25], v[158:161], v[206:209], v[22:25]
	v_mfma_f32_16x16x32_bf16 v[18:21], v[170:173], v[206:209], v[18:21]
	v_mfma_f32_16x16x32_bf16 v[6:9], v[158:161], v[214:217], v[6:9]
	v_mfma_f32_16x16x32_bf16 v[2:5], v[170:173], v[214:217], v[2:5]
	s_setprio 0
	s_setprio 1
	v_mfma_f32_16x16x32_bf16 v[54:57], v[164:167], v[182:185], v[54:57]
	v_mfma_f32_16x16x32_bf16 v[50:53], v[174:177], v[182:185], v[50:53]
	v_mfma_f32_16x16x32_bf16 v[38:41], v[164:167], v[194:197], v[38:41]
	v_mfma_f32_16x16x32_bf16 v[34:37], v[174:177], v[194:197], v[34:37]
	v_mfma_f32_16x16x32_bf16 v[22:25], v[164:167], v[210:213], v[22:25]
	v_mfma_f32_16x16x32_bf16 v[18:21], v[174:177], v[210:213], v[18:21]
	v_mfma_f32_16x16x32_bf16 v[6:9], v[164:167], v[218:221], v[6:9]
	v_mfma_f32_16x16x32_bf16 v[2:5], v[174:177], v[218:221], v[2:5]
	s_setprio 0
	s_barrier
	s_add_i32 s41, 0, 0x18000
	v_add_u32_e32 v0, s41, v143
	s_add_i32 s42, 0, 0x1c000
	ds_read_b128 v[138:141], v0
	ds_read_b128 v[146:149], v0 offset:1024
	ds_read_b128 v[150:153], v0 offset:2048
	ds_read_b128 v[154:157], v0 offset:3072
	v_add_u32_e32 v0, s42, v143
	ds_read_b128 v[158:161], v0
	ds_read_b128 v[164:167], v0 offset:1024
	ds_read_b128 v[170:173], v0 offset:2048
	ds_read_b128 v[174:177], v0 offset:3072
	s_add_u32 s24, s24, 0x40000
	s_addc_u32 s25, s25, 0
	s_mov_b32 m0, s28
	v_lshl_add_u64 v[224:225], s[24:25], 0, v[132:133]
	ds_read_b128 v[178:181], v145 offset:32768
	ds_read_b128 v[182:185], v145 offset:33792
	ds_read_b128 v[186:189], v145 offset:34816
	ds_read_b128 v[194:197], v145 offset:35840
	ds_read_b128 v[206:209], v145 offset:36864
	ds_read_b128 v[210:213], v145 offset:37888
	ds_read_b128 v[214:217], v145 offset:38912
	ds_read_b128 v[218:221], v145 offset:39936
	global_load_lds_dwordx4 v[224:225], off
	v_lshl_add_u64 v[224:225], s[24:25], 0, v[130:131]
	s_mov_b32 m0, s29
	s_nop 0
	global_load_lds_dwordx4 v[224:225], off
	s_waitcnt vmcnt(8)
	s_waitcnt lgkmcnt(0)
	s_barrier
	s_setprio 1
	s_waitcnt lgkmcnt(0)
	v_mfma_f32_16x16x32_bf16 v[126:129], v[138:141], v[178:181], v[126:129]
	v_mfma_f32_16x16x32_bf16 v[122:125], v[150:153], v[178:181], v[122:125]
	v_mfma_f32_16x16x32_bf16 v[110:113], v[138:141], v[186:189], v[110:113]
	v_mfma_f32_16x16x32_bf16 v[106:109], v[150:153], v[186:189], v[106:109]
	v_mfma_f32_16x16x32_bf16 v[94:97], v[138:141], v[206:209], v[94:97]
	v_mfma_f32_16x16x32_bf16 v[90:93], v[150:153], v[206:209], v[90:93]
	v_mfma_f32_16x16x32_bf16 v[78:81], v[138:141], v[214:217], v[78:81]
	v_mfma_f32_16x16x32_bf16 v[74:77], v[150:153], v[214:217], v[74:77]
	s_setprio 0
	s_setprio 1
	v_mfma_f32_16x16x32_bf16 v[126:129], v[146:149], v[182:185], v[126:129]
	v_mfma_f32_16x16x32_bf16 v[122:125], v[154:157], v[182:185], v[122:125]
	v_mfma_f32_16x16x32_bf16 v[110:113], v[146:149], v[194:197], v[110:113]
	v_mfma_f32_16x16x32_bf16 v[106:109], v[154:157], v[194:197], v[106:109]
	v_mfma_f32_16x16x32_bf16 v[94:97], v[146:149], v[210:213], v[94:97]
	v_mfma_f32_16x16x32_bf16 v[90:93], v[154:157], v[210:213], v[90:93]
	v_mfma_f32_16x16x32_bf16 v[78:81], v[146:149], v[218:221], v[78:81]
	v_mfma_f32_16x16x32_bf16 v[74:77], v[154:157], v[218:221], v[74:77]
	s_setprio 0
	s_setprio 1
	v_mfma_f32_16x16x32_bf16 v[118:121], v[158:161], v[178:181], v[118:121]
	v_mfma_f32_16x16x32_bf16 v[114:117], v[170:173], v[178:181], v[114:117]
	v_mfma_f32_16x16x32_bf16 v[102:105], v[158:161], v[186:189], v[102:105]
	v_mfma_f32_16x16x32_bf16 v[98:101], v[170:173], v[186:189], v[98:101]
	v_mfma_f32_16x16x32_bf16 v[86:89], v[158:161], v[206:209], v[86:89]
	v_mfma_f32_16x16x32_bf16 v[82:85], v[170:173], v[206:209], v[82:85]
	v_mfma_f32_16x16x32_bf16 v[70:73], v[158:161], v[214:217], v[70:73]
	v_mfma_f32_16x16x32_bf16 v[66:69], v[170:173], v[214:217], v[66:69]
	s_setprio 0
	s_setprio 1
	v_mfma_f32_16x16x32_bf16 v[118:121], v[164:167], v[182:185], v[118:121]
	v_mfma_f32_16x16x32_bf16 v[114:117], v[174:177], v[182:185], v[114:117]
	v_mfma_f32_16x16x32_bf16 v[102:105], v[164:167], v[194:197], v[102:105]
	v_mfma_f32_16x16x32_bf16 v[98:101], v[174:177], v[194:197], v[98:101]
	v_mfma_f32_16x16x32_bf16 v[86:89], v[164:167], v[210:213], v[86:89]
	v_mfma_f32_16x16x32_bf16 v[82:85], v[174:177], v[210:213], v[82:85]
	v_mfma_f32_16x16x32_bf16 v[70:73], v[164:167], v[218:221], v[70:73]
	v_mfma_f32_16x16x32_bf16 v[66:69], v[174:177], v[218:221], v[66:69]
	s_setprio 0
	s_barrier
; #define PG8_STAGE(bufoff, gbase, voff) do { _Pragma("unroll") for (int _i = 0; _i < 2; ++_i) \
;         __builtin_amdgcn_global_load_lds((const unsigned*)((const char*)(gbase) + (voff)[_i]), (LAS unsigned*)(lds + (bufoff) + ldsw + _i * 8192), 16, 0, 0); } while (0)
; #define PG8_LDA(dst, b, h) do { _Pragma("unroll") for (int m = 0; m < 4; ++m) _Pragma("unroll") for (int k = 0; k < 2; ++k) dst[m][k] = *(const LAS bf16x8*)(lds + PG8_SA(b, h) + aoff + m * 2048 + k * 1024); } while (0)
; #define PG8_LDB(dst, b, h) do { _Pragma("unroll") for (int n = 0; n < 2; ++n) _Pragma("unroll") for (int k = 0; k < 2; ++k) dst[n][k] = *(const LAS bf16x8*)(lds + PG8_SB(b, h) + boff + n * 2048 + k * 1024); } while (0)
; #define PG8_MMA(ai, bj, At, Bt) do { __builtin_amdgcn_s_setprio(1); _Pragma("unroll") for (int m = 0; m < 4; ++m) _Pragma("unroll") for (int n = 0; n < 2; ++n) _Pragma("unroll") for (int k = 0; k < 2; ++k) \
;         acc[ai][bj][m][n] = __builtin_amdgcn_mfma_f32_16x16x32_bf16(Bt[n][k], At[m][k], acc[ai][bj][m][n], 0, 0, 0); __builtin_amdgcn_s_setprio(0); } while (0)
; #define PG8_WAIT_V(n) asm volatile("s_waitcnt vmcnt(" #n ")" ::: "memory")
; #define PG8_WAIT_L(n) asm volatile("s_waitcnt lgkmcnt(" #n ")" ::: "memory")
; #define PG8_BAR __builtin_amdgcn_s_barrier()
; #define PG8_SCHED __builtin_amdgcn_sched_barrier(0)
; template <class Epi, bool ALIGN_EPI = PG8_ALIGN, bool SP2 = PG8_SP2>
; __device__ __forceinline__ void gemm_phase(LAS unsigned char* lds, const Gemm g, const StaticOrder& S, const Epi& E) {
;     ...
;             PG8_LDB(B0, 1, 0); PG8_LDB(B1, 1, 1); PG8_SCHED; PG8_LDA(At, 1, 0); PG8_STAGE(PG8_SA(0, 1), a2 + hstepA, voffA);
;             PG8_WAIT_V(8); PG8_WAIT_L(0); PG8_BAR; PG8_MMA(0, 0, At, B0); PG8_MMA(0, 1, At, B1); PG8_BAR; PG8_SCHED;
;             PG8_LDA(At, 1, 1); PG8_STAGE(PG8_SB(1, 0), b3, voffB); PG8_STAGE(PG8_SB(1, 1), b3 + hstepB, voffB); PG8_STAGE(PG8_SA(1, 0), a3, voffA);
;             PG8_WAIT_V(8); PG8_WAIT_L(0); PG8_BAR; PG8_MMA(1, 0, At, B0); PG8_MMA(1, 1, At, B1); PG8_BAR; PG8_SCHED;
	s_add_i32 s24, s41, s3
	v_lshl_add_u64 v[190:191], v[190:191], 0, s[50:51]
	s_mov_b32 m0, s24
	ds_read_b128 v[178:181], v145 offset:49152
	ds_read_b128 v[182:185], v145 offset:50176
	ds_read_b128 v[186:189], v145 offset:51200
	ds_read_b128 v[194:197], v145 offset:52224
	ds_read_b128 v[206:209], v145 offset:53248
	ds_read_b128 v[210:213], v145 offset:54272
	ds_read_b128 v[214:217], v145 offset:55296
	ds_read_b128 v[218:221], v145 offset:56320
	global_load_lds_dwordx4 v[190:191], off
	s_add_i32 m0, s24, 0x2000
	s_add_u32 s22, s22, 0x40080
	v_lshl_add_u64 v[190:191], v[202:203], 0, s[50:51]
	s_addc_u32 s23, s23, 0
	s_add_i32 s24, s42, s3
	global_load_lds_dwordx4 v[190:191], off
	v_lshl_add_u64 v[190:191], s[22:23], 0, v[132:133]
	s_mov_b32 m0, s24
	s_nop 0
	global_load_lds_dwordx4 v[190:191], off
	v_lshl_add_u64 v[190:191], s[22:23], 0, v[130:131]
	s_add_i32 m0, s24, 0x2000
	s_nop 0
	global_load_lds_dwordx4 v[190:191], off
	v_lshl_add_u64 v[190:191], v[204:205], 0, s[50:51]
	s_mov_b32 m0, s30
	s_nop 0
	global_load_lds_dwordx4 v[190:191], off
	v_lshl_add_u64 v[190:191], v[222:223], 0, s[50:51]
	s_mov_b32 m0, s31
	s_nop 0
	global_load_lds_dwordx4 v[190:191], off
	s_waitcnt vmcnt(8)
	s_waitcnt lgkmcnt(0)
	s_barrier
	s_setprio 1
	s_waitcnt lgkmcnt(0)
	v_mfma_f32_16x16x32_bf16 v[62:65], v[138:141], v[178:181], v[62:65]
	v_mfma_f32_16x16x32_bf16 v[58:61], v[150:153], v[178:181], v[58:61]
	v_mfma_f32_16x16x32_bf16 v[46:49], v[138:141], v[186:189], v[46:49]
	v_mfma_f32_16x16x32_bf16 v[42:45], v[150:153], v[186:189], v[42:45]
	v_mfma_f32_16x16x32_bf16 v[30:33], v[138:141], v[206:209], v[30:33]
	v_mfma_f32_16x16x32_bf16 v[26:29], v[150:153], v[206:209], v[26:29]
	v_mfma_f32_16x16x32_bf16 v[14:17], v[138:141], v[214:217], v[14:17]
	v_mfma_f32_16x16x32_bf16 v[10:13], v[150:153], v[214:217], v[10:13]
	s_setprio 0
	s_setprio 1
	v_mfma_f32_16x16x32_bf16 v[62:65], v[146:149], v[182:185], v[62:65]
	v_mfma_f32_16x16x32_bf16 v[58:61], v[154:157], v[182:185], v[58:61]
	v_mfma_f32_16x16x32_bf16 v[46:49], v[146:149], v[194:197], v[46:49]
	v_mfma_f32_16x16x32_bf16 v[42:45], v[154:157], v[194:197], v[42:45]
	v_mfma_f32_16x16x32_bf16 v[30:33], v[146:149], v[210:213], v[30:33]
	v_mfma_f32_16x16x32_bf16 v[26:29], v[154:157], v[210:213], v[26:29]
	v_mfma_f32_16x16x32_bf16 v[14:17], v[146:149], v[218:221], v[14:17]
	v_mfma_f32_16x16x32_bf16 v[10:13], v[154:157], v[218:221], v[10:13]
	s_setprio 0
	s_setprio 1
	v_mfma_f32_16x16x32_bf16 v[54:57], v[158:161], v[178:181], v[54:57]
	v_mfma_f32_16x16x32_bf16 v[50:53], v[170:173], v[178:181], v[50:53]
	v_mfma_f32_16x16x32_bf16 v[38:41], v[158:161], v[186:189], v[38:41]
	v_mfma_f32_16x16x32_bf16 v[34:37], v[170:173], v[186:189], v[34:37]
	v_mfma_f32_16x16x32_bf16 v[22:25], v[158:161], v[206:209], v[22:25]
	v_mfma_f32_16x16x32_bf16 v[18:21], v[170:173], v[206:209], v[18:21]
	v_mfma_f32_16x16x32_bf16 v[6:9], v[158:161], v[214:217], v[6:9]
	v_mfma_f32_16x16x32_bf16 v[2:5], v[170:173], v[214:217], v[2:5]
	s_setprio 0
	s_setprio 1
	v_mfma_f32_16x16x32_bf16 v[54:57], v[164:167], v[182:185], v[54:57]
	v_mfma_f32_16x16x32_bf16 v[50:53], v[174:177], v[182:185], v[50:53]
	v_mfma_f32_16x16x32_bf16 v[38:41], v[164:167], v[194:197], v[38:41]
	v_mfma_f32_16x16x32_bf16 v[34:37], v[174:177], v[194:197], v[34:37]
	v_mfma_f32_16x16x32_bf16 v[22:25], v[164:167], v[210:213], v[22:25]
	v_mfma_f32_16x16x32_bf16 v[18:21], v[174:177], v[210:213], v[18:21]
	v_mfma_f32_16x16x32_bf16 v[6:9], v[164:167], v[218:221], v[6:9]
	v_mfma_f32_16x16x32_bf16 v[2:5], v[174:177], v[218:221], v[2:5]
	s_setprio 0
	s_barrier
	s_add_i32 s40, s40, 2
	s_add_u32 s4, s4, 0x100
	s_addc_u32 s5, s5, 0
	s_add_u32 s38, s38, 0x100
	s_addc_u32 s39, s39, 0
	s_cmp_gt_u32 s40, 13
	s_cbranch_scc0 .LBB0_139
	s_and_b64 vcc, exec, s[12:13]
	s_cbranch_vccz .LBB0_142
	s_barrier

; #define PG8_STAGE(bufoff, gbase, voff) do { _Pragma("unroll") for (int _i = 0; _i < 2; ++_i) \
;         __builtin_amdgcn_global_load_lds((const unsigned*)((const char*)(gbase) + (voff)[_i]), (LAS unsigned*)(lds + (bufoff) + ldsw + _i * 8192), 16, 0, 0); } while (0)
; #define PG8_LDA(dst, b, h) do { _Pragma("unroll") for (int m = 0; m < 4; ++m) _Pragma("unroll") for (int k = 0; k < 2; ++k) dst[m][k] = *(const LAS bf16x8*)(lds + PG8_SA(b, h) + aoff + m * 2048 + k * 1024); } while (0)
; #define PG8_LDB(dst, b, h) do { _Pragma("unroll") for (int n = 0; n < 2; ++n) _Pragma("unroll") for (int k = 0; k < 2; ++k) dst[n][k] = *(const LAS bf16x8*)(lds + PG8_SB(b, h) + boff + n * 2048 + k * 1024); } while (0)
; #define PG8_MMA(ai, bj, At, Bt) do { __builtin_amdgcn_s_setprio(1); _Pragma("unroll") for (int m = 0; m < 4; ++m) _Pragma("unroll") for (int n = 0; n < 2; ++n) _Pragma("unroll") for (int k = 0; k < 2; ++k) \
;         acc[ai][bj][m][n] = __builtin_amdgcn_mfma_f32_16x16x32_bf16(Bt[n][k], At[m][k], acc[ai][bj][m][n], 0, 0, 0); __builtin_amdgcn_s_setprio(0); } while (0)
; #define PG8_WAIT_V(n) asm volatile("s_waitcnt vmcnt(" #n ")" ::: "memory")
; #define PG8_WAIT_L(n) asm volatile("s_waitcnt lgkmcnt(" #n ")" ::: "memory")
; #define PG8_BAR __builtin_amdgcn_s_barrier()
; #define PG8_SCHED __builtin_amdgcn_sched_barrier(0)
; template <class Epi, bool ALIGN_EPI = PG8_ALIGN, bool SP2 = PG8_SP2>
; __device__ __forceinline__ void gemm_phase(LAS unsigned char* lds, const Gemm g, const StaticOrder& S, const Epi& E) {
;     ...
;             PG8_LDB(B0, 0, 0); PG8_LDB(B1, 0, 1); PG8_SCHED; PG8_LDA(At, 0, 0); PG8_STAGE(PG8_SA(1, 1), a1 + hstepA, voffA);
;             PG8_WAIT_V(8); PG8_WAIT_L(0); PG8_BAR; PG8_MMA(0, 0, At, B0); PG8_MMA(0, 1, At, B1); PG8_BAR; PG8_SCHED;
;             PG8_LDA(At, 0, 1); PG8_STAGE(PG8_SB(0, 0), b2, voffB); PG8_STAGE(PG8_SB(0, 1), b2 + hstepB, voffB); PG8_STAGE(PG8_SA(0, 0), a2, voffA);
;             PG8_WAIT_V(8); PG8_WAIT_L(0); PG8_BAR; PG8_MMA(1, 0, At, B0); PG8_MMA(1, 1, At, B1); PG8_BAR; PG8_SCHED;
.Lfirst_iter_u139:
	s_add_u32 s22, s4, 0xfffc0080
	s_addc_u32 s23, s5, -1
	s_add_i32 s41, 0, 0x10000
	s_cmp_eq_u32 s40, 12
	s_cselect_b32 s25, s17, s23
	s_cselect_b32 s24, s36, s22
	v_add_u32_e32 v0, s41, v143
	s_cselect_b32 s23, s15, s39
	s_cselect_b32 s22, s37, s38
	s_add_i32 s44, 0, 0x14000
	ds_read_b128 v[138:141], v0
	ds_read_b128 v[146:149], v0 offset:1024
	ds_read_b128 v[150:153], v0 offset:2048
	ds_read_b128 v[154:157], v0 offset:3072
	v_add_u32_e32 v0, s44, v143
	ds_read_b128 v[158:161], v0
	ds_read_b128 v[164:167], v0 offset:1024
	ds_read_b128 v[170:173], v0 offset:2048
	ds_read_b128 v[174:177], v0 offset:3072
	v_lshl_add_u64 v[190:191], s[4:5], 0, v[134:135]
	s_add_i32 m0, s26, 0xc000
	ds_read_b128 v[178:181], v145
	ds_read_b128 v[182:185], v145 offset:1024
	ds_read_b128 v[186:189], v145 offset:2048
	ds_read_b128 v[194:197], v145 offset:3072
	ds_read_b128 v[206:209], v145 offset:4096
	ds_read_b128 v[210:213], v145 offset:5120
	ds_read_b128 v[214:217], v145 offset:6144
	ds_read_b128 v[218:221], v145 offset:7168
	global_load_lds_dwordx4 v[190:191], off
	v_lshl_add_u64 v[190:191], s[4:5], 0, v[136:137]
	s_add_i32 m0, s26, 0xe000
	s_nop 0
	global_load_lds_dwordx4 v[190:191], off
	s_waitcnt vmcnt(8)
	s_waitcnt lgkmcnt(0)
	s_barrier
	s_setprio 1
	s_waitcnt lgkmcnt(0)
	v_mfma_f32_16x16x32_bf16 v[126:129], v[138:141], v[178:181], 0
	v_mfma_f32_16x16x32_bf16 v[122:125], v[150:153], v[178:181], 0
	v_mfma_f32_16x16x32_bf16 v[110:113], v[138:141], v[186:189], 0
	v_mfma_f32_16x16x32_bf16 v[106:109], v[150:153], v[186:189], 0
	v_mfma_f32_16x16x32_bf16 v[94:97], v[138:141], v[206:209], 0
	v_mfma_f32_16x16x32_bf16 v[90:93], v[150:153], v[206:209], 0
	v_mfma_f32_16x16x32_bf16 v[78:81], v[138:141], v[214:217], 0
	v_mfma_f32_16x16x32_bf16 v[74:77], v[150:153], v[214:217], 0
	s_setprio 0
	s_setprio 1
	v_mfma_f32_16x16x32_bf16 v[126:129], v[146:149], v[182:185], v[126:129]
	v_mfma_f32_16x16x32_bf16 v[122:125], v[154:157], v[182:185], v[122:125]
	v_mfma_f32_16x16x32_bf16 v[110:113], v[146:149], v[194:197], v[110:113]
	v_mfma_f32_16x16x32_bf16 v[106:109], v[154:157], v[194:197], v[106:109]
	v_mfma_f32_16x16x32_bf16 v[94:97], v[146:149], v[210:213], v[94:97]
	v_mfma_f32_16x16x32_bf16 v[90:93], v[154:157], v[210:213], v[90:93]
	v_mfma_f32_16x16x32_bf16 v[78:81], v[146:149], v[218:221], v[78:81]
	v_mfma_f32_16x16x32_bf16 v[74:77], v[154:157], v[218:221], v[74:77]
	s_setprio 0
	s_setprio 1
	v_mfma_f32_16x16x32_bf16 v[118:121], v[158:161], v[178:181], 0
	v_mfma_f32_16x16x32_bf16 v[114:117], v[170:173], v[178:181], 0
	v_mfma_f32_16x16x32_bf16 v[102:105], v[158:161], v[186:189], 0
	v_mfma_f32_16x16x32_bf16 v[98:101], v[170:173], v[186:189], 0
	v_mfma_f32_16x16x32_bf16 v[86:89], v[158:161], v[206:209], 0
	v_mfma_f32_16x16x32_bf16 v[82:85], v[170:173], v[206:209], 0
	v_mfma_f32_16x16x32_bf16 v[70:73], v[158:161], v[214:217], 0
	v_mfma_f32_16x16x32_bf16 v[66:69], v[170:173], v[214:217], 0
	s_setprio 0
	s_setprio 1
	v_mfma_f32_16x16x32_bf16 v[118:121], v[164:167], v[182:185], v[118:121]
	v_mfma_f32_16x16x32_bf16 v[114:117], v[174:177], v[182:185], v[114:117]
	v_mfma_f32_16x16x32_bf16 v[102:105], v[164:167], v[194:197], v[102:105]
	v_mfma_f32_16x16x32_bf16 v[98:101], v[174:177], v[194:197], v[98:101]
	v_mfma_f32_16x16x32_bf16 v[86:89], v[164:167], v[210:213], v[86:89]
	v_mfma_f32_16x16x32_bf16 v[82:85], v[174:177], v[210:213], v[82:85]
	v_mfma_f32_16x16x32_bf16 v[70:73], v[164:167], v[218:221], v[70:73]
	v_mfma_f32_16x16x32_bf16 v[66:69], v[174:177], v[218:221], v[66:69]
	s_setprio 0
	s_barrier
	s_add_i32 s41, s41, s3
	v_lshl_add_u64 v[190:191], s[22:23], 0, v[132:133]
	s_mov_b32 m0, s41
	ds_read_b128 v[178:181], v145 offset:16384
	ds_read_b128 v[182:185], v145 offset:17408
	ds_read_b128 v[186:189], v145 offset:18432
	ds_read_b128 v[194:197], v145 offset:19456
	ds_read_b128 v[206:209], v145 offset:20480
	ds_read_b128 v[210:213], v145 offset:21504
	ds_read_b128 v[214:217], v145 offset:22528
	ds_read_b128 v[218:221], v145 offset:23552
	global_load_lds_dwordx4 v[190:191], off
	s_add_i32 m0, s41, 0x2000
	s_add_u32 s42, s22, 0x40000
	v_lshl_add_u64 v[202:203], s[22:23], 0, v[130:131]
	s_addc_u32 s43, s23, 0
	s_add_i32 s41, s44, s3
	global_load_lds_dwordx4 v[202:203], off
	v_lshl_add_u64 v[204:205], s[42:43], 0, v[132:133]
	s_mov_b32 m0, s41
	v_lshl_add_u64 v[222:223], s[24:25], 0, v[130:131]
	global_load_lds_dwordx4 v[204:205], off
	v_lshl_add_u64 v[204:205], s[42:43], 0, v[130:131]
	s_add_i32 m0, s41, 0x2000
	s_nop 0
	global_load_lds_dwordx4 v[204:205], off
	v_lshl_add_u64 v[204:205], s[24:25], 0, v[132:133]
	s_mov_b32 m0, s26
	s_nop 0
	global_load_lds_dwordx4 v[204:205], off
	s_mov_b32 m0, s27
	s_nop 0
	global_load_lds_dwordx4 v[222:223], off
	s_waitcnt vmcnt(8)
	s_waitcnt lgkmcnt(0)
	s_barrier
; #define PG8_STAGE(bufoff, gbase, voff) do { _Pragma("unroll") for (int _i = 0; _i < 2; ++_i) \
;         __builtin_amdgcn_global_load_lds((const unsigned*)((const char*)(gbase) + (voff)[_i]), (LAS unsigned*)(lds + (bufoff) + ldsw + _i * 8192), 16, 0, 0); } while (0)
; #define PG8_LDA(dst, b, h) do { _Pragma("unroll") for (int m = 0; m < 4; ++m) _Pragma("unroll") for (int k = 0; k < 2; ++k) dst[m][k] = *(const LAS bf16x8*)(lds + PG8_SA(b, h) + aoff + m * 2048 + k * 1024); } while (0)
; #define PG8_LDB(dst, b, h) do { _Pragma("unroll") for (int n = 0; n < 2; ++n) _Pragma("unroll") for (int k = 0; k < 2; ++k) dst[n][k] = *(const LAS bf16x8*)(lds + PG8_SB(b, h) + boff + n * 2048 + k * 1024); } while (0)
; #define PG8_MMA(ai, bj, At, Bt) do { __builtin_amdgcn_s_setprio(1); _Pragma("unroll") for (int m = 0; m < 4; ++m) _Pragma("unroll") for (int n = 0; n < 2; ++n) _Pragma("unroll") for (int k = 0; k < 2; ++k) \
;         acc[ai][bj][m][n] = __builtin_amdgcn_mfma_f32_16x16x32_bf16(Bt[n][k], At[m][k], acc[ai][bj][m][n], 0, 0, 0); __builtin_amdgcn_s_setprio(0); } while (0)
; #define PG8_WAIT_V(n) asm volatile("s_waitcnt vmcnt(" #n ")" ::: "memory")
; #define PG8_WAIT_L(n) asm volatile("s_waitcnt lgkmcnt(" #n ")" ::: "memory")
; #define PG8_BAR __builtin_amdgcn_s_barrier()
; #define PG8_SCHED __builtin_amdgcn_sched_barrier(0)
; template <class Epi, bool ALIGN_EPI = PG8_ALIGN, bool SP2 = PG8_SP2>
; __device__ __forceinline__ void gemm_phase(LAS unsigned char* lds, const Gemm g, const StaticOrder& S, const Epi& E) {
;     ...
;             PG8_WAIT_V(8); PG8_WAIT_L(0); PG8_BAR; PG8_MMA(1, 0, At, B0); PG8_MMA(1, 1, At, B1); PG8_BAR; PG8_SCHED;
;             PG8_LDB(B0, 1, 0); PG8_LDB(B1, 1, 1); PG8_SCHED; PG8_LDA(At, 1, 0); PG8_STAGE(PG8_SA(0, 1), a2 + hstepA, voffA);
;             PG8_WAIT_V(8); PG8_WAIT_L(0); PG8_BAR; PG8_MMA(0, 0, At, B0); PG8_MMA(0, 1, At, B1); PG8_BAR; PG8_SCHED;
	s_setprio 1
	s_waitcnt lgkmcnt(0)
	v_mfma_f32_16x16x32_bf16 v[62:65], v[138:141], v[178:181], 0
	v_mfma_f32_16x16x32_bf16 v[58:61], v[150:153], v[178:181], 0
	v_mfma_f32_16x16x32_bf16 v[46:49], v[138:141], v[186:189], 0
	v_mfma_f32_16x16x32_bf16 v[42:45], v[150:153], v[186:189], 0
	v_mfma_f32_16x16x32_bf16 v[30:33], v[138:141], v[206:209], 0
	v_mfma_f32_16x16x32_bf16 v[26:29], v[150:153], v[206:209], 0
	v_mfma_f32_16x16x32_bf16 v[14:17], v[138:141], v[214:217], 0
	v_mfma_f32_16x16x32_bf16 v[10:13], v[150:153], v[214:217], 0
	s_setprio 0
	s_setprio 1
	v_mfma_f32_16x16x32_bf16 v[62:65], v[146:149], v[182:185], v[62:65]
	v_mfma_f32_16x16x32_bf16 v[58:61], v[154:157], v[182:185], v[58:61]
	v_mfma_f32_16x16x32_bf16 v[46:49], v[146:149], v[194:197], v[46:49]
	v_mfma_f32_16x16x32_bf16 v[42:45], v[154:157], v[194:197], v[42:45]
	v_mfma_f32_16x16x32_bf16 v[30:33], v[146:149], v[210:213], v[30:33]
	v_mfma_f32_16x16x32_bf16 v[26:29], v[154:157], v[210:213], v[26:29]
	v_mfma_f32_16x16x32_bf16 v[14:17], v[146:149], v[218:221], v[14:17]
	v_mfma_f32_16x16x32_bf16 v[10:13], v[154:157], v[218:221], v[10:13]
	s_setprio 0
	s_setprio 1
	v_mfma_f32_16x16x32_bf16 v[54:57], v[158:161], v[178:181], 0
	v_mfma_f32_16x16x32_bf16 v[50:53], v[170:173], v[178:181], 0
	v_mfma_f32_16x16x32_bf16 v[38:41], v[158:161], v[186:189], 0
	v_mfma_f32_16x16x32_bf16 v[34:37], v[170:173], v[186:189], 0
	v_mfma_f32_16x16x32_bf16 v[22:25], v[158:161], v[206:209], 0
	v_mfma_f32_16x16x32_bf16 v[18:21], v[170:173], v[206:209], 0
	v_mfma_f32_16x16x32_bf16 v[6:9], v[158:161], v[214:217], 0
	v_mfma_f32_16x16x32_bf16 v[2:5], v[170:173], v[214:217], 0
	s_setprio 0
	s_setprio 1
	v_mfma_f32_16x16x32_bf16 v[54:57], v[164:167], v[182:185], v[54:57]
	v_mfma_f32_16x16x32_bf16 v[50:53], v[174:177], v[182:185], v[50:53]
	v_mfma_f32_16x16x32_bf16 v[38:41], v[164:167], v[194:197], v[38:41]
	v_mfma_f32_16x16x32_bf16 v[34:37], v[174:177], v[194:197], v[34:37]
	v_mfma_f32_16x16x32_bf16 v[22:25], v[164:167], v[210:213], v[22:25]
	v_mfma_f32_16x16x32_bf16 v[18:21], v[174:177], v[210:213], v[18:21]
	v_mfma_f32_16x16x32_bf16 v[6:9], v[164:167], v[218:221], v[6:9]
	v_mfma_f32_16x16x32_bf16 v[2:5], v[174:177], v[218:221], v[2:5]
	s_setprio 0
	s_barrier
	s_add_i32 s41, 0, 0x18000
	v_add_u32_e32 v0, s41, v143
	s_add_i32 s42, 0, 0x1c000
	ds_read_b128 v[138:141], v0
	ds_read_b128 v[146:149], v0 offset:1024
	ds_read_b128 v[150:153], v0 offset:2048
	ds_read_b128 v[154:157], v0 offset:3072
	v_add_u32_e32 v0, s42, v143
	ds_read_b128 v[158:161], v0
	ds_read_b128 v[164:167], v0 offset:1024
	ds_read_b128 v[170:173], v0 offset:2048
	ds_read_b128 v[174:177], v0 offset:3072
	s_add_u32 s24, s24, 0x40000
	s_addc_u32 s25, s25, 0
	s_mov_b32 m0, s28
	v_lshl_add_u64 v[224:225], s[24:25], 0, v[132:133]
	ds_read_b128 v[178:181], v145 offset:32768
	ds_read_b128 v[182:185], v145 offset:33792
	ds_read_b128 v[186:189], v145 offset:34816
	ds_read_b128 v[194:197], v145 offset:35840
	ds_read_b128 v[206:209], v145 offset:36864
	ds_read_b128 v[210:213], v145 offset:37888
	ds_read_b128 v[214:217], v145 offset:38912
	ds_read_b128 v[218:221], v145 offset:39936
	global_load_lds_dwordx4 v[224:225], off
	v_lshl_add_u64 v[224:225], s[24:25], 0, v[130:131]
	s_mov_b32 m0, s29
	s_nop 0
	global_load_lds_dwordx4 v[224:225], off
	s_waitcnt vmcnt(8)
	s_waitcnt lgkmcnt(0)
	s_barrier
	s_setprio 1
	s_waitcnt lgkmcnt(0)
	v_mfma_f32_16x16x32_bf16 v[126:129], v[138:141], v[178:181], v[126:129]
	v_mfma_f32_16x16x32_bf16 v[122:125], v[150:153], v[178:181], v[122:125]
	v_mfma_f32_16x16x32_bf16 v[110:113], v[138:141], v[186:189], v[110:113]
	v_mfma_f32_16x16x32_bf16 v[106:109], v[150:153], v[186:189], v[106:109]
	v_mfma_f32_16x16x32_bf16 v[94:97], v[138:141], v[206:209], v[94:97]
	v_mfma_f32_16x16x32_bf16 v[90:93], v[150:153], v[206:209], v[90:93]
	v_mfma_f32_16x16x32_bf16 v[78:81], v[138:141], v[214:217], v[78:81]
	v_mfma_f32_16x16x32_bf16 v[74:77], v[150:153], v[214:217], v[74:77]
	s_setprio 0
	s_setprio 1
	v_mfma_f32_16x16x32_bf16 v[126:129], v[146:149], v[182:185], v[126:129]
	v_mfma_f32_16x16x32_bf16 v[122:125], v[154:157], v[182:185], v[122:125]
	v_mfma_f32_16x16x32_bf16 v[110:113], v[146:149], v[194:197], v[110:113]
	v_mfma_f32_16x16x32_bf16 v[106:109], v[154:157], v[194:197], v[106:109]
	v_mfma_f32_16x16x32_bf16 v[94:97], v[146:149], v[210:213], v[94:97]
	v_mfma_f32_16x16x32_bf16 v[90:93], v[154:157], v[210:213], v[90:93]
	v_mfma_f32_16x16x32_bf16 v[78:81], v[146:149], v[218:221], v[78:81]
	v_mfma_f32_16x16x32_bf16 v[74:77], v[154:157], v[218:221], v[74:77]
	s_setprio 0
	s_setprio 1
	v_mfma_f32_16x16x32_bf16 v[118:121], v[158:161], v[178:181], v[118:121]
	v_mfma_f32_16x16x32_bf16 v[114:117], v[170:173], v[178:181], v[114:117]
	v_mfma_f32_16x16x32_bf16 v[102:105], v[158:161], v[186:189], v[102:105]
	v_mfma_f32_16x16x32_bf16 v[98:101], v[170:173], v[186:189], v[98:101]
	v_mfma_f32_16x16x32_bf16 v[86:89], v[158:161], v[206:209], v[86:89]
	v_mfma_f32_16x16x32_bf16 v[82:85], v[170:173], v[206:209], v[82:85]
	v_mfma_f32_16x16x32_bf16 v[70:73], v[158:161], v[214:217], v[70:73]
	v_mfma_f32_16x16x32_bf16 v[66:69], v[170:173], v[214:217], v[66:69]
	s_setprio 0
	s_setprio 1
	v_mfma_f32_16x16x32_bf16 v[118:121], v[164:167], v[182:185], v[118:121]
	v_mfma_f32_16x16x32_bf16 v[114:117], v[174:177], v[182:185], v[114:117]
	v_mfma_f32_16x16x32_bf16 v[102:105], v[164:167], v[194:197], v[102:105]
	v_mfma_f32_16x16x32_bf16 v[98:101], v[174:177], v[194:197], v[98:101]
	v_mfma_f32_16x16x32_bf16 v[86:89], v[164:167], v[210:213], v[86:89]
	v_mfma_f32_16x16x32_bf16 v[82:85], v[174:177], v[210:213], v[82:85]
	v_mfma_f32_16x16x32_bf16 v[70:73], v[164:167], v[218:221], v[70:73]
	v_mfma_f32_16x16x32_bf16 v[66:69], v[174:177], v[218:221], v[66:69]
	s_setprio 0
	s_barrier
; #define PG8_STAGE(bufoff, gbase, voff) do { _Pragma("unroll") for (int _i = 0; _i < 2; ++_i) \
;         __builtin_amdgcn_global_load_lds((const unsigned*)((const char*)(gbase) + (voff)[_i]), (LAS unsigned*)(lds + (bufoff) + ldsw + _i * 8192), 16, 0, 0); } while (0)
; #define PG8_LDA(dst, b, h) do { _Pragma("unroll") for (int m = 0; m < 4; ++m) _Pragma("unroll") for (int k = 0; k < 2; ++k) dst[m][k] = *(const LAS bf16x8*)(lds + PG8_SA(b, h) + aoff + m * 2048 + k * 1024); } while (0)
; #define PG8_LDB(dst, b, h) do { _Pragma("unroll") for (int n = 0; n < 2; ++n) _Pragma("unroll") for (int k = 0; k < 2; ++k) dst[n][k] = *(const LAS bf16x8*)(lds + PG8_SB(b, h) + boff + n * 2048 + k * 1024); } while (0)
; #define PG8_MMA(ai, bj, At, Bt) do { __builtin_amdgcn_s_setprio(1); _Pragma("unroll") for (int m = 0; m < 4; ++m) _Pragma("unroll") for (int n = 0; n < 2; ++n) _Pragma("unroll") for (int k = 0; k < 2; ++k) \
;         acc[ai][bj][m][n] = __builtin_amdgcn_mfma_f32_16x16x32_bf16(Bt[n][k], At[m][k], acc[ai][bj][m][n], 0, 0, 0); __builtin_amdgcn_s_setprio(0); } while (0)
; #define PG8_WAIT_V(n) asm volatile("s_waitcnt vmcnt(" #n ")" ::: "memory")
; #define PG8_WAIT_L(n) asm volatile("s_waitcnt lgkmcnt(" #n ")" ::: "memory")
; #define PG8_BAR __builtin_amdgcn_s_barrier()
; #define PG8_SCHED __builtin_amdgcn_sched_barrier(0)
; template <class Epi, bool ALIGN_EPI = PG8_ALIGN, bool SP2 = PG8_SP2>
; __device__ __forceinline__ void gemm_phase(LAS unsigned char* lds, const Gemm g, const StaticOrder& S, const Epi& E) {
;     ...
;             PG8_LDB(B0, 1, 0); PG8_LDB(B1, 1, 1); PG8_SCHED; PG8_LDA(At, 1, 0); PG8_STAGE(PG8_SA(0, 1), a2 + hstepA, voffA);
;             PG8_WAIT_V(8); PG8_WAIT_L(0); PG8_BAR; PG8_MMA(0, 0, At, B0); PG8_MMA(0, 1, At, B1); PG8_BAR; PG8_SCHED;
;             PG8_LDA(At, 1, 1); PG8_STAGE(PG8_SB(1, 0), b3, voffB); PG8_STAGE(PG8_SB(1, 1), b3 + hstepB, voffB); PG8_STAGE(PG8_SA(1, 0), a3, voffA);
;             PG8_WAIT_V(8); PG8_WAIT_L(0); PG8_BAR; PG8_MMA(1, 0, At, B0); PG8_MMA(1, 1, At, B1); PG8_BAR; PG8_SCHED;
	s_add_i32 s24, s41, s3
	v_lshl_add_u64 v[190:191], v[190:191], 0, s[50:51]
	s_mov_b32 m0, s24
	ds_read_b128 v[178:181], v145 offset:49152
	ds_read_b128 v[182:185], v145 offset:50176
	ds_read_b128 v[186:189], v145 offset:51200
	ds_read_b128 v[194:197], v145 offset:52224
	ds_read_b128 v[206:209], v145 offset:53248
	ds_read_b128 v[210:213], v145 offset:54272
	ds_read_b128 v[214:217], v145 offset:55296
	ds_read_b128 v[218:221], v145 offset:56320
	global_load_lds_dwordx4 v[190:191], off
	s_add_i32 m0, s24, 0x2000
	s_add_u32 s22, s22, 0x40080
	v_lshl_add_u64 v[190:191], v[202:203], 0, s[50:51]
	s_addc_u32 s23, s23, 0
	s_add_i32 s24, s42, s3
	global_load_lds_dwordx4 v[190:191], off
	v_lshl_add_u64 v[190:191], s[22:23], 0, v[132:133]
	s_mov_b32 m0, s24
	s_nop 0
	global_load_lds_dwordx4 v[190:191], off
	v_lshl_add_u64 v[190:191], s[22:23], 0, v[130:131]
	s_add_i32 m0, s24, 0x2000
	s_nop 0
	global_load_lds_dwordx4 v[190:191], off
	v_lshl_add_u64 v[190:191], v[204:205], 0, s[50:51]
	s_mov_b32 m0, s30
	s_nop 0
	global_load_lds_dwordx4 v[190:191], off
	v_lshl_add_u64 v[190:191], v[222:223], 0, s[50:51]
	s_mov_b32 m0, s31
	s_nop 0
	global_load_lds_dwordx4 v[190:191], off
	s_waitcnt vmcnt(8)
	s_waitcnt lgkmcnt(0)
	s_barrier
	s_setprio 1
	s_waitcnt lgkmcnt(0)
	v_mfma_f32_16x16x32_bf16 v[62:65], v[138:141], v[178:181], v[62:65]
	v_mfma_f32_16x16x32_bf16 v[58:61], v[150:153], v[178:181], v[58:61]
	v_mfma_f32_16x16x32_bf16 v[46:49], v[138:141], v[186:189], v[46:49]
	v_mfma_f32_16x16x32_bf16 v[42:45], v[150:153], v[186:189], v[42:45]
	v_mfma_f32_16x16x32_bf16 v[30:33], v[138:141], v[206:209], v[30:33]
	v_mfma_f32_16x16x32_bf16 v[26:29], v[150:153], v[206:209], v[26:29]
	v_mfma_f32_16x16x32_bf16 v[14:17], v[138:141], v[214:217], v[14:17]
	v_mfma_f32_16x16x32_bf16 v[10:13], v[150:153], v[214:217], v[10:13]
	s_setprio 0
	s_setprio 1
	v_mfma_f32_16x16x32_bf16 v[62:65], v[146:149], v[182:185], v[62:65]
	v_mfma_f32_16x16x32_bf16 v[58:61], v[154:157], v[182:185], v[58:61]
	v_mfma_f32_16x16x32_bf16 v[46:49], v[146:149], v[194:197], v[46:49]
	v_mfma_f32_16x16x32_bf16 v[42:45], v[154:157], v[194:197], v[42:45]
	v_mfma_f32_16x16x32_bf16 v[30:33], v[146:149], v[210:213], v[30:33]
	v_mfma_f32_16x16x32_bf16 v[26:29], v[154:157], v[210:213], v[26:29]
	v_mfma_f32_16x16x32_bf16 v[14:17], v[146:149], v[218:221], v[14:17]
	v_mfma_f32_16x16x32_bf16 v[10:13], v[154:157], v[218:221], v[10:13]
	s_setprio 0
	s_setprio 1
	v_mfma_f32_16x16x32_bf16 v[54:57], v[158:161], v[178:181], v[54:57]
	v_mfma_f32_16x16x32_bf16 v[50:53], v[170:173], v[178:181], v[50:53]
	v_mfma_f32_16x16x32_bf16 v[38:41], v[158:161], v[186:189], v[38:41]
	v_mfma_f32_16x16x32_bf16 v[34:37], v[170:173], v[186:189], v[34:37]
	v_mfma_f32_16x16x32_bf16 v[22:25], v[158:161], v[206:209], v[22:25]
	v_mfma_f32_16x16x32_bf16 v[18:21], v[170:173], v[206:209], v[18:21]
	v_mfma_f32_16x16x32_bf16 v[6:9], v[158:161], v[214:217], v[6:9]
	v_mfma_f32_16x16x32_bf16 v[2:5], v[170:173], v[214:217], v[2:5]
	s_setprio 0
	s_setprio 1
	v_mfma_f32_16x16x32_bf16 v[54:57], v[164:167], v[182:185], v[54:57]
	v_mfma_f32_16x16x32_bf16 v[50:53], v[174:177], v[182:185], v[50:53]
	v_mfma_f32_16x16x32_bf16 v[38:41], v[164:167], v[194:197], v[38:41]
	v_mfma_f32_16x16x32_bf16 v[34:37], v[174:177], v[194:197], v[34:37]
	v_mfma_f32_16x16x32_bf16 v[22:25], v[164:167], v[210:213], v[22:25]
	v_mfma_f32_16x16x32_bf16 v[18:21], v[174:177], v[210:213], v[18:21]
	v_mfma_f32_16x16x32_bf16 v[6:9], v[164:167], v[218:221], v[6:9]
	v_mfma_f32_16x16x32_bf16 v[2:5], v[174:177], v[218:221], v[2:5]
	s_setprio 0
	s_barrier
	s_add_i32 s40, s40, 2
	s_add_u32 s4, s4, 0x100
	s_addc_u32 s5, s5, 0
	s_add_u32 s38, s38, 0x100
	s_addc_u32 s39, s39, 0
	s_cmp_gt_u32 s40, 13
	s_branch .LBB0_139

; #define PG8_STAGE(bufoff, gbase, voff) do { _Pragma("unroll") for (int _i = 0; _i < 2; ++_i) \
;         __builtin_amdgcn_global_load_lds((const unsigned*)((const char*)(gbase) + (voff)[_i]), (LAS unsigned*)(lds + (bufoff) + ldsw + _i * 8192), 16, 0, 0); } while (0)
; #define PG8_LDA(dst, b, h) do { _Pragma("unroll") for (int m = 0; m < 4; ++m) _Pragma("unroll") for (int k = 0; k < 2; ++k) dst[m][k] = *(const LAS bf16x8*)(lds + PG8_SA(b, h) + aoff + m * 2048 + k * 1024); } while (0)
; #define PG8_LDB(dst, b, h) do { _Pragma("unroll") for (int n = 0; n < 2; ++n) _Pragma("unroll") for (int k = 0; k < 2; ++k) dst[n][k] = *(const LAS bf16x8*)(lds + PG8_SB(b, h) + boff + n * 2048 + k * 1024); } while (0)
; #define PG8_WAIT_V(n) asm volatile("s_waitcnt vmcnt(" #n ")" ::: "memory")
; #define PG8_WAIT_L(n) asm volatile("s_waitcnt lgkmcnt(" #n ")" ::: "memory")
; #define PG8_BAR __builtin_amdgcn_s_barrier()
; #define PG8_SCHED __builtin_amdgcn_sched_barrier(0)
; template <class Epi, bool ALIGN_EPI = PG8_ALIGN, bool SP2 = PG8_SP2>
; __device__ __forceinline__ void gemm_phase(LAS unsigned char* lds, const Gemm g, const StaticOrder& S, const Epi& E) {
;     ...
;         const bool has_next = S.next(ui + 1, nxt);
;         const char* nA = has_next ? (const char*)g.A + (size_t)nxt.pm * tstepA : cA; const char* nB = has_next ? (const char*)g.Bt + (size_t)nxt.pn * tstepB : cB;
;         for (int t = 0; t < nt; t += 2) {
;             const bool last = (t == nt - 2);
;             const char* a1 = cA + (size_t)(t + 1) * kstepA;
;             const char* a2 = last ? nA : cA + (size_t)(t + 2) * kstepA; const char* b2 = last ? nB : cB + (size_t)(t + 2) * kstepB;
;             const char* a3 = a2 + kstepA; const char* b3 = b2 + kstepB;
;             if constexpr (SP2) {
;             PG8_LDB(B0, 0, 0); PG8_LDB(B1, 0, 1); PG8_SCHED; PG8_LDA(At, 0, 0); PG8_STAGE(PG8_SA(1, 1), a1 + hstepA, voffA);
;             PG8_WAIT_V(8); PG8_WAIT_L(0); PG8_BAR; PG8_MMA(0, 0, At, B0); PG8_MMA(0, 1, At, B1); PG8_BAR; PG8_SCHED;
;             PG8_LDA(At, 0, 1); PG8_STAGE(PG8_SB(0, 0), b2, voffB); PG8_STAGE(PG8_SB(0, 1), b2 + hstepB, voffB); PG8_STAGE(PG8_SA(0, 0), a2, voffA);
;             PG8_WAIT_V(8); PG8_WAIT_L(0); PG8_BAR; PG8_MMA(1, 0, At, B0); PG8_MMA(1, 1, At, B1); PG8_BAR; PG8_SCHED;
.LBB0_535:
	s_cmp_eq_u32 s39, -2
	s_cbranch_scc1 .Lfirst_iter_u535
	s_add_u32 s4, s0, 0xfffc0080
	s_addc_u32 s5, s1, -1
	s_add_i32 s40, 0, 0x10000
	s_cmp_eq_u32 s39, 12
	s_cselect_b32 s9, s19, s5
	s_cselect_b32 s8, s35, s4
	v_add_u32_e32 v0, s40, v206
	s_cselect_b32 s5, s17, s38
	s_cselect_b32 s4, s36, s37
	s_add_i32 s42, 0, 0x14000
	ds_read_b128 v[114:117], v0
	ds_read_b128 v[122:125], v0 offset:1024
	ds_read_b128 v[130:133], v0 offset:2048
	ds_read_b128 v[134:137], v0 offset:3072
	v_add_u32_e32 v0, s42, v206
	ds_read_b128 v[146:149], v0
	ds_read_b128 v[150:153], v0 offset:1024
	ds_read_b128 v[154:157], v0 offset:2048
	ds_read_b128 v[158:161], v0 offset:3072
	v_lshl_add_u64 v[190:191], s[0:1], 0, v[178:179]
	s_add_i32 m0, s24, 0xc000
	ds_read_b128 v[164:167], v211
	ds_read_b128 v[182:185], v211 offset:1024
	ds_read_b128 v[186:189], v211 offset:2048
	ds_read_b128 v[194:197], v211 offset:3072
	ds_read_b128 v[212:215], v211 offset:4096
	ds_read_b128 v[216:219], v211 offset:5120
	ds_read_b128 v[220:223], v211 offset:6144
	ds_read_b128 v[224:227], v211 offset:7168
	global_load_lds_dwordx4 v[190:191], off
	v_lshl_add_u64 v[190:191], s[0:1], 0, v[180:181]
	s_add_i32 m0, s24, 0xe000
	s_nop 0
	global_load_lds_dwordx4 v[190:191], off
	s_waitcnt vmcnt(8)
	s_waitcnt lgkmcnt(0)
	s_barrier
	s_setprio 1
	s_waitcnt lgkmcnt(0)
	v_mfma_f32_16x16x32_bf16 v[70:73], v[114:117], v[164:167], v[70:73]
	v_mfma_f32_16x16x32_bf16 v[30:33], v[130:133], v[164:167], v[30:33]
	v_mfma_f32_16x16x32_bf16 v[58:61], v[114:117], v[186:189], v[58:61]
	v_mfma_f32_16x16x32_bf16 v[26:29], v[130:133], v[186:189], v[26:29]
	v_mfma_f32_16x16x32_bf16 v[54:57], v[114:117], v[212:215], v[54:57]
	v_mfma_f32_16x16x32_bf16 v[22:25], v[130:133], v[212:215], v[22:25]
	v_mfma_f32_16x16x32_bf16 v[50:53], v[114:117], v[220:223], v[50:53]
	v_mfma_f32_16x16x32_bf16 v[18:21], v[130:133], v[220:223], v[18:21]
	s_setprio 0
	s_setprio 1
	v_mfma_f32_16x16x32_bf16 v[70:73], v[122:125], v[182:185], v[70:73]
	v_mfma_f32_16x16x32_bf16 v[30:33], v[134:137], v[182:185], v[30:33]
	v_mfma_f32_16x16x32_bf16 v[58:61], v[122:125], v[194:197], v[58:61]
	v_mfma_f32_16x16x32_bf16 v[26:29], v[134:137], v[194:197], v[26:29]
	v_mfma_f32_16x16x32_bf16 v[54:57], v[122:125], v[216:219], v[54:57]
	v_mfma_f32_16x16x32_bf16 v[22:25], v[134:137], v[216:219], v[22:25]
	v_mfma_f32_16x16x32_bf16 v[50:53], v[122:125], v[224:227], v[50:53]
	v_mfma_f32_16x16x32_bf16 v[18:21], v[134:137], v[224:227], v[18:21]
	s_setprio 0
	s_setprio 1
	v_mfma_f32_16x16x32_bf16 v[142:145], v[146:149], v[164:167], v[142:145]
	v_mfma_f32_16x16x32_bf16 v[138:141], v[154:157], v[164:167], v[138:141]
	v_mfma_f32_16x16x32_bf16 v[126:129], v[146:149], v[186:189], v[126:129]
	v_mfma_f32_16x16x32_bf16 v[118:121], v[154:157], v[186:189], v[118:121]
	v_mfma_f32_16x16x32_bf16 v[110:113], v[146:149], v[212:215], v[110:113]
	v_mfma_f32_16x16x32_bf16 v[106:109], v[154:157], v[212:215], v[106:109]
	v_mfma_f32_16x16x32_bf16 v[102:105], v[146:149], v[220:223], v[102:105]
	v_mfma_f32_16x16x32_bf16 v[98:101], v[154:157], v[220:223], v[98:101]
	s_setprio 0
	s_setprio 1
	v_mfma_f32_16x16x32_bf16 v[142:145], v[150:153], v[182:185], v[142:145]
	v_mfma_f32_16x16x32_bf16 v[138:141], v[158:161], v[182:185], v[138:141]
	v_mfma_f32_16x16x32_bf16 v[126:129], v[150:153], v[194:197], v[126:129]
	v_mfma_f32_16x16x32_bf16 v[118:121], v[158:161], v[194:197], v[118:121]
	v_mfma_f32_16x16x32_bf16 v[110:113], v[150:153], v[216:219], v[110:113]
	v_mfma_f32_16x16x32_bf16 v[106:109], v[158:161], v[216:219], v[106:109]
	v_mfma_f32_16x16x32_bf16 v[102:105], v[150:153], v[224:227], v[102:105]
	v_mfma_f32_16x16x32_bf16 v[98:101], v[158:161], v[224:227], v[98:101]
	s_setprio 0
	s_barrier
	s_add_i32 s40, s40, s3
	v_lshl_add_u64 v[190:191], s[4:5], 0, v[172:173]
	s_mov_b32 m0, s40
	ds_read_b128 v[164:167], v211 offset:16384
	ds_read_b128 v[182:185], v211 offset:17408
	ds_read_b128 v[186:189], v211 offset:18432
	ds_read_b128 v[194:197], v211 offset:19456
	ds_read_b128 v[212:215], v211 offset:20480
	ds_read_b128 v[216:219], v211 offset:21504
	ds_read_b128 v[220:223], v211 offset:22528
	ds_read_b128 v[224:227], v211 offset:23552
	global_load_lds_dwordx4 v[190:191], off
	s_add_i32 m0, s40, 0x2000
	s_add_u32 s40, s4, 0x40000
	v_lshl_add_u64 v[202:203], s[4:5], 0, v[170:171]
	s_addc_u32 s41, s5, 0
	s_add_i32 s42, s42, s3
	global_load_lds_dwordx4 v[202:203], off
	v_lshl_add_u64 v[228:229], s[40:41], 0, v[172:173]
	s_mov_b32 m0, s42
	v_lshl_add_u64 v[230:231], s[8:9], 0, v[170:171]
	global_load_lds_dwordx4 v[228:229], off
	v_lshl_add_u64 v[228:229], s[40:41], 0, v[170:171]
	s_add_i32 m0, s42, 0x2000
	s_nop 0
	global_load_lds_dwordx4 v[228:229], off
	v_lshl_add_u64 v[228:229], s[8:9], 0, v[172:173]
	s_mov_b32 m0, s24
	s_nop 0
	global_load_lds_dwordx4 v[228:229], off
	s_mov_b32 m0, s25
	s_nop 0
	global_load_lds_dwordx4 v[230:231], off
	s_waitcnt vmcnt(8)
	s_waitcnt lgkmcnt(0)
	s_barrier
; #define PG8_STAGE(bufoff, gbase, voff) do { _Pragma("unroll") for (int _i = 0; _i < 2; ++_i) \
;         __builtin_amdgcn_global_load_lds((const unsigned*)((const char*)(gbase) + (voff)[_i]), (LAS unsigned*)(lds + (bufoff) + ldsw + _i * 8192), 16, 0, 0); } while (0)
; #define PG8_LDA(dst, b, h) do { _Pragma("unroll") for (int m = 0; m < 4; ++m) _Pragma("unroll") for (int k = 0; k < 2; ++k) dst[m][k] = *(const LAS bf16x8*)(lds + PG8_SA(b, h) + aoff + m * 2048 + k * 1024); } while (0)
; #define PG8_LDB(dst, b, h) do { _Pragma("unroll") for (int n = 0; n < 2; ++n) _Pragma("unroll") for (int k = 0; k < 2; ++k) dst[n][k] = *(const LAS bf16x8*)(lds + PG8_SB(b, h) + boff + n * 2048 + k * 1024); } while (0)
; #define PG8_MMA(ai, bj, At, Bt) do { __builtin_amdgcn_s_setprio(1); _Pragma("unroll") for (int m = 0; m < 4; ++m) _Pragma("unroll") for (int n = 0; n < 2; ++n) _Pragma("unroll") for (int k = 0; k < 2; ++k) \
;         acc[ai][bj][m][n] = __builtin_amdgcn_mfma_f32_16x16x32_bf16(Bt[n][k], At[m][k], acc[ai][bj][m][n], 0, 0, 0); __builtin_amdgcn_s_setprio(0); } while (0)
; #define PG8_WAIT_V(n) asm volatile("s_waitcnt vmcnt(" #n ")" ::: "memory")
; #define PG8_WAIT_L(n) asm volatile("s_waitcnt lgkmcnt(" #n ")" ::: "memory")
; #define PG8_BAR __builtin_amdgcn_s_barrier()
; #define PG8_SCHED __builtin_amdgcn_sched_barrier(0)
; template <class Epi, bool ALIGN_EPI = PG8_ALIGN, bool SP2 = PG8_SP2>
; __device__ __forceinline__ void gemm_phase(LAS unsigned char* lds, const Gemm g, const StaticOrder& S, const Epi& E) {
;     ...
;             PG8_WAIT_V(8); PG8_WAIT_L(0); PG8_BAR; PG8_MMA(1, 0, At, B0); PG8_MMA(1, 1, At, B1); PG8_BAR; PG8_SCHED;
;             PG8_LDB(B0, 1, 0); PG8_LDB(B1, 1, 1); PG8_SCHED; PG8_LDA(At, 1, 0); PG8_STAGE(PG8_SA(0, 1), a2 + hstepA, voffA);
;             PG8_WAIT_V(8); PG8_WAIT_L(0); PG8_BAR; PG8_MMA(0, 0, At, B0); PG8_MMA(0, 1, At, B1); PG8_BAR; PG8_SCHED;
	s_setprio 1
	s_waitcnt lgkmcnt(0)
	v_mfma_f32_16x16x32_bf16 v[46:49], v[114:117], v[164:167], v[46:49]
	v_mfma_f32_16x16x32_bf16 v[14:17], v[130:133], v[164:167], v[14:17]
	v_mfma_f32_16x16x32_bf16 v[42:45], v[114:117], v[186:189], v[42:45]
	v_mfma_f32_16x16x32_bf16 v[10:13], v[130:133], v[186:189], v[10:13]
	v_mfma_f32_16x16x32_bf16 v[38:41], v[114:117], v[212:215], v[38:41]
	v_mfma_f32_16x16x32_bf16 v[6:9], v[130:133], v[212:215], v[6:9]
	v_mfma_f32_16x16x32_bf16 v[34:37], v[114:117], v[220:223], v[34:37]
	v_mfma_f32_16x16x32_bf16 v[2:5], v[130:133], v[220:223], v[2:5]
	s_setprio 0
	s_setprio 1
	v_mfma_f32_16x16x32_bf16 v[46:49], v[122:125], v[182:185], v[46:49]
	v_mfma_f32_16x16x32_bf16 v[14:17], v[134:137], v[182:185], v[14:17]
	v_mfma_f32_16x16x32_bf16 v[42:45], v[122:125], v[194:197], v[42:45]
	v_mfma_f32_16x16x32_bf16 v[10:13], v[134:137], v[194:197], v[10:13]
	v_mfma_f32_16x16x32_bf16 v[38:41], v[122:125], v[216:219], v[38:41]
	v_mfma_f32_16x16x32_bf16 v[6:9], v[134:137], v[216:219], v[6:9]
	v_mfma_f32_16x16x32_bf16 v[34:37], v[122:125], v[224:227], v[34:37]
	v_mfma_f32_16x16x32_bf16 v[2:5], v[134:137], v[224:227], v[2:5]
	s_setprio 0
	s_setprio 1
	v_mfma_f32_16x16x32_bf16 v[94:97], v[146:149], v[164:167], v[94:97]
	v_mfma_f32_16x16x32_bf16 v[90:93], v[154:157], v[164:167], v[90:93]
	v_mfma_f32_16x16x32_bf16 v[86:89], v[146:149], v[186:189], v[86:89]
	v_mfma_f32_16x16x32_bf16 v[82:85], v[154:157], v[186:189], v[82:85]
	v_mfma_f32_16x16x32_bf16 v[78:81], v[146:149], v[212:215], v[78:81]
	v_mfma_f32_16x16x32_bf16 v[74:77], v[154:157], v[212:215], v[74:77]
	v_mfma_f32_16x16x32_bf16 v[66:69], v[146:149], v[220:223], v[66:69]
	v_mfma_f32_16x16x32_bf16 v[62:65], v[154:157], v[220:223], v[62:65]
	s_setprio 0
	s_setprio 1
	v_mfma_f32_16x16x32_bf16 v[94:97], v[150:153], v[182:185], v[94:97]
	v_mfma_f32_16x16x32_bf16 v[90:93], v[158:161], v[182:185], v[90:93]
	v_mfma_f32_16x16x32_bf16 v[86:89], v[150:153], v[194:197], v[86:89]
	v_mfma_f32_16x16x32_bf16 v[82:85], v[158:161], v[194:197], v[82:85]
	v_mfma_f32_16x16x32_bf16 v[78:81], v[150:153], v[216:219], v[78:81]
	v_mfma_f32_16x16x32_bf16 v[74:77], v[158:161], v[216:219], v[74:77]
	v_mfma_f32_16x16x32_bf16 v[66:69], v[150:153], v[224:227], v[66:69]
	v_mfma_f32_16x16x32_bf16 v[62:65], v[158:161], v[224:227], v[62:65]
	s_setprio 0
	s_barrier
	s_add_i32 s40, 0, 0x18000
	v_add_u32_e32 v0, s40, v206
	s_add_i32 s41, 0, 0x1c000
	ds_read_b128 v[114:117], v0
	ds_read_b128 v[122:125], v0 offset:1024
	ds_read_b128 v[130:133], v0 offset:2048
	ds_read_b128 v[134:137], v0 offset:3072
	v_add_u32_e32 v0, s41, v206
	ds_read_b128 v[146:149], v0
	ds_read_b128 v[150:153], v0 offset:1024
	ds_read_b128 v[154:157], v0 offset:2048
	ds_read_b128 v[158:161], v0 offset:3072
	s_add_u32 s8, s8, 0x40000
	s_addc_u32 s9, s9, 0
	s_mov_b32 m0, s26
	v_lshl_add_u64 v[232:233], s[8:9], 0, v[172:173]
	ds_read_b128 v[164:167], v211 offset:32768
	ds_read_b128 v[182:185], v211 offset:33792
	ds_read_b128 v[186:189], v211 offset:34816
	ds_read_b128 v[194:197], v211 offset:35840
	ds_read_b128 v[212:215], v211 offset:36864
	ds_read_b128 v[216:219], v211 offset:37888
	ds_read_b128 v[220:223], v211 offset:38912
	ds_read_b128 v[224:227], v211 offset:39936
	global_load_lds_dwordx4 v[232:233], off
	v_lshl_add_u64 v[232:233], s[8:9], 0, v[170:171]
	s_mov_b32 m0, s27
	s_nop 0
	global_load_lds_dwordx4 v[232:233], off
	s_waitcnt vmcnt(8)
	s_waitcnt lgkmcnt(0)
	s_barrier
	s_setprio 1
	s_waitcnt lgkmcnt(0)
	v_mfma_f32_16x16x32_bf16 v[70:73], v[114:117], v[164:167], v[70:73]
	v_mfma_f32_16x16x32_bf16 v[30:33], v[130:133], v[164:167], v[30:33]
	v_mfma_f32_16x16x32_bf16 v[58:61], v[114:117], v[186:189], v[58:61]
	v_mfma_f32_16x16x32_bf16 v[26:29], v[130:133], v[186:189], v[26:29]
	v_mfma_f32_16x16x32_bf16 v[54:57], v[114:117], v[212:215], v[54:57]
	v_mfma_f32_16x16x32_bf16 v[22:25], v[130:133], v[212:215], v[22:25]
	v_mfma_f32_16x16x32_bf16 v[50:53], v[114:117], v[220:223], v[50:53]
	v_mfma_f32_16x16x32_bf16 v[18:21], v[130:133], v[220:223], v[18:21]
	s_setprio 0
	s_setprio 1
	v_mfma_f32_16x16x32_bf16 v[70:73], v[122:125], v[182:185], v[70:73]
	v_mfma_f32_16x16x32_bf16 v[30:33], v[134:137], v[182:185], v[30:33]
	v_mfma_f32_16x16x32_bf16 v[58:61], v[122:125], v[194:197], v[58:61]
	v_mfma_f32_16x16x32_bf16 v[26:29], v[134:137], v[194:197], v[26:29]
	v_mfma_f32_16x16x32_bf16 v[54:57], v[122:125], v[216:219], v[54:57]
	v_mfma_f32_16x16x32_bf16 v[22:25], v[134:137], v[216:219], v[22:25]
	v_mfma_f32_16x16x32_bf16 v[50:53], v[122:125], v[224:227], v[50:53]
	v_mfma_f32_16x16x32_bf16 v[18:21], v[134:137], v[224:227], v[18:21]
	s_setprio 0
	s_setprio 1
	v_mfma_f32_16x16x32_bf16 v[142:145], v[146:149], v[164:167], v[142:145]
	v_mfma_f32_16x16x32_bf16 v[138:141], v[154:157], v[164:167], v[138:141]
	v_mfma_f32_16x16x32_bf16 v[126:129], v[146:149], v[186:189], v[126:129]
	v_mfma_f32_16x16x32_bf16 v[118:121], v[154:157], v[186:189], v[118:121]
	v_mfma_f32_16x16x32_bf16 v[110:113], v[146:149], v[212:215], v[110:113]
	v_mfma_f32_16x16x32_bf16 v[106:109], v[154:157], v[212:215], v[106:109]
	v_mfma_f32_16x16x32_bf16 v[102:105], v[146:149], v[220:223], v[102:105]
	v_mfma_f32_16x16x32_bf16 v[98:101], v[154:157], v[220:223], v[98:101]
	s_setprio 0
	s_setprio 1
	v_mfma_f32_16x16x32_bf16 v[142:145], v[150:153], v[182:185], v[142:145]
	v_mfma_f32_16x16x32_bf16 v[138:141], v[158:161], v[182:185], v[138:141]
	v_mfma_f32_16x16x32_bf16 v[126:129], v[150:153], v[194:197], v[126:129]
	v_mfma_f32_16x16x32_bf16 v[118:121], v[158:161], v[194:197], v[118:121]
	v_mfma_f32_16x16x32_bf16 v[110:113], v[150:153], v[216:219], v[110:113]
	v_mfma_f32_16x16x32_bf16 v[106:109], v[158:161], v[216:219], v[106:109]
	v_mfma_f32_16x16x32_bf16 v[102:105], v[150:153], v[224:227], v[102:105]
	v_mfma_f32_16x16x32_bf16 v[98:101], v[158:161], v[224:227], v[98:101]
	s_setprio 0
	s_barrier
; #define PG8_STAGE(bufoff, gbase, voff) do { _Pragma("unroll") for (int _i = 0; _i < 2; ++_i) \
;         __builtin_amdgcn_global_load_lds((const unsigned*)((const char*)(gbase) + (voff)[_i]), (LAS unsigned*)(lds + (bufoff) + ldsw + _i * 8192), 16, 0, 0); } while (0)
; #define PG8_LDA(dst, b, h) do { _Pragma("unroll") for (int m = 0; m < 4; ++m) _Pragma("unroll") for (int k = 0; k < 2; ++k) dst[m][k] = *(const LAS bf16x8*)(lds + PG8_SA(b, h) + aoff + m * 2048 + k * 1024); } while (0)
; #define PG8_LDB(dst, b, h) do { _Pragma("unroll") for (int n = 0; n < 2; ++n) _Pragma("unroll") for (int k = 0; k < 2; ++k) dst[n][k] = *(const LAS bf16x8*)(lds + PG8_SB(b, h) + boff + n * 2048 + k * 1024); } while (0)
; #define PG8_MMA(ai, bj, At, Bt) do { __builtin_amdgcn_s_setprio(1); _Pragma("unroll") for (int m = 0; m < 4; ++m) _Pragma("unroll") for (int n = 0; n < 2; ++n) _Pragma("unroll") for (int k = 0; k < 2; ++k) \
;         acc[ai][bj][m][n] = __builtin_amdgcn_mfma_f32_16x16x32_bf16(Bt[n][k], At[m][k], acc[ai][bj][m][n], 0, 0, 0); __builtin_amdgcn_s_setprio(0); } while (0)
; #define PG8_WAIT_V(n) asm volatile("s_waitcnt vmcnt(" #n ")" ::: "memory")
; #define PG8_WAIT_L(n) asm volatile("s_waitcnt lgkmcnt(" #n ")" ::: "memory")
; #define PG8_BAR __builtin_amdgcn_s_barrier()
; #define PG8_SCHED __builtin_amdgcn_sched_barrier(0)
; template <class Epi, bool ALIGN_EPI = PG8_ALIGN, bool SP2 = PG8_SP2>
; __device__ __forceinline__ void gemm_phase(LAS unsigned char* lds, const Gemm g, const StaticOrder& S, const Epi& E) {
;     ...
;             PG8_LDB(B0, 1, 0); PG8_LDB(B1, 1, 1); PG8_SCHED; PG8_LDA(At, 1, 0); PG8_STAGE(PG8_SA(0, 1), a2 + hstepA, voffA);
;             PG8_WAIT_V(8); PG8_WAIT_L(0); PG8_BAR; PG8_MMA(0, 0, At, B0); PG8_MMA(0, 1, At, B1); PG8_BAR; PG8_SCHED;
;             PG8_LDA(At, 1, 1); PG8_STAGE(PG8_SB(1, 0), b3, voffB); PG8_STAGE(PG8_SB(1, 1), b3 + hstepB, voffB); PG8_STAGE(PG8_SA(1, 0), a3, voffA);
;             PG8_WAIT_V(8); PG8_WAIT_L(0); PG8_BAR; PG8_MMA(1, 0, At, B0); PG8_MMA(1, 1, At, B1); PG8_BAR; PG8_SCHED;
	s_add_i32 s8, s40, s3
	v_lshl_add_u64 v[190:191], v[190:191], 0, s[50:51]
	s_mov_b32 m0, s8
	ds_read_b128 v[164:167], v211 offset:49152
	ds_read_b128 v[182:185], v211 offset:50176
	ds_read_b128 v[186:189], v211 offset:51200
	ds_read_b128 v[194:197], v211 offset:52224
	ds_read_b128 v[212:215], v211 offset:53248
	ds_read_b128 v[216:219], v211 offset:54272
	ds_read_b128 v[220:223], v211 offset:55296
	ds_read_b128 v[224:227], v211 offset:56320
	global_load_lds_dwordx4 v[190:191], off
	s_add_i32 m0, s8, 0x2000
	s_add_u32 s4, s4, 0x40080
	v_lshl_add_u64 v[190:191], v[202:203], 0, s[50:51]
	s_addc_u32 s5, s5, 0
	s_add_i32 s8, s41, s3
	global_load_lds_dwordx4 v[190:191], off
	v_lshl_add_u64 v[190:191], s[4:5], 0, v[172:173]
	s_mov_b32 m0, s8
	s_nop 0
	global_load_lds_dwordx4 v[190:191], off
	v_lshl_add_u64 v[190:191], s[4:5], 0, v[170:171]
	s_add_i32 m0, s8, 0x2000
	s_nop 0
	global_load_lds_dwordx4 v[190:191], off
	v_lshl_add_u64 v[190:191], v[228:229], 0, s[50:51]
	s_mov_b32 m0, s29
	s_nop 0
	global_load_lds_dwordx4 v[190:191], off
	v_lshl_add_u64 v[190:191], v[230:231], 0, s[50:51]
	s_mov_b32 m0, s30
	s_nop 0
	global_load_lds_dwordx4 v[190:191], off
	s_waitcnt vmcnt(8)
	s_waitcnt lgkmcnt(0)
	s_barrier
	s_setprio 1
	s_waitcnt lgkmcnt(0)
	v_mfma_f32_16x16x32_bf16 v[46:49], v[114:117], v[164:167], v[46:49]
	v_mfma_f32_16x16x32_bf16 v[14:17], v[130:133], v[164:167], v[14:17]
	v_mfma_f32_16x16x32_bf16 v[42:45], v[114:117], v[186:189], v[42:45]
	v_mfma_f32_16x16x32_bf16 v[10:13], v[130:133], v[186:189], v[10:13]
	v_mfma_f32_16x16x32_bf16 v[38:41], v[114:117], v[212:215], v[38:41]
	v_mfma_f32_16x16x32_bf16 v[6:9], v[130:133], v[212:215], v[6:9]
	v_mfma_f32_16x16x32_bf16 v[34:37], v[114:117], v[220:223], v[34:37]
	v_mfma_f32_16x16x32_bf16 v[2:5], v[130:133], v[220:223], v[2:5]
	s_setprio 0
	s_setprio 1
	v_mfma_f32_16x16x32_bf16 v[46:49], v[122:125], v[182:185], v[46:49]
	v_mfma_f32_16x16x32_bf16 v[14:17], v[134:137], v[182:185], v[14:17]
	v_mfma_f32_16x16x32_bf16 v[42:45], v[122:125], v[194:197], v[42:45]
	v_mfma_f32_16x16x32_bf16 v[10:13], v[134:137], v[194:197], v[10:13]
	v_mfma_f32_16x16x32_bf16 v[38:41], v[122:125], v[216:219], v[38:41]
	v_mfma_f32_16x16x32_bf16 v[6:9], v[134:137], v[216:219], v[6:9]
	v_mfma_f32_16x16x32_bf16 v[34:37], v[122:125], v[224:227], v[34:37]
	v_mfma_f32_16x16x32_bf16 v[2:5], v[134:137], v[224:227], v[2:5]
	s_setprio 0
	s_setprio 1
	v_mfma_f32_16x16x32_bf16 v[94:97], v[146:149], v[164:167], v[94:97]
	v_mfma_f32_16x16x32_bf16 v[90:93], v[154:157], v[164:167], v[90:93]
	v_mfma_f32_16x16x32_bf16 v[86:89], v[146:149], v[186:189], v[86:89]
	v_mfma_f32_16x16x32_bf16 v[82:85], v[154:157], v[186:189], v[82:85]
	v_mfma_f32_16x16x32_bf16 v[78:81], v[146:149], v[212:215], v[78:81]
	v_mfma_f32_16x16x32_bf16 v[74:77], v[154:157], v[212:215], v[74:77]
	v_mfma_f32_16x16x32_bf16 v[66:69], v[146:149], v[220:223], v[66:69]
	v_mfma_f32_16x16x32_bf16 v[62:65], v[154:157], v[220:223], v[62:65]
	s_setprio 0
	s_setprio 1
	v_mfma_f32_16x16x32_bf16 v[94:97], v[150:153], v[182:185], v[94:97]
	v_mfma_f32_16x16x32_bf16 v[90:93], v[158:161], v[182:185], v[90:93]
	v_mfma_f32_16x16x32_bf16 v[86:89], v[150:153], v[194:197], v[86:89]
	v_mfma_f32_16x16x32_bf16 v[82:85], v[158:161], v[194:197], v[82:85]
	v_mfma_f32_16x16x32_bf16 v[78:81], v[150:153], v[216:219], v[78:81]
	v_mfma_f32_16x16x32_bf16 v[74:77], v[158:161], v[216:219], v[74:77]
	v_mfma_f32_16x16x32_bf16 v[66:69], v[150:153], v[224:227], v[66:69]
	v_mfma_f32_16x16x32_bf16 v[62:65], v[158:161], v[224:227], v[62:65]
	s_setprio 0
	s_barrier
	s_add_i32 s39, s39, 2
	s_add_u32 s0, s0, 0x100
	s_addc_u32 s1, s1, 0
	s_add_u32 s37, s37, 0x100
	s_addc_u32 s38, s38, 0
	s_cmp_gt_u32 s39, 13
	s_cbranch_scc0 .LBB0_535
	s_and_b64 vcc, exec, s[12:13]
	s_cbranch_vccz .LBB0_538
	s_barrier

; #define PG8_STAGE(bufoff, gbase, voff) do { _Pragma("unroll") for (int _i = 0; _i < 2; ++_i) \
;         __builtin_amdgcn_global_load_lds((const unsigned*)((const char*)(gbase) + (voff)[_i]), (LAS unsigned*)(lds + (bufoff) + ldsw + _i * 8192), 16, 0, 0); } while (0)
; #define PG8_LDA(dst, b, h) do { _Pragma("unroll") for (int m = 0; m < 4; ++m) _Pragma("unroll") for (int k = 0; k < 2; ++k) dst[m][k] = *(const LAS bf16x8*)(lds + PG8_SA(b, h) + aoff + m * 2048 + k * 1024); } while (0)
; #define PG8_LDB(dst, b, h) do { _Pragma("unroll") for (int n = 0; n < 2; ++n) _Pragma("unroll") for (int k = 0; k < 2; ++k) dst[n][k] = *(const LAS bf16x8*)(lds + PG8_SB(b, h) + boff + n * 2048 + k * 1024); } while (0)
; #define PG8_MMA(ai, bj, At, Bt) do { __builtin_amdgcn_s_setprio(1); _Pragma("unroll") for (int m = 0; m < 4; ++m) _Pragma("unroll") for (int n = 0; n < 2; ++n) _Pragma("unroll") for (int k = 0; k < 2; ++k) \
;         acc[ai][bj][m][n] = __builtin_amdgcn_mfma_f32_16x16x32_bf16(Bt[n][k], At[m][k], acc[ai][bj][m][n], 0, 0, 0); __builtin_amdgcn_s_setprio(0); } while (0)
; #define PG8_WAIT_V(n) asm volatile("s_waitcnt vmcnt(" #n ")" ::: "memory")
; #define PG8_WAIT_L(n) asm volatile("s_waitcnt lgkmcnt(" #n ")" ::: "memory")
; #define PG8_BAR __builtin_amdgcn_s_barrier()
; #define PG8_SCHED __builtin_amdgcn_sched_barrier(0)
; template <class Epi, bool ALIGN_EPI = PG8_ALIGN, bool SP2 = PG8_SP2>
; __device__ __forceinline__ void gemm_phase(LAS unsigned char* lds, const Gemm g, const StaticOrder& S, const Epi& E) {
;     ...
;             const bool last = (t == nt - 2);
;             const char* a1 = cA + (size_t)(t + 1) * kstepA;
;             const char* a2 = last ? nA : cA + (size_t)(t + 2) * kstepA; const char* b2 = last ? nB : cB + (size_t)(t + 2) * kstepB;
;             const char* a3 = a2 + kstepA; const char* b3 = b2 + kstepB;
;             if constexpr (SP2) {
;             PG8_LDB(B0, 0, 0); PG8_LDB(B1, 0, 1); PG8_SCHED; PG8_LDA(At, 0, 0); PG8_STAGE(PG8_SA(1, 1), a1 + hstepA, voffA);
;             PG8_WAIT_V(8); PG8_WAIT_L(0); PG8_BAR; PG8_MMA(0, 0, At, B0); PG8_MMA(0, 1, At, B1); PG8_BAR; PG8_SCHED;
;             PG8_LDA(At, 0, 1); PG8_STAGE(PG8_SB(0, 0), b2, voffB); PG8_STAGE(PG8_SB(0, 1), b2 + hstepB, voffB); PG8_STAGE(PG8_SA(0, 0), a2, voffA);
;             PG8_WAIT_V(8); PG8_WAIT_L(0); PG8_BAR; PG8_MMA(1, 0, At, B0); PG8_MMA(1, 1, At, B1); PG8_BAR; PG8_SCHED;
.Lfirst_iter_u535:
	s_add_u32 s4, s0, 0xfffc0080
	s_addc_u32 s5, s1, -1
	s_add_i32 s40, 0, 0x10000
	s_cmp_eq_u32 s39, 12
	s_cselect_b32 s9, s19, s5
	s_cselect_b32 s8, s35, s4
	v_add_u32_e32 v0, s40, v206
	s_cselect_b32 s5, s17, s38
	s_cselect_b32 s4, s36, s37
	s_add_i32 s42, 0, 0x14000
	ds_read_b128 v[114:117], v0
	ds_read_b128 v[122:125], v0 offset:1024
	ds_read_b128 v[130:133], v0 offset:2048
	ds_read_b128 v[134:137], v0 offset:3072
	v_add_u32_e32 v0, s42, v206
	ds_read_b128 v[146:149], v0
	ds_read_b128 v[150:153], v0 offset:1024
	ds_read_b128 v[154:157], v0 offset:2048
	ds_read_b128 v[158:161], v0 offset:3072
	v_lshl_add_u64 v[190:191], s[0:1], 0, v[178:179]
	s_add_i32 m0, s24, 0xc000
	ds_read_b128 v[164:167], v211
	ds_read_b128 v[182:185], v211 offset:1024
	ds_read_b128 v[186:189], v211 offset:2048
	ds_read_b128 v[194:197], v211 offset:3072
	ds_read_b128 v[212:215], v211 offset:4096
	ds_read_b128 v[216:219], v211 offset:5120
	ds_read_b128 v[220:223], v211 offset:6144
	ds_read_b128 v[224:227], v211 offset:7168
	global_load_lds_dwordx4 v[190:191], off
	v_lshl_add_u64 v[190:191], s[0:1], 0, v[180:181]
	s_add_i32 m0, s24, 0xe000
	s_nop 0
	global_load_lds_dwordx4 v[190:191], off
	s_waitcnt vmcnt(8)
	s_waitcnt lgkmcnt(0)
	s_barrier
	s_setprio 1
	s_waitcnt lgkmcnt(0)
	v_mfma_f32_16x16x32_bf16 v[70:73], v[114:117], v[164:167], 0
	v_mfma_f32_16x16x32_bf16 v[30:33], v[130:133], v[164:167], 0
	v_mfma_f32_16x16x32_bf16 v[58:61], v[114:117], v[186:189], 0
	v_mfma_f32_16x16x32_bf16 v[26:29], v[130:133], v[186:189], 0
	v_mfma_f32_16x16x32_bf16 v[54:57], v[114:117], v[212:215], 0
	v_mfma_f32_16x16x32_bf16 v[22:25], v[130:133], v[212:215], 0
	v_mfma_f32_16x16x32_bf16 v[50:53], v[114:117], v[220:223], 0
	v_mfma_f32_16x16x32_bf16 v[18:21], v[130:133], v[220:223], 0
	s_setprio 0
	s_setprio 1
	v_mfma_f32_16x16x32_bf16 v[70:73], v[122:125], v[182:185], v[70:73]
	v_mfma_f32_16x16x32_bf16 v[30:33], v[134:137], v[182:185], v[30:33]
	v_mfma_f32_16x16x32_bf16 v[58:61], v[122:125], v[194:197], v[58:61]
	v_mfma_f32_16x16x32_bf16 v[26:29], v[134:137], v[194:197], v[26:29]
	v_mfma_f32_16x16x32_bf16 v[54:57], v[122:125], v[216:219], v[54:57]
	v_mfma_f32_16x16x32_bf16 v[22:25], v[134:137], v[216:219], v[22:25]
	v_mfma_f32_16x16x32_bf16 v[50:53], v[122:125], v[224:227], v[50:53]
	v_mfma_f32_16x16x32_bf16 v[18:21], v[134:137], v[224:227], v[18:21]
	s_setprio 0
	s_setprio 1
	v_mfma_f32_16x16x32_bf16 v[142:145], v[146:149], v[164:167], 0
	v_mfma_f32_16x16x32_bf16 v[138:141], v[154:157], v[164:167], 0
	v_mfma_f32_16x16x32_bf16 v[126:129], v[146:149], v[186:189], 0
	v_mfma_f32_16x16x32_bf16 v[118:121], v[154:157], v[186:189], 0
	v_mfma_f32_16x16x32_bf16 v[110:113], v[146:149], v[212:215], 0
	v_mfma_f32_16x16x32_bf16 v[106:109], v[154:157], v[212:215], 0
	v_mfma_f32_16x16x32_bf16 v[102:105], v[146:149], v[220:223], 0
	v_mfma_f32_16x16x32_bf16 v[98:101], v[154:157], v[220:223], 0
	s_setprio 0
	s_setprio 1
	v_mfma_f32_16x16x32_bf16 v[142:145], v[150:153], v[182:185], v[142:145]
	v_mfma_f32_16x16x32_bf16 v[138:141], v[158:161], v[182:185], v[138:141]
	v_mfma_f32_16x16x32_bf16 v[126:129], v[150:153], v[194:197], v[126:129]
	v_mfma_f32_16x16x32_bf16 v[118:121], v[158:161], v[194:197], v[118:121]
	v_mfma_f32_16x16x32_bf16 v[110:113], v[150:153], v[216:219], v[110:113]
	v_mfma_f32_16x16x32_bf16 v[106:109], v[158:161], v[216:219], v[106:109]
	v_mfma_f32_16x16x32_bf16 v[102:105], v[150:153], v[224:227], v[102:105]
	v_mfma_f32_16x16x32_bf16 v[98:101], v[158:161], v[224:227], v[98:101]
	s_setprio 0
	s_barrier
	s_add_i32 s40, s40, s3
	v_lshl_add_u64 v[190:191], s[4:5], 0, v[172:173]
	s_mov_b32 m0, s40
	ds_read_b128 v[164:167], v211 offset:16384
	ds_read_b128 v[182:185], v211 offset:17408
	ds_read_b128 v[186:189], v211 offset:18432
	ds_read_b128 v[194:197], v211 offset:19456
	ds_read_b128 v[212:215], v211 offset:20480
	ds_read_b128 v[216:219], v211 offset:21504
	ds_read_b128 v[220:223], v211 offset:22528
	ds_read_b128 v[224:227], v211 offset:23552
	global_load_lds_dwordx4 v[190:191], off
	s_add_i32 m0, s40, 0x2000
	s_add_u32 s40, s4, 0x40000
	v_lshl_add_u64 v[202:203], s[4:5], 0, v[170:171]
	s_addc_u32 s41, s5, 0
	s_add_i32 s42, s42, s3
	global_load_lds_dwordx4 v[202:203], off
	v_lshl_add_u64 v[228:229], s[40:41], 0, v[172:173]
	s_mov_b32 m0, s42
	v_lshl_add_u64 v[230:231], s[8:9], 0, v[170:171]
	global_load_lds_dwordx4 v[228:229], off
	v_lshl_add_u64 v[228:229], s[40:41], 0, v[170:171]
	s_add_i32 m0, s42, 0x2000
	s_nop 0
	global_load_lds_dwordx4 v[228:229], off
	v_lshl_add_u64 v[228:229], s[8:9], 0, v[172:173]
	s_mov_b32 m0, s24
	s_nop 0
	global_load_lds_dwordx4 v[228:229], off
	s_mov_b32 m0, s25
	s_nop 0
	global_load_lds_dwordx4 v[230:231], off
	s_waitcnt vmcnt(8)
	s_waitcnt lgkmcnt(0)
	s_barrier
; #define PG8_STAGE(bufoff, gbase, voff) do { _Pragma("unroll") for (int _i = 0; _i < 2; ++_i) \
;         __builtin_amdgcn_global_load_lds((const unsigned*)((const char*)(gbase) + (voff)[_i]), (LAS unsigned*)(lds + (bufoff) + ldsw + _i * 8192), 16, 0, 0); } while (0)
; #define PG8_LDA(dst, b, h) do { _Pragma("unroll") for (int m = 0; m < 4; ++m) _Pragma("unroll") for (int k = 0; k < 2; ++k) dst[m][k] = *(const LAS bf16x8*)(lds + PG8_SA(b, h) + aoff + m * 2048 + k * 1024); } while (0)
; #define PG8_LDB(dst, b, h) do { _Pragma("unroll") for (int n = 0; n < 2; ++n) _Pragma("unroll") for (int k = 0; k < 2; ++k) dst[n][k] = *(const LAS bf16x8*)(lds + PG8_SB(b, h) + boff + n * 2048 + k * 1024); } while (0)
; #define PG8_MMA(ai, bj, At, Bt) do { __builtin_amdgcn_s_setprio(1); _Pragma("unroll") for (int m = 0; m < 4; ++m) _Pragma("unroll") for (int n = 0; n < 2; ++n) _Pragma("unroll") for (int k = 0; k < 2; ++k) \
;         acc[ai][bj][m][n] = __builtin_amdgcn_mfma_f32_16x16x32_bf16(Bt[n][k], At[m][k], acc[ai][bj][m][n], 0, 0, 0); __builtin_amdgcn_s_setprio(0); } while (0)
; #define PG8_WAIT_V(n) asm volatile("s_waitcnt vmcnt(" #n ")" ::: "memory")
; #define PG8_WAIT_L(n) asm volatile("s_waitcnt lgkmcnt(" #n ")" ::: "memory")
; #define PG8_BAR __builtin_amdgcn_s_barrier()
; #define PG8_SCHED __builtin_amdgcn_sched_barrier(0)
; template <class Epi, bool ALIGN_EPI = PG8_ALIGN, bool SP2 = PG8_SP2>
; __device__ __forceinline__ void gemm_phase(LAS unsigned char* lds, const Gemm g, const StaticOrder& S, const Epi& E) {
;     ...
;             PG8_WAIT_V(8); PG8_WAIT_L(0); PG8_BAR; PG8_MMA(1, 0, At, B0); PG8_MMA(1, 1, At, B1); PG8_BAR; PG8_SCHED;
;             PG8_LDB(B0, 1, 0); PG8_LDB(B1, 1, 1); PG8_SCHED; PG8_LDA(At, 1, 0); PG8_STAGE(PG8_SA(0, 1), a2 + hstepA, voffA);
;             PG8_WAIT_V(8); PG8_WAIT_L(0); PG8_BAR; PG8_MMA(0, 0, At, B0); PG8_MMA(0, 1, At, B1); PG8_BAR; PG8_SCHED;
	s_setprio 1
	s_waitcnt lgkmcnt(0)
	v_mfma_f32_16x16x32_bf16 v[46:49], v[114:117], v[164:167], 0
	v_mfma_f32_16x16x32_bf16 v[14:17], v[130:133], v[164:167], 0
	v_mfma_f32_16x16x32_bf16 v[42:45], v[114:117], v[186:189], 0
	v_mfma_f32_16x16x32_bf16 v[10:13], v[130:133], v[186:189], 0
	v_mfma_f32_16x16x32_bf16 v[38:41], v[114:117], v[212:215], 0
	v_mfma_f32_16x16x32_bf16 v[6:9], v[130:133], v[212:215], 0
	v_mfma_f32_16x16x32_bf16 v[34:37], v[114:117], v[220:223], 0
	v_mfma_f32_16x16x32_bf16 v[2:5], v[130:133], v[220:223], 0
	s_setprio 0
	s_setprio 1
	v_mfma_f32_16x16x32_bf16 v[46:49], v[122:125], v[182:185], v[46:49]
	v_mfma_f32_16x16x32_bf16 v[14:17], v[134:137], v[182:185], v[14:17]
	v_mfma_f32_16x16x32_bf16 v[42:45], v[122:125], v[194:197], v[42:45]
	v_mfma_f32_16x16x32_bf16 v[10:13], v[134:137], v[194:197], v[10:13]
	v_mfma_f32_16x16x32_bf16 v[38:41], v[122:125], v[216:219], v[38:41]
	v_mfma_f32_16x16x32_bf16 v[6:9], v[134:137], v[216:219], v[6:9]
	v_mfma_f32_16x16x32_bf16 v[34:37], v[122:125], v[224:227], v[34:37]
	v_mfma_f32_16x16x32_bf16 v[2:5], v[134:137], v[224:227], v[2:5]
	s_setprio 0
	s_setprio 1
	v_mfma_f32_16x16x32_bf16 v[94:97], v[146:149], v[164:167], 0
	v_mfma_f32_16x16x32_bf16 v[90:93], v[154:157], v[164:167], 0
	v_mfma_f32_16x16x32_bf16 v[86:89], v[146:149], v[186:189], 0
	v_mfma_f32_16x16x32_bf16 v[82:85], v[154:157], v[186:189], 0
	v_mfma_f32_16x16x32_bf16 v[78:81], v[146:149], v[212:215], 0
	v_mfma_f32_16x16x32_bf16 v[74:77], v[154:157], v[212:215], 0
	v_mfma_f32_16x16x32_bf16 v[66:69], v[146:149], v[220:223], 0
	v_mfma_f32_16x16x32_bf16 v[62:65], v[154:157], v[220:223], 0
	s_setprio 0
	s_setprio 1
	v_mfma_f32_16x16x32_bf16 v[94:97], v[150:153], v[182:185], v[94:97]
	v_mfma_f32_16x16x32_bf16 v[90:93], v[158:161], v[182:185], v[90:93]
	v_mfma_f32_16x16x32_bf16 v[86:89], v[150:153], v[194:197], v[86:89]
	v_mfma_f32_16x16x32_bf16 v[82:85], v[158:161], v[194:197], v[82:85]
	v_mfma_f32_16x16x32_bf16 v[78:81], v[150:153], v[216:219], v[78:81]
	v_mfma_f32_16x16x32_bf16 v[74:77], v[158:161], v[216:219], v[74:77]
	v_mfma_f32_16x16x32_bf16 v[66:69], v[150:153], v[224:227], v[66:69]
	v_mfma_f32_16x16x32_bf16 v[62:65], v[158:161], v[224:227], v[62:65]
	s_setprio 0
	s_barrier
	s_add_i32 s40, 0, 0x18000
	v_add_u32_e32 v0, s40, v206
	s_add_i32 s41, 0, 0x1c000
	ds_read_b128 v[114:117], v0
	ds_read_b128 v[122:125], v0 offset:1024
	ds_read_b128 v[130:133], v0 offset:2048
	ds_read_b128 v[134:137], v0 offset:3072
	v_add_u32_e32 v0, s41, v206
	ds_read_b128 v[146:149], v0
	ds_read_b128 v[150:153], v0 offset:1024
	ds_read_b128 v[154:157], v0 offset:2048
	ds_read_b128 v[158:161], v0 offset:3072
	s_add_u32 s8, s8, 0x40000
	s_addc_u32 s9, s9, 0
	s_mov_b32 m0, s26
	v_lshl_add_u64 v[232:233], s[8:9], 0, v[172:173]
	ds_read_b128 v[164:167], v211 offset:32768
	ds_read_b128 v[182:185], v211 offset:33792
	ds_read_b128 v[186:189], v211 offset:34816
	ds_read_b128 v[194:197], v211 offset:35840
	ds_read_b128 v[212:215], v211 offset:36864
	ds_read_b128 v[216:219], v211 offset:37888
	ds_read_b128 v[220:223], v211 offset:38912
	ds_read_b128 v[224:227], v211 offset:39936
	global_load_lds_dwordx4 v[232:233], off
	v_lshl_add_u64 v[232:233], s[8:9], 0, v[170:171]
	s_mov_b32 m0, s27
	s_nop 0
	global_load_lds_dwordx4 v[232:233], off
	s_waitcnt vmcnt(8)
	s_waitcnt lgkmcnt(0)
	s_barrier
	s_setprio 1
	s_waitcnt lgkmcnt(0)
	v_mfma_f32_16x16x32_bf16 v[70:73], v[114:117], v[164:167], v[70:73]
	v_mfma_f32_16x16x32_bf16 v[30:33], v[130:133], v[164:167], v[30:33]
	v_mfma_f32_16x16x32_bf16 v[58:61], v[114:117], v[186:189], v[58:61]
	v_mfma_f32_16x16x32_bf16 v[26:29], v[130:133], v[186:189], v[26:29]
	v_mfma_f32_16x16x32_bf16 v[54:57], v[114:117], v[212:215], v[54:57]
	v_mfma_f32_16x16x32_bf16 v[22:25], v[130:133], v[212:215], v[22:25]
	v_mfma_f32_16x16x32_bf16 v[50:53], v[114:117], v[220:223], v[50:53]
	v_mfma_f32_16x16x32_bf16 v[18:21], v[130:133], v[220:223], v[18:21]
	s_setprio 0
	s_setprio 1
	v_mfma_f32_16x16x32_bf16 v[70:73], v[122:125], v[182:185], v[70:73]
	v_mfma_f32_16x16x32_bf16 v[30:33], v[134:137], v[182:185], v[30:33]
	v_mfma_f32_16x16x32_bf16 v[58:61], v[122:125], v[194:197], v[58:61]
	v_mfma_f32_16x16x32_bf16 v[26:29], v[134:137], v[194:197], v[26:29]
	v_mfma_f32_16x16x32_bf16 v[54:57], v[122:125], v[216:219], v[54:57]
	v_mfma_f32_16x16x32_bf16 v[22:25], v[134:137], v[216:219], v[22:25]
	v_mfma_f32_16x16x32_bf16 v[50:53], v[122:125], v[224:227], v[50:53]
	v_mfma_f32_16x16x32_bf16 v[18:21], v[134:137], v[224:227], v[18:21]
	s_setprio 0
	s_setprio 1
	v_mfma_f32_16x16x32_bf16 v[142:145], v[146:149], v[164:167], v[142:145]
	v_mfma_f32_16x16x32_bf16 v[138:141], v[154:157], v[164:167], v[138:141]
	v_mfma_f32_16x16x32_bf16 v[126:129], v[146:149], v[186:189], v[126:129]
	v_mfma_f32_16x16x32_bf16 v[118:121], v[154:157], v[186:189], v[118:121]
	v_mfma_f32_16x16x32_bf16 v[110:113], v[146:149], v[212:215], v[110:113]
	v_mfma_f32_16x16x32_bf16 v[106:109], v[154:157], v[212:215], v[106:109]
	v_mfma_f32_16x16x32_bf16 v[102:105], v[146:149], v[220:223], v[102:105]
	v_mfma_f32_16x16x32_bf16 v[98:101], v[154:157], v[220:223], v[98:101]
	s_setprio 0
	s_setprio 1
	v_mfma_f32_16x16x32_bf16 v[142:145], v[150:153], v[182:185], v[142:145]
	v_mfma_f32_16x16x32_bf16 v[138:141], v[158:161], v[182:185], v[138:141]
	v_mfma_f32_16x16x32_bf16 v[126:129], v[150:153], v[194:197], v[126:129]
	v_mfma_f32_16x16x32_bf16 v[118:121], v[158:161], v[194:197], v[118:121]
	v_mfma_f32_16x16x32_bf16 v[110:113], v[150:153], v[216:219], v[110:113]
	v_mfma_f32_16x16x32_bf16 v[106:109], v[158:161], v[216:219], v[106:109]
	v_mfma_f32_16x16x32_bf16 v[102:105], v[150:153], v[224:227], v[102:105]
	v_mfma_f32_16x16x32_bf16 v[98:101], v[158:161], v[224:227], v[98:101]
	s_setprio 0
	s_barrier
; #define PG8_STAGE(bufoff, gbase, voff) do { _Pragma("unroll") for (int _i = 0; _i < 2; ++_i) \
;         __builtin_amdgcn_global_load_lds((const unsigned*)((const char*)(gbase) + (voff)[_i]), (LAS unsigned*)(lds + (bufoff) + ldsw + _i * 8192), 16, 0, 0); } while (0)
; #define PG8_LDA(dst, b, h) do { _Pragma("unroll") for (int m = 0; m < 4; ++m) _Pragma("unroll") for (int k = 0; k < 2; ++k) dst[m][k] = *(const LAS bf16x8*)(lds + PG8_SA(b, h) + aoff + m * 2048 + k * 1024); } while (0)
; #define PG8_MMA(ai, bj, At, Bt) do { __builtin_amdgcn_s_setprio(1); _Pragma("unroll") for (int m = 0; m < 4; ++m) _Pragma("unroll") for (int n = 0; n < 2; ++n) _Pragma("unroll") for (int k = 0; k < 2; ++k) \
;         acc[ai][bj][m][n] = __builtin_amdgcn_mfma_f32_16x16x32_bf16(Bt[n][k], At[m][k], acc[ai][bj][m][n], 0, 0, 0); __builtin_amdgcn_s_setprio(0); } while (0)
; #define PG8_WAIT_V(n) asm volatile("s_waitcnt vmcnt(" #n ")" ::: "memory")
; #define PG8_WAIT_L(n) asm volatile("s_waitcnt lgkmcnt(" #n ")" ::: "memory")
; #define PG8_BAR __builtin_amdgcn_s_barrier()
; #define PG8_SCHED __builtin_amdgcn_sched_barrier(0)
; template <class Epi, bool ALIGN_EPI = PG8_ALIGN, bool SP2 = PG8_SP2>
; __device__ __forceinline__ void gemm_phase(LAS unsigned char* lds, const Gemm g, const StaticOrder& S, const Epi& E) {
;     ...
;             PG8_LDA(At, 1, 1); PG8_STAGE(PG8_SB(1, 0), b3, voffB); PG8_STAGE(PG8_SB(1, 1), b3 + hstepB, voffB); PG8_STAGE(PG8_SA(1, 0), a3, voffA);
;             PG8_WAIT_V(8); PG8_WAIT_L(0); PG8_BAR; PG8_MMA(1, 0, At, B0); PG8_MMA(1, 1, At, B1); PG8_BAR; PG8_SCHED;
	s_add_i32 s8, s40, s3
	v_lshl_add_u64 v[190:191], v[190:191], 0, s[50:51]
	s_mov_b32 m0, s8
	ds_read_b128 v[164:167], v211 offset:49152
	ds_read_b128 v[182:185], v211 offset:50176
	ds_read_b128 v[186:189], v211 offset:51200
	ds_read_b128 v[194:197], v211 offset:52224
	ds_read_b128 v[212:215], v211 offset:53248
	ds_read_b128 v[216:219], v211 offset:54272
	ds_read_b128 v[220:223], v211 offset:55296
	ds_read_b128 v[224:227], v211 offset:56320
	global_load_lds_dwordx4 v[190:191], off
	s_add_i32 m0, s8, 0x2000
	s_add_u32 s4, s4, 0x40080
	v_lshl_add_u64 v[190:191], v[202:203], 0, s[50:51]
	s_addc_u32 s5, s5, 0
	s_add_i32 s8, s41, s3
	global_load_lds_dwordx4 v[190:191], off
	v_lshl_add_u64 v[190:191], s[4:5], 0, v[172:173]
	s_mov_b32 m0, s8
	s_nop 0
	global_load_lds_dwordx4 v[190:191], off
	v_lshl_add_u64 v[190:191], s[4:5], 0, v[170:171]
	s_add_i32 m0, s8, 0x2000
	s_nop 0
	global_load_lds_dwordx4 v[190:191], off
	v_lshl_add_u64 v[190:191], v[228:229], 0, s[50:51]
	s_mov_b32 m0, s29
	s_nop 0
	global_load_lds_dwordx4 v[190:191], off
	v_lshl_add_u64 v[190:191], v[230:231], 0, s[50:51]
	s_mov_b32 m0, s30
	s_nop 0
	global_load_lds_dwordx4 v[190:191], off
	s_waitcnt vmcnt(8)
	s_waitcnt lgkmcnt(0)
	s_barrier
	s_setprio 1
	s_waitcnt lgkmcnt(0)
	v_mfma_f32_16x16x32_bf16 v[46:49], v[114:117], v[164:167], v[46:49]
	v_mfma_f32_16x16x32_bf16 v[14:17], v[130:133], v[164:167], v[14:17]
	v_mfma_f32_16x16x32_bf16 v[42:45], v[114:117], v[186:189], v[42:45]
	v_mfma_f32_16x16x32_bf16 v[10:13], v[130:133], v[186:189], v[10:13]
	v_mfma_f32_16x16x32_bf16 v[38:41], v[114:117], v[212:215], v[38:41]
	v_mfma_f32_16x16x32_bf16 v[6:9], v[130:133], v[212:215], v[6:9]
	v_mfma_f32_16x16x32_bf16 v[34:37], v[114:117], v[220:223], v[34:37]
	v_mfma_f32_16x16x32_bf16 v[2:5], v[130:133], v[220:223], v[2:5]
	s_setprio 0
	s_setprio 1
	v_mfma_f32_16x16x32_bf16 v[46:49], v[122:125], v[182:185], v[46:49]
	v_mfma_f32_16x16x32_bf16 v[14:17], v[134:137], v[182:185], v[14:17]
	v_mfma_f32_16x16x32_bf16 v[42:45], v[122:125], v[194:197], v[42:45]
	v_mfma_f32_16x16x32_bf16 v[10:13], v[134:137], v[194:197], v[10:13]
	v_mfma_f32_16x16x32_bf16 v[38:41], v[122:125], v[216:219], v[38:41]
	v_mfma_f32_16x16x32_bf16 v[6:9], v[134:137], v[216:219], v[6:9]
	v_mfma_f32_16x16x32_bf16 v[34:37], v[122:125], v[224:227], v[34:37]
	v_mfma_f32_16x16x32_bf16 v[2:5], v[134:137], v[224:227], v[2:5]
	s_setprio 0
	s_setprio 1
	v_mfma_f32_16x16x32_bf16 v[94:97], v[146:149], v[164:167], v[94:97]
	v_mfma_f32_16x16x32_bf16 v[90:93], v[154:157], v[164:167], v[90:93]
	v_mfma_f32_16x16x32_bf16 v[86:89], v[146:149], v[186:189], v[86:89]
	v_mfma_f32_16x16x32_bf16 v[82:85], v[154:157], v[186:189], v[82:85]
	v_mfma_f32_16x16x32_bf16 v[78:81], v[146:149], v[212:215], v[78:81]
	v_mfma_f32_16x16x32_bf16 v[74:77], v[154:157], v[212:215], v[74:77]
	v_mfma_f32_16x16x32_bf16 v[66:69], v[146:149], v[220:223], v[66:69]
	v_mfma_f32_16x16x32_bf16 v[62:65], v[154:157], v[220:223], v[62:65]
	s_setprio 0
	s_setprio 1
	v_mfma_f32_16x16x32_bf16 v[94:97], v[150:153], v[182:185], v[94:97]
	v_mfma_f32_16x16x32_bf16 v[90:93], v[158:161], v[182:185], v[90:93]
	v_mfma_f32_16x16x32_bf16 v[86:89], v[150:153], v[194:197], v[86:89]
	v_mfma_f32_16x16x32_bf16 v[82:85], v[158:161], v[194:197], v[82:85]
	v_mfma_f32_16x16x32_bf16 v[78:81], v[150:153], v[216:219], v[78:81]
	v_mfma_f32_16x16x32_bf16 v[74:77], v[158:161], v[216:219], v[74:77]
	v_mfma_f32_16x16x32_bf16 v[66:69], v[150:153], v[224:227], v[66:69]
	v_mfma_f32_16x16x32_bf16 v[62:65], v[158:161], v[224:227], v[62:65]
	s_setprio 0
	s_barrier
	s_add_i32 s39, s39, 2
	s_add_u32 s0, s0, 0x100
	s_addc_u32 s1, s1, 0
	s_add_u32 s37, s37, 0x100
	s_addc_u32 s38, s38, 0
	s_cmp_gt_u32 s39, 13
	s_branch .LBB0_535

; #define PG8_STAGE(bufoff, gbase, voff) do { _Pragma("unroll") for (int _i = 0; _i < 2; ++_i) \
;         __builtin_amdgcn_global_load_lds((const unsigned*)((const char*)(gbase) + (voff)[_i]), (LAS unsigned*)(lds + (bufoff) + ldsw + _i * 8192), 16, 0, 0); } while (0)
; #define PG8_LDA(dst, b, h) do { _Pragma("unroll") for (int m = 0; m < 4; ++m) _Pragma("unroll") for (int k = 0; k < 2; ++k) dst[m][k] = *(const LAS bf16x8*)(lds + PG8_SA(b, h) + aoff + m * 2048 + k * 1024); } while (0)
; #define PG8_LDB(dst, b, h) do { _Pragma("unroll") for (int n = 0; n < 2; ++n) _Pragma("unroll") for (int k = 0; k < 2; ++k) dst[n][k] = *(const LAS bf16x8*)(lds + PG8_SB(b, h) + boff + n * 2048 + k * 1024); } while (0)
; #define PG8_MMA(ai, bj, At, Bt) do { __builtin_amdgcn_s_setprio(1); _Pragma("unroll") for (int m = 0; m < 4; ++m) _Pragma("unroll") for (int n = 0; n < 2; ++n) _Pragma("unroll") for (int k = 0; k < 2; ++k) \
;         acc[ai][bj][m][n] = __builtin_amdgcn_mfma_f32_16x16x32_bf16(Bt[n][k], At[m][k], acc[ai][bj][m][n], 0, 0, 0); __builtin_amdgcn_s_setprio(0); } while (0)
; #define PG8_WAIT_V(n) asm volatile("s_waitcnt vmcnt(" #n ")" ::: "memory")
; #define PG8_WAIT_L(n) asm volatile("s_waitcnt lgkmcnt(" #n ")" ::: "memory")
; #define PG8_BAR __builtin_amdgcn_s_barrier()
; #define PG8_SCHED __builtin_amdgcn_sched_barrier(0)
; template <class Epi, bool ALIGN_EPI = PG8_ALIGN, bool SP2 = PG8_SP2>
; __device__ __forceinline__ void gemm_phase(LAS unsigned char* lds, const Gemm g, const StaticOrder& S, const Epi& E) {
;     ...
;             const bool last = (t == nt - 2);
;             const char* a1 = cA + (size_t)(t + 1) * kstepA;
;             const char* a2 = last ? nA : cA + (size_t)(t + 2) * kstepA; const char* b2 = last ? nB : cB + (size_t)(t + 2) * kstepB;
;             const char* a3 = a2 + kstepA; const char* b3 = b2 + kstepB;
;             if constexpr (SP2) {
;             PG8_LDB(B0, 0, 0); PG8_LDB(B1, 0, 1); PG8_SCHED; PG8_LDA(At, 0, 0); PG8_STAGE(PG8_SA(1, 1), a1 + hstepA, voffA);
;             PG8_WAIT_V(8); PG8_WAIT_L(0); PG8_BAR; PG8_MMA(0, 0, At, B0); PG8_MMA(0, 1, At, B1); PG8_BAR; PG8_SCHED;
;             PG8_LDA(At, 0, 1); PG8_STAGE(PG8_SB(0, 0), b2, voffB); PG8_STAGE(PG8_SB(0, 1), b2 + hstepB, voffB); PG8_STAGE(PG8_SA(0, 0), a2, voffA);
;             PG8_WAIT_V(8); PG8_WAIT_L(0); PG8_BAR; PG8_MMA(1, 0, At, B0); PG8_MMA(1, 1, At, B1); PG8_BAR; PG8_SCHED;
.LBB0_583:
	s_cmp_eq_u32 s28, 0
	s_cbranch_scc1 .Lfirst_iter_u583
	s_add_u32 s74, s28, 1
	s_addc_u32 s75, s29, 0
	s_add_u32 s30, s28, 2
	s_addc_u32 s31, s29, 0
	s_lshl_b64 s[34:35], s[30:31], s56
	s_add_u32 s29, s26, s34
	s_addc_u32 s36, s27, s35
	s_add_u32 s34, s24, s34
	s_addc_u32 s35, s25, s35
	s_cmp_eq_u32 s66, s28
	s_cselect_b32 s37, s21, s36
	s_cselect_b32 s36, s20, s29
	s_cselect_b32 s34, s22, s34
	s_cselect_b32 s35, s23, s35
	s_add_u32 s28, s36, s52
	s_addc_u32 s29, s37, 0
	s_add_i32 s73, 0, 0x10000
	s_add_i32 s76, 0, 0x14000
	v_add_u32_e32 v144, s73, v155
	v_add_u32_e32 v152, s76, v155
	ds_read_b128 v[132:135], v144
	ds_read_b128 v[136:139], v144 offset:1024
	ds_read_b128 v[140:143], v144 offset:2048
	ds_read_b128 v[144:147], v144 offset:3072
	ds_read_b128 v[148:151], v152
	ds_read_b128 v[158:161], v152 offset:1024
	ds_read_b128 v[170:173], v152 offset:2048
	ds_read_b128 v[174:177], v152 offset:3072
	s_lshl_b64 s[74:75], s[74:75], s56
	s_add_u32 s74, s71, s74
	s_addc_u32 s75, s72, s75
	v_lshl_add_u64 v[152:153], s[74:75], 0, v[0:1]
	s_add_i32 m0, s41, 0xc000
	ds_read_b128 v[178:181], v157
	ds_read_b128 v[182:185], v157 offset:1024
	ds_read_b128 v[186:189], v157 offset:2048
	ds_read_b128 v[206:209], v157 offset:3072
	ds_read_b128 v[210:213], v157 offset:4096
	ds_read_b128 v[214:217], v157 offset:5120
	ds_read_b128 v[218:221], v157 offset:6144
	ds_read_b128 v[222:225], v157 offset:7168
	global_load_lds_dwordx4 v[152:153], off
	v_lshl_add_u64 v[152:153], s[74:75], 0, v[130:131]
	s_add_i32 m0, s41, 0xe000
	s_nop 0
	global_load_lds_dwordx4 v[152:153], off
	s_waitcnt vmcnt(8)
	s_waitcnt lgkmcnt(0)
	s_barrier
	s_setprio 1
	s_waitcnt lgkmcnt(0)
	v_mfma_f32_16x16x32_bf16 v[126:129], v[132:135], v[178:181], v[126:129]
	v_mfma_f32_16x16x32_bf16 v[122:125], v[140:143], v[178:181], v[122:125]
	v_mfma_f32_16x16x32_bf16 v[118:121], v[132:135], v[186:189], v[118:121]
	v_mfma_f32_16x16x32_bf16 v[114:117], v[140:143], v[186:189], v[114:117]
	v_mfma_f32_16x16x32_bf16 v[110:113], v[132:135], v[210:213], v[110:113]
	v_mfma_f32_16x16x32_bf16 v[90:93], v[140:143], v[210:213], v[90:93]
	v_mfma_f32_16x16x32_bf16 v[86:89], v[132:135], v[218:221], v[86:89]
	v_mfma_f32_16x16x32_bf16 v[78:81], v[140:143], v[218:221], v[78:81]
	s_setprio 0
	s_setprio 1
	v_mfma_f32_16x16x32_bf16 v[126:129], v[136:139], v[182:185], v[126:129]
	v_mfma_f32_16x16x32_bf16 v[122:125], v[144:147], v[182:185], v[122:125]
	v_mfma_f32_16x16x32_bf16 v[118:121], v[136:139], v[206:209], v[118:121]
	v_mfma_f32_16x16x32_bf16 v[114:117], v[144:147], v[206:209], v[114:117]
	v_mfma_f32_16x16x32_bf16 v[110:113], v[136:139], v[214:217], v[110:113]
	v_mfma_f32_16x16x32_bf16 v[90:93], v[144:147], v[214:217], v[90:93]
	v_mfma_f32_16x16x32_bf16 v[86:89], v[136:139], v[222:225], v[86:89]
	v_mfma_f32_16x16x32_bf16 v[78:81], v[144:147], v[222:225], v[78:81]
	s_setprio 0
	s_setprio 1
	v_mfma_f32_16x16x32_bf16 v[106:109], v[148:151], v[178:181], v[106:109]
	v_mfma_f32_16x16x32_bf16 v[102:105], v[170:173], v[178:181], v[102:105]
	v_mfma_f32_16x16x32_bf16 v[98:101], v[148:151], v[186:189], v[98:101]
	v_mfma_f32_16x16x32_bf16 v[94:97], v[170:173], v[186:189], v[94:97]
	v_mfma_f32_16x16x32_bf16 v[82:85], v[148:151], v[210:213], v[82:85]
	v_mfma_f32_16x16x32_bf16 v[74:77], v[170:173], v[210:213], v[74:77]
	v_mfma_f32_16x16x32_bf16 v[70:73], v[148:151], v[218:221], v[70:73]
	v_mfma_f32_16x16x32_bf16 v[66:69], v[170:173], v[218:221], v[66:69]
	s_setprio 0
	s_setprio 1
	v_mfma_f32_16x16x32_bf16 v[106:109], v[158:161], v[182:185], v[106:109]
	v_mfma_f32_16x16x32_bf16 v[102:105], v[174:177], v[182:185], v[102:105]
	v_mfma_f32_16x16x32_bf16 v[98:101], v[158:161], v[206:209], v[98:101]
	v_mfma_f32_16x16x32_bf16 v[94:97], v[174:177], v[206:209], v[94:97]
	v_mfma_f32_16x16x32_bf16 v[82:85], v[158:161], v[214:217], v[82:85]
	v_mfma_f32_16x16x32_bf16 v[74:77], v[174:177], v[214:217], v[74:77]
	v_mfma_f32_16x16x32_bf16 v[70:73], v[158:161], v[222:225], v[70:73]
	v_mfma_f32_16x16x32_bf16 v[66:69], v[174:177], v[222:225], v[66:69]
	s_setprio 0
	s_barrier
	s_add_i32 s73, s73, s40
	v_lshl_add_u64 v[152:153], s[34:35], 0, v[0:1]
	s_mov_b32 m0, s73
	ds_read_b128 v[178:181], v157 offset:16384
	ds_read_b128 v[182:185], v157 offset:17408
	ds_read_b128 v[186:189], v157 offset:18432
	ds_read_b128 v[206:209], v157 offset:19456
	ds_read_b128 v[210:213], v157 offset:20480
	ds_read_b128 v[214:217], v157 offset:21504
	ds_read_b128 v[218:221], v157 offset:22528
	ds_read_b128 v[222:225], v157 offset:23552
	global_load_lds_dwordx4 v[152:153], off
	s_add_i32 m0, s73, 0x2000
	s_add_u32 s74, s34, s38
	v_lshl_add_u64 v[152:153], s[34:35], 0, v[130:131]
	s_addc_u32 s75, s35, s33
	s_add_i32 s73, s76, s40
	global_load_lds_dwordx4 v[152:153], off
	v_lshl_add_u64 v[152:153], s[74:75], 0, v[0:1]
	s_mov_b32 m0, s73
	s_nop 0
	global_load_lds_dwordx4 v[152:153], off
	v_lshl_add_u64 v[152:153], s[74:75], 0, v[130:131]
	s_add_i32 m0, s73, 0x2000
	s_nop 0
	global_load_lds_dwordx4 v[152:153], off
	v_lshl_add_u64 v[152:153], s[36:37], 0, v[0:1]
	s_mov_b32 m0, s41
	s_nop 0
	global_load_lds_dwordx4 v[152:153], off
	v_lshl_add_u64 v[152:153], s[36:37], 0, v[130:131]
	s_mov_b32 m0, s42
	s_nop 0
	global_load_lds_dwordx4 v[152:153], off
	s_waitcnt vmcnt(8)
	s_waitcnt lgkmcnt(0)
	s_barrier
; #define PG8_STAGE(bufoff, gbase, voff) do { _Pragma("unroll") for (int _i = 0; _i < 2; ++_i) \
;         __builtin_amdgcn_global_load_lds((const unsigned*)((const char*)(gbase) + (voff)[_i]), (LAS unsigned*)(lds + (bufoff) + ldsw + _i * 8192), 16, 0, 0); } while (0)
; #define PG8_LDA(dst, b, h) do { _Pragma("unroll") for (int m = 0; m < 4; ++m) _Pragma("unroll") for (int k = 0; k < 2; ++k) dst[m][k] = *(const LAS bf16x8*)(lds + PG8_SA(b, h) + aoff + m * 2048 + k * 1024); } while (0)
; #define PG8_LDB(dst, b, h) do { _Pragma("unroll") for (int n = 0; n < 2; ++n) _Pragma("unroll") for (int k = 0; k < 2; ++k) dst[n][k] = *(const LAS bf16x8*)(lds + PG8_SB(b, h) + boff + n * 2048 + k * 1024); } while (0)
; #define PG8_MMA(ai, bj, At, Bt) do { __builtin_amdgcn_s_setprio(1); _Pragma("unroll") for (int m = 0; m < 4; ++m) _Pragma("unroll") for (int n = 0; n < 2; ++n) _Pragma("unroll") for (int k = 0; k < 2; ++k) \
;         acc[ai][bj][m][n] = __builtin_amdgcn_mfma_f32_16x16x32_bf16(Bt[n][k], At[m][k], acc[ai][bj][m][n], 0, 0, 0); __builtin_amdgcn_s_setprio(0); } while (0)
; #define PG8_WAIT_V(n) asm volatile("s_waitcnt vmcnt(" #n ")" ::: "memory")
; #define PG8_WAIT_L(n) asm volatile("s_waitcnt lgkmcnt(" #n ")" ::: "memory")
; #define PG8_BAR __builtin_amdgcn_s_barrier()
; #define PG8_SCHED __builtin_amdgcn_sched_barrier(0)
; template <class Epi, bool ALIGN_EPI = PG8_ALIGN, bool SP2 = PG8_SP2>
; __device__ __forceinline__ void gemm_phase(LAS unsigned char* lds, const Gemm g, const StaticOrder& S, const Epi& E) {
;     ...
;             PG8_WAIT_V(8); PG8_WAIT_L(0); PG8_BAR; PG8_MMA(1, 0, At, B0); PG8_MMA(1, 1, At, B1); PG8_BAR; PG8_SCHED;
;             PG8_LDB(B0, 1, 0); PG8_LDB(B1, 1, 1); PG8_SCHED; PG8_LDA(At, 1, 0); PG8_STAGE(PG8_SA(0, 1), a2 + hstepA, voffA);
;             PG8_WAIT_V(8); PG8_WAIT_L(0); PG8_BAR; PG8_MMA(0, 0, At, B0); PG8_MMA(0, 1, At, B1); PG8_BAR; PG8_SCHED;
	s_setprio 1
	s_waitcnt lgkmcnt(0)
	v_mfma_f32_16x16x32_bf16 v[62:65], v[132:135], v[178:181], v[62:65]
	v_mfma_f32_16x16x32_bf16 v[58:61], v[140:143], v[178:181], v[58:61]
	v_mfma_f32_16x16x32_bf16 v[54:57], v[132:135], v[186:189], v[54:57]
	v_mfma_f32_16x16x32_bf16 v[50:53], v[140:143], v[186:189], v[50:53]
	v_mfma_f32_16x16x32_bf16 v[46:49], v[132:135], v[210:213], v[46:49]
	v_mfma_f32_16x16x32_bf16 v[34:37], v[140:143], v[210:213], v[34:37]
	v_mfma_f32_16x16x32_bf16 v[18:21], v[132:135], v[218:221], v[18:21]
	v_mfma_f32_16x16x32_bf16 v[14:17], v[140:143], v[218:221], v[14:17]
	s_setprio 0
	s_setprio 1
	v_mfma_f32_16x16x32_bf16 v[62:65], v[136:139], v[182:185], v[62:65]
	v_mfma_f32_16x16x32_bf16 v[58:61], v[144:147], v[182:185], v[58:61]
	v_mfma_f32_16x16x32_bf16 v[54:57], v[136:139], v[206:209], v[54:57]
	v_mfma_f32_16x16x32_bf16 v[50:53], v[144:147], v[206:209], v[50:53]
	v_mfma_f32_16x16x32_bf16 v[46:49], v[136:139], v[214:217], v[46:49]
	v_mfma_f32_16x16x32_bf16 v[34:37], v[144:147], v[214:217], v[34:37]
	v_mfma_f32_16x16x32_bf16 v[18:21], v[136:139], v[222:225], v[18:21]
	v_mfma_f32_16x16x32_bf16 v[14:17], v[144:147], v[222:225], v[14:17]
	s_setprio 0
	s_setprio 1
	v_mfma_f32_16x16x32_bf16 v[42:45], v[148:151], v[178:181], v[42:45]
	v_mfma_f32_16x16x32_bf16 v[38:41], v[170:173], v[178:181], v[38:41]
	v_mfma_f32_16x16x32_bf16 v[30:33], v[148:151], v[186:189], v[30:33]
	v_mfma_f32_16x16x32_bf16 v[26:29], v[170:173], v[186:189], v[26:29]
	v_mfma_f32_16x16x32_bf16 v[22:25], v[148:151], v[210:213], v[22:25]
	v_mfma_f32_16x16x32_bf16 v[10:13], v[170:173], v[210:213], v[10:13]
	v_mfma_f32_16x16x32_bf16 v[6:9], v[148:151], v[218:221], v[6:9]
	v_mfma_f32_16x16x32_bf16 v[2:5], v[170:173], v[218:221], v[2:5]
	s_setprio 0
	s_setprio 1
	v_mfma_f32_16x16x32_bf16 v[42:45], v[158:161], v[182:185], v[42:45]
	v_mfma_f32_16x16x32_bf16 v[38:41], v[174:177], v[182:185], v[38:41]
	v_mfma_f32_16x16x32_bf16 v[30:33], v[158:161], v[206:209], v[30:33]
	v_mfma_f32_16x16x32_bf16 v[26:29], v[174:177], v[206:209], v[26:29]
	v_mfma_f32_16x16x32_bf16 v[22:25], v[158:161], v[214:217], v[22:25]
	v_mfma_f32_16x16x32_bf16 v[10:13], v[174:177], v[214:217], v[10:13]
	v_mfma_f32_16x16x32_bf16 v[6:9], v[158:161], v[222:225], v[6:9]
	v_mfma_f32_16x16x32_bf16 v[2:5], v[174:177], v[222:225], v[2:5]
	s_setprio 0
	s_barrier
	s_add_i32 s73, 0, 0x18000
	s_add_i32 s74, 0, 0x1c000
	v_add_u32_e32 v144, s73, v155
	v_add_u32_e32 v152, s74, v155
	ds_read_b128 v[132:135], v144
	ds_read_b128 v[136:139], v144 offset:1024
	ds_read_b128 v[140:143], v144 offset:2048
	ds_read_b128 v[144:147], v144 offset:3072
	ds_read_b128 v[148:151], v152
	ds_read_b128 v[158:161], v152 offset:1024
	ds_read_b128 v[170:173], v152 offset:2048
	ds_read_b128 v[174:177], v152 offset:3072
	s_add_u32 s36, s36, s38
	s_addc_u32 s37, s37, s33
	s_mov_b32 m0, s43
	v_lshl_add_u64 v[152:153], s[36:37], 0, v[0:1]
	ds_read_b128 v[178:181], v157 offset:32768
	ds_read_b128 v[182:185], v157 offset:33792
	ds_read_b128 v[186:189], v157 offset:34816
	ds_read_b128 v[206:209], v157 offset:35840
	ds_read_b128 v[210:213], v157 offset:36864
	ds_read_b128 v[214:217], v157 offset:37888
	ds_read_b128 v[218:221], v157 offset:38912
	ds_read_b128 v[222:225], v157 offset:39936
	global_load_lds_dwordx4 v[152:153], off
	v_lshl_add_u64 v[152:153], s[36:37], 0, v[130:131]
	s_mov_b32 m0, s44
	s_nop 0
	global_load_lds_dwordx4 v[152:153], off
	s_waitcnt vmcnt(8)
	s_waitcnt lgkmcnt(0)
	s_barrier
	s_setprio 1
	s_waitcnt lgkmcnt(0)
	v_mfma_f32_16x16x32_bf16 v[126:129], v[132:135], v[178:181], v[126:129]
	v_mfma_f32_16x16x32_bf16 v[122:125], v[140:143], v[178:181], v[122:125]
	v_mfma_f32_16x16x32_bf16 v[118:121], v[132:135], v[186:189], v[118:121]
	v_mfma_f32_16x16x32_bf16 v[114:117], v[140:143], v[186:189], v[114:117]
	v_mfma_f32_16x16x32_bf16 v[110:113], v[132:135], v[210:213], v[110:113]
	v_mfma_f32_16x16x32_bf16 v[90:93], v[140:143], v[210:213], v[90:93]
	v_mfma_f32_16x16x32_bf16 v[86:89], v[132:135], v[218:221], v[86:89]
	v_mfma_f32_16x16x32_bf16 v[78:81], v[140:143], v[218:221], v[78:81]
	s_setprio 0
	s_setprio 1
	v_mfma_f32_16x16x32_bf16 v[126:129], v[136:139], v[182:185], v[126:129]
	v_mfma_f32_16x16x32_bf16 v[122:125], v[144:147], v[182:185], v[122:125]
	v_mfma_f32_16x16x32_bf16 v[118:121], v[136:139], v[206:209], v[118:121]
	v_mfma_f32_16x16x32_bf16 v[114:117], v[144:147], v[206:209], v[114:117]
	v_mfma_f32_16x16x32_bf16 v[110:113], v[136:139], v[214:217], v[110:113]
	v_mfma_f32_16x16x32_bf16 v[90:93], v[144:147], v[214:217], v[90:93]
	v_mfma_f32_16x16x32_bf16 v[86:89], v[136:139], v[222:225], v[86:89]
	v_mfma_f32_16x16x32_bf16 v[78:81], v[144:147], v[222:225], v[78:81]
	s_setprio 0
	s_setprio 1
	v_mfma_f32_16x16x32_bf16 v[106:109], v[148:151], v[178:181], v[106:109]
	v_mfma_f32_16x16x32_bf16 v[102:105], v[170:173], v[178:181], v[102:105]
	v_mfma_f32_16x16x32_bf16 v[98:101], v[148:151], v[186:189], v[98:101]
	v_mfma_f32_16x16x32_bf16 v[94:97], v[170:173], v[186:189], v[94:97]
	v_mfma_f32_16x16x32_bf16 v[82:85], v[148:151], v[210:213], v[82:85]
	v_mfma_f32_16x16x32_bf16 v[74:77], v[170:173], v[210:213], v[74:77]
	v_mfma_f32_16x16x32_bf16 v[70:73], v[148:151], v[218:221], v[70:73]
	v_mfma_f32_16x16x32_bf16 v[66:69], v[170:173], v[218:221], v[66:69]
	s_setprio 0
	s_setprio 1
	v_mfma_f32_16x16x32_bf16 v[106:109], v[158:161], v[182:185], v[106:109]
	v_mfma_f32_16x16x32_bf16 v[102:105], v[174:177], v[182:185], v[102:105]
	v_mfma_f32_16x16x32_bf16 v[98:101], v[158:161], v[206:209], v[98:101]
	v_mfma_f32_16x16x32_bf16 v[94:97], v[174:177], v[206:209], v[94:97]
	v_mfma_f32_16x16x32_bf16 v[82:85], v[158:161], v[214:217], v[82:85]
	v_mfma_f32_16x16x32_bf16 v[74:77], v[174:177], v[214:217], v[74:77]
	v_mfma_f32_16x16x32_bf16 v[70:73], v[158:161], v[222:225], v[70:73]
	v_mfma_f32_16x16x32_bf16 v[66:69], v[174:177], v[222:225], v[66:69]
	s_setprio 0
	s_barrier
; #define PG8_STAGE(bufoff, gbase, voff) do { _Pragma("unroll") for (int _i = 0; _i < 2; ++_i) \
;         __builtin_amdgcn_global_load_lds((const unsigned*)((const char*)(gbase) + (voff)[_i]), (LAS unsigned*)(lds + (bufoff) + ldsw + _i * 8192), 16, 0, 0); } while (0)
; #define PG8_LDA(dst, b, h) do { _Pragma("unroll") for (int m = 0; m < 4; ++m) _Pragma("unroll") for (int k = 0; k < 2; ++k) dst[m][k] = *(const LAS bf16x8*)(lds + PG8_SA(b, h) + aoff + m * 2048 + k * 1024); } while (0)
; #define PG8_MMA(ai, bj, At, Bt) do { __builtin_amdgcn_s_setprio(1); _Pragma("unroll") for (int m = 0; m < 4; ++m) _Pragma("unroll") for (int n = 0; n < 2; ++n) _Pragma("unroll") for (int k = 0; k < 2; ++k) \
;         acc[ai][bj][m][n] = __builtin_amdgcn_mfma_f32_16x16x32_bf16(Bt[n][k], At[m][k], acc[ai][bj][m][n], 0, 0, 0); __builtin_amdgcn_s_setprio(0); } while (0)
; #define PG8_WAIT_V(n) asm volatile("s_waitcnt vmcnt(" #n ")" ::: "memory")
; #define PG8_WAIT_L(n) asm volatile("s_waitcnt lgkmcnt(" #n ")" ::: "memory")
; #define PG8_BAR __builtin_amdgcn_s_barrier()
; #define PG8_SCHED __builtin_amdgcn_sched_barrier(0)
; template <class Epi, bool ALIGN_EPI = PG8_ALIGN, bool SP2 = PG8_SP2>
; __device__ __forceinline__ void gemm_phase(LAS unsigned char* lds, const Gemm g, const StaticOrder& S, const Epi& E) {
;     ...
;             PG8_LDA(At, 1, 1); PG8_STAGE(PG8_SB(1, 0), b3, voffB); PG8_STAGE(PG8_SB(1, 1), b3 + hstepB, voffB); PG8_STAGE(PG8_SA(1, 0), a3, voffA);
;             PG8_WAIT_V(8); PG8_WAIT_L(0); PG8_BAR; PG8_MMA(1, 0, At, B0); PG8_MMA(1, 1, At, B1); PG8_BAR; PG8_SCHED;
	s_add_u32 s34, s34, s52
	s_addc_u32 s35, s35, 0
	s_add_i32 s36, s73, s40
	v_lshl_add_u64 v[152:153], s[34:35], 0, v[0:1]
	s_mov_b32 m0, s36
	ds_read_b128 v[178:181], v157 offset:49152
	ds_read_b128 v[182:185], v157 offset:50176
	ds_read_b128 v[186:189], v157 offset:51200
	ds_read_b128 v[206:209], v157 offset:52224
	ds_read_b128 v[210:213], v157 offset:53248
	ds_read_b128 v[214:217], v157 offset:54272
	ds_read_b128 v[218:221], v157 offset:55296
	ds_read_b128 v[222:225], v157 offset:56320
	global_load_lds_dwordx4 v[152:153], off
	s_add_i32 m0, s36, 0x2000
	v_lshl_add_u64 v[152:153], s[34:35], 0, v[130:131]
	s_add_u32 s34, s34, s38
	s_addc_u32 s35, s35, s33
	s_add_i32 s36, s74, s40
	global_load_lds_dwordx4 v[152:153], off
	v_lshl_add_u64 v[152:153], s[34:35], 0, v[0:1]
	s_mov_b32 m0, s36
	s_nop 0
	global_load_lds_dwordx4 v[152:153], off
	v_lshl_add_u64 v[152:153], s[34:35], 0, v[130:131]
	s_add_i32 m0, s36, 0x2000
	s_nop 0
	global_load_lds_dwordx4 v[152:153], off
	v_lshl_add_u64 v[152:153], s[28:29], 0, v[0:1]
	s_mov_b32 m0, s53
	s_nop 0
	global_load_lds_dwordx4 v[152:153], off
	v_lshl_add_u64 v[152:153], s[28:29], 0, v[130:131]
	s_mov_b32 m0, s54
	s_nop 0
	global_load_lds_dwordx4 v[152:153], off
	s_waitcnt vmcnt(8)
	s_waitcnt lgkmcnt(0)
	s_barrier
	s_setprio 1
	s_waitcnt lgkmcnt(0)
	v_mfma_f32_16x16x32_bf16 v[62:65], v[132:135], v[178:181], v[62:65]
	v_mfma_f32_16x16x32_bf16 v[58:61], v[140:143], v[178:181], v[58:61]
	v_mfma_f32_16x16x32_bf16 v[54:57], v[132:135], v[186:189], v[54:57]
	v_mfma_f32_16x16x32_bf16 v[50:53], v[140:143], v[186:189], v[50:53]
	v_mfma_f32_16x16x32_bf16 v[46:49], v[132:135], v[210:213], v[46:49]
	v_mfma_f32_16x16x32_bf16 v[34:37], v[140:143], v[210:213], v[34:37]
	v_mfma_f32_16x16x32_bf16 v[18:21], v[132:135], v[218:221], v[18:21]
	v_mfma_f32_16x16x32_bf16 v[14:17], v[140:143], v[218:221], v[14:17]
	s_setprio 0
	s_setprio 1
	v_mfma_f32_16x16x32_bf16 v[62:65], v[136:139], v[182:185], v[62:65]
	v_mfma_f32_16x16x32_bf16 v[58:61], v[144:147], v[182:185], v[58:61]
	v_mfma_f32_16x16x32_bf16 v[54:57], v[136:139], v[206:209], v[54:57]
	v_mfma_f32_16x16x32_bf16 v[50:53], v[144:147], v[206:209], v[50:53]
	v_mfma_f32_16x16x32_bf16 v[46:49], v[136:139], v[214:217], v[46:49]
	v_mfma_f32_16x16x32_bf16 v[34:37], v[144:147], v[214:217], v[34:37]
	v_mfma_f32_16x16x32_bf16 v[18:21], v[136:139], v[222:225], v[18:21]
	v_mfma_f32_16x16x32_bf16 v[14:17], v[144:147], v[222:225], v[14:17]
	s_setprio 0
	s_setprio 1
	v_mfma_f32_16x16x32_bf16 v[42:45], v[148:151], v[178:181], v[42:45]
	v_mfma_f32_16x16x32_bf16 v[38:41], v[170:173], v[178:181], v[38:41]
	v_mfma_f32_16x16x32_bf16 v[30:33], v[148:151], v[186:189], v[30:33]
	v_mfma_f32_16x16x32_bf16 v[26:29], v[170:173], v[186:189], v[26:29]
	v_mfma_f32_16x16x32_bf16 v[22:25], v[148:151], v[210:213], v[22:25]
	v_mfma_f32_16x16x32_bf16 v[10:13], v[170:173], v[210:213], v[10:13]
	v_mfma_f32_16x16x32_bf16 v[6:9], v[148:151], v[218:221], v[6:9]
	v_mfma_f32_16x16x32_bf16 v[2:5], v[170:173], v[218:221], v[2:5]
	s_setprio 0
	s_setprio 1
	v_mfma_f32_16x16x32_bf16 v[42:45], v[158:161], v[182:185], v[42:45]
	v_mfma_f32_16x16x32_bf16 v[38:41], v[174:177], v[182:185], v[38:41]
	v_mfma_f32_16x16x32_bf16 v[30:33], v[158:161], v[206:209], v[30:33]
	v_mfma_f32_16x16x32_bf16 v[26:29], v[174:177], v[206:209], v[26:29]
	v_mfma_f32_16x16x32_bf16 v[22:25], v[158:161], v[214:217], v[22:25]
	v_mfma_f32_16x16x32_bf16 v[10:13], v[174:177], v[214:217], v[10:13]
	v_mfma_f32_16x16x32_bf16 v[6:9], v[158:161], v[222:225], v[6:9]
	v_mfma_f32_16x16x32_bf16 v[2:5], v[174:177], v[222:225], v[2:5]
	s_setprio 0
	s_barrier
	s_cmp_ge_u32 s30, s49
	s_mov_b64 s[28:29], s[30:31]
	s_cbranch_scc0 .LBB0_583
	s_and_b64 vcc, exec, s[18:19]
	s_cbranch_vccz .LBB0_586
	s_barrier

; #define PG8_STAGE(bufoff, gbase, voff) do { _Pragma("unroll") for (int _i = 0; _i < 2; ++_i) \
;         __builtin_amdgcn_global_load_lds((const unsigned*)((const char*)(gbase) + (voff)[_i]), (LAS unsigned*)(lds + (bufoff) + ldsw + _i * 8192), 16, 0, 0); } while (0)
; #define PG8_LDA(dst, b, h) do { _Pragma("unroll") for (int m = 0; m < 4; ++m) _Pragma("unroll") for (int k = 0; k < 2; ++k) dst[m][k] = *(const LAS bf16x8*)(lds + PG8_SA(b, h) + aoff + m * 2048 + k * 1024); } while (0)
; #define PG8_LDB(dst, b, h) do { _Pragma("unroll") for (int n = 0; n < 2; ++n) _Pragma("unroll") for (int k = 0; k < 2; ++k) dst[n][k] = *(const LAS bf16x8*)(lds + PG8_SB(b, h) + boff + n * 2048 + k * 1024); } while (0)
; #define PG8_MMA(ai, bj, At, Bt) do { __builtin_amdgcn_s_setprio(1); _Pragma("unroll") for (int m = 0; m < 4; ++m) _Pragma("unroll") for (int n = 0; n < 2; ++n) _Pragma("unroll") for (int k = 0; k < 2; ++k) \
;         acc[ai][bj][m][n] = __builtin_amdgcn_mfma_f32_16x16x32_bf16(Bt[n][k], At[m][k], acc[ai][bj][m][n], 0, 0, 0); __builtin_amdgcn_s_setprio(0); } while (0)
; #define PG8_WAIT_V(n) asm volatile("s_waitcnt vmcnt(" #n ")" ::: "memory")
; #define PG8_WAIT_L(n) asm volatile("s_waitcnt lgkmcnt(" #n ")" ::: "memory")
; #define PG8_BAR __builtin_amdgcn_s_barrier()
; #define PG8_SCHED __builtin_amdgcn_sched_barrier(0)
; template <class Epi, bool ALIGN_EPI = PG8_ALIGN, bool SP2 = PG8_SP2>
; __device__ __forceinline__ void gemm_phase(LAS unsigned char* lds, const Gemm g, const StaticOrder& S, const Epi& E) {
;     ...
;             const bool last = (t == nt - 2);
;             const char* a1 = cA + (size_t)(t + 1) * kstepA;
;             const char* a2 = last ? nA : cA + (size_t)(t + 2) * kstepA; const char* b2 = last ? nB : cB + (size_t)(t + 2) * kstepB;
;             const char* a3 = a2 + kstepA; const char* b3 = b2 + kstepB;
;             if constexpr (SP2) {
;             PG8_LDB(B0, 0, 0); PG8_LDB(B1, 0, 1); PG8_SCHED; PG8_LDA(At, 0, 0); PG8_STAGE(PG8_SA(1, 1), a1 + hstepA, voffA);
;             PG8_WAIT_V(8); PG8_WAIT_L(0); PG8_BAR; PG8_MMA(0, 0, At, B0); PG8_MMA(0, 1, At, B1); PG8_BAR; PG8_SCHED;
;             PG8_LDA(At, 0, 1); PG8_STAGE(PG8_SB(0, 0), b2, voffB); PG8_STAGE(PG8_SB(0, 1), b2 + hstepB, voffB); PG8_STAGE(PG8_SA(0, 0), a2, voffA);
;             PG8_WAIT_V(8); PG8_WAIT_L(0); PG8_BAR; PG8_MMA(1, 0, At, B0); PG8_MMA(1, 1, At, B1); PG8_BAR; PG8_SCHED;
.Lfirst_iter_u583:
	s_add_u32 s74, s28, 1
	s_addc_u32 s75, s29, 0
	s_add_u32 s30, s28, 2
	s_addc_u32 s31, s29, 0
	s_lshl_b64 s[34:35], s[30:31], s56
	s_add_u32 s29, s26, s34
	s_addc_u32 s36, s27, s35
	s_add_u32 s34, s24, s34
	s_addc_u32 s35, s25, s35
	s_cmp_eq_u32 s66, s28
	s_cselect_b32 s37, s21, s36
	s_cselect_b32 s36, s20, s29
	s_cselect_b32 s34, s22, s34
	s_cselect_b32 s35, s23, s35
	s_add_u32 s28, s36, s52
	s_addc_u32 s29, s37, 0
	s_add_i32 s73, 0, 0x10000
	s_add_i32 s76, 0, 0x14000
	v_add_u32_e32 v144, s73, v155
	v_add_u32_e32 v152, s76, v155
	ds_read_b128 v[132:135], v144
	ds_read_b128 v[136:139], v144 offset:1024
	ds_read_b128 v[140:143], v144 offset:2048
	ds_read_b128 v[144:147], v144 offset:3072
	ds_read_b128 v[148:151], v152
	ds_read_b128 v[158:161], v152 offset:1024
	ds_read_b128 v[170:173], v152 offset:2048
	ds_read_b128 v[174:177], v152 offset:3072
	s_lshl_b64 s[74:75], s[74:75], s56
	s_add_u32 s74, s71, s74
	s_addc_u32 s75, s72, s75
	v_lshl_add_u64 v[152:153], s[74:75], 0, v[0:1]
	s_add_i32 m0, s41, 0xc000
	ds_read_b128 v[178:181], v157
	ds_read_b128 v[182:185], v157 offset:1024
	ds_read_b128 v[186:189], v157 offset:2048
	ds_read_b128 v[206:209], v157 offset:3072
	ds_read_b128 v[210:213], v157 offset:4096
	ds_read_b128 v[214:217], v157 offset:5120
	ds_read_b128 v[218:221], v157 offset:6144
	ds_read_b128 v[222:225], v157 offset:7168
	global_load_lds_dwordx4 v[152:153], off
	v_lshl_add_u64 v[152:153], s[74:75], 0, v[130:131]
	s_add_i32 m0, s41, 0xe000
	s_nop 0
	global_load_lds_dwordx4 v[152:153], off
	s_waitcnt vmcnt(8)
	s_waitcnt lgkmcnt(0)
	s_barrier
	s_setprio 1
	s_waitcnt lgkmcnt(0)
	v_mfma_f32_16x16x32_bf16 v[126:129], v[132:135], v[178:181], 0
	v_mfma_f32_16x16x32_bf16 v[122:125], v[140:143], v[178:181], 0
	v_mfma_f32_16x16x32_bf16 v[118:121], v[132:135], v[186:189], 0
	v_mfma_f32_16x16x32_bf16 v[114:117], v[140:143], v[186:189], 0
	v_mfma_f32_16x16x32_bf16 v[110:113], v[132:135], v[210:213], 0
	v_mfma_f32_16x16x32_bf16 v[90:93], v[140:143], v[210:213], 0
	v_mfma_f32_16x16x32_bf16 v[86:89], v[132:135], v[218:221], 0
	v_mfma_f32_16x16x32_bf16 v[78:81], v[140:143], v[218:221], 0
	s_setprio 0
	s_setprio 1
	v_mfma_f32_16x16x32_bf16 v[126:129], v[136:139], v[182:185], v[126:129]
	v_mfma_f32_16x16x32_bf16 v[122:125], v[144:147], v[182:185], v[122:125]
	v_mfma_f32_16x16x32_bf16 v[118:121], v[136:139], v[206:209], v[118:121]
	v_mfma_f32_16x16x32_bf16 v[114:117], v[144:147], v[206:209], v[114:117]
	v_mfma_f32_16x16x32_bf16 v[110:113], v[136:139], v[214:217], v[110:113]
	v_mfma_f32_16x16x32_bf16 v[90:93], v[144:147], v[214:217], v[90:93]
	v_mfma_f32_16x16x32_bf16 v[86:89], v[136:139], v[222:225], v[86:89]
	v_mfma_f32_16x16x32_bf16 v[78:81], v[144:147], v[222:225], v[78:81]
	s_setprio 0
	s_setprio 1
	v_mfma_f32_16x16x32_bf16 v[106:109], v[148:151], v[178:181], 0
	v_mfma_f32_16x16x32_bf16 v[102:105], v[170:173], v[178:181], 0
	v_mfma_f32_16x16x32_bf16 v[98:101], v[148:151], v[186:189], 0
	v_mfma_f32_16x16x32_bf16 v[94:97], v[170:173], v[186:189], 0
	v_mfma_f32_16x16x32_bf16 v[82:85], v[148:151], v[210:213], 0
	v_mfma_f32_16x16x32_bf16 v[74:77], v[170:173], v[210:213], 0
	v_mfma_f32_16x16x32_bf16 v[70:73], v[148:151], v[218:221], 0
	v_mfma_f32_16x16x32_bf16 v[66:69], v[170:173], v[218:221], 0
	s_setprio 0
	s_setprio 1
	v_mfma_f32_16x16x32_bf16 v[106:109], v[158:161], v[182:185], v[106:109]
	v_mfma_f32_16x16x32_bf16 v[102:105], v[174:177], v[182:185], v[102:105]
	v_mfma_f32_16x16x32_bf16 v[98:101], v[158:161], v[206:209], v[98:101]
	v_mfma_f32_16x16x32_bf16 v[94:97], v[174:177], v[206:209], v[94:97]
	v_mfma_f32_16x16x32_bf16 v[82:85], v[158:161], v[214:217], v[82:85]
	v_mfma_f32_16x16x32_bf16 v[74:77], v[174:177], v[214:217], v[74:77]
	v_mfma_f32_16x16x32_bf16 v[70:73], v[158:161], v[222:225], v[70:73]
	v_mfma_f32_16x16x32_bf16 v[66:69], v[174:177], v[222:225], v[66:69]
	s_setprio 0
	s_barrier
	s_add_i32 s73, s73, s40
	v_lshl_add_u64 v[152:153], s[34:35], 0, v[0:1]
	s_mov_b32 m0, s73
	ds_read_b128 v[178:181], v157 offset:16384
	ds_read_b128 v[182:185], v157 offset:17408
	ds_read_b128 v[186:189], v157 offset:18432
	ds_read_b128 v[206:209], v157 offset:19456
	ds_read_b128 v[210:213], v157 offset:20480
	ds_read_b128 v[214:217], v157 offset:21504
	ds_read_b128 v[218:221], v157 offset:22528
	ds_read_b128 v[222:225], v157 offset:23552
	global_load_lds_dwordx4 v[152:153], off
	s_add_i32 m0, s73, 0x2000
	s_add_u32 s74, s34, s38
	v_lshl_add_u64 v[152:153], s[34:35], 0, v[130:131]
	s_addc_u32 s75, s35, s33
	s_add_i32 s73, s76, s40
	global_load_lds_dwordx4 v[152:153], off
	v_lshl_add_u64 v[152:153], s[74:75], 0, v[0:1]
	s_mov_b32 m0, s73
	s_nop 0
	global_load_lds_dwordx4 v[152:153], off
	v_lshl_add_u64 v[152:153], s[74:75], 0, v[130:131]
	s_add_i32 m0, s73, 0x2000
	s_nop 0
	global_load_lds_dwordx4 v[152:153], off
	v_lshl_add_u64 v[152:153], s[36:37], 0, v[0:1]
	s_mov_b32 m0, s41
	s_nop 0
	global_load_lds_dwordx4 v[152:153], off
	v_lshl_add_u64 v[152:153], s[36:37], 0, v[130:131]
	s_mov_b32 m0, s42
	s_nop 0
	global_load_lds_dwordx4 v[152:153], off
	s_waitcnt vmcnt(8)
	s_waitcnt lgkmcnt(0)
	s_barrier
; #define PG8_STAGE(bufoff, gbase, voff) do { _Pragma("unroll") for (int _i = 0; _i < 2; ++_i) \
;         __builtin_amdgcn_global_load_lds((const unsigned*)((const char*)(gbase) + (voff)[_i]), (LAS unsigned*)(lds + (bufoff) + ldsw + _i * 8192), 16, 0, 0); } while (0)
; #define PG8_LDA(dst, b, h) do { _Pragma("unroll") for (int m = 0; m < 4; ++m) _Pragma("unroll") for (int k = 0; k < 2; ++k) dst[m][k] = *(const LAS bf16x8*)(lds + PG8_SA(b, h) + aoff + m * 2048 + k * 1024); } while (0)
; #define PG8_LDB(dst, b, h) do { _Pragma("unroll") for (int n = 0; n < 2; ++n) _Pragma("unroll") for (int k = 0; k < 2; ++k) dst[n][k] = *(const LAS bf16x8*)(lds + PG8_SB(b, h) + boff + n * 2048 + k * 1024); } while (0)
; #define PG8_MMA(ai, bj, At, Bt) do { __builtin_amdgcn_s_setprio(1); _Pragma("unroll") for (int m = 0; m < 4; ++m) _Pragma("unroll") for (int n = 0; n < 2; ++n) _Pragma("unroll") for (int k = 0; k < 2; ++k) \
;         acc[ai][bj][m][n] = __builtin_amdgcn_mfma_f32_16x16x32_bf16(Bt[n][k], At[m][k], acc[ai][bj][m][n], 0, 0, 0); __builtin_amdgcn_s_setprio(0); } while (0)
; #define PG8_WAIT_V(n) asm volatile("s_waitcnt vmcnt(" #n ")" ::: "memory")
; #define PG8_WAIT_L(n) asm volatile("s_waitcnt lgkmcnt(" #n ")" ::: "memory")
; #define PG8_BAR __builtin_amdgcn_s_barrier()
; #define PG8_SCHED __builtin_amdgcn_sched_barrier(0)
; template <class Epi, bool ALIGN_EPI = PG8_ALIGN, bool SP2 = PG8_SP2>
; __device__ __forceinline__ void gemm_phase(LAS unsigned char* lds, const Gemm g, const StaticOrder& S, const Epi& E) {
;     ...
;             PG8_WAIT_V(8); PG8_WAIT_L(0); PG8_BAR; PG8_MMA(1, 0, At, B0); PG8_MMA(1, 1, At, B1); PG8_BAR; PG8_SCHED;
;             PG8_LDB(B0, 1, 0); PG8_LDB(B1, 1, 1); PG8_SCHED; PG8_LDA(At, 1, 0); PG8_STAGE(PG8_SA(0, 1), a2 + hstepA, voffA);
;             PG8_WAIT_V(8); PG8_WAIT_L(0); PG8_BAR; PG8_MMA(0, 0, At, B0); PG8_MMA(0, 1, At, B1); PG8_BAR; PG8_SCHED;
	s_setprio 1
	s_waitcnt lgkmcnt(0)
	v_mfma_f32_16x16x32_bf16 v[62:65], v[132:135], v[178:181], 0
	v_mfma_f32_16x16x32_bf16 v[58:61], v[140:143], v[178:181], 0
	v_mfma_f32_16x16x32_bf16 v[54:57], v[132:135], v[186:189], 0
	v_mfma_f32_16x16x32_bf16 v[50:53], v[140:143], v[186:189], 0
	v_mfma_f32_16x16x32_bf16 v[46:49], v[132:135], v[210:213], 0
	v_mfma_f32_16x16x32_bf16 v[34:37], v[140:143], v[210:213], 0
	v_mfma_f32_16x16x32_bf16 v[18:21], v[132:135], v[218:221], 0
	v_mfma_f32_16x16x32_bf16 v[14:17], v[140:143], v[218:221], 0
	s_setprio 0
	s_setprio 1
	v_mfma_f32_16x16x32_bf16 v[62:65], v[136:139], v[182:185], v[62:65]
	v_mfma_f32_16x16x32_bf16 v[58:61], v[144:147], v[182:185], v[58:61]
	v_mfma_f32_16x16x32_bf16 v[54:57], v[136:139], v[206:209], v[54:57]
	v_mfma_f32_16x16x32_bf16 v[50:53], v[144:147], v[206:209], v[50:53]
	v_mfma_f32_16x16x32_bf16 v[46:49], v[136:139], v[214:217], v[46:49]
	v_mfma_f32_16x16x32_bf16 v[34:37], v[144:147], v[214:217], v[34:37]
	v_mfma_f32_16x16x32_bf16 v[18:21], v[136:139], v[222:225], v[18:21]
	v_mfma_f32_16x16x32_bf16 v[14:17], v[144:147], v[222:225], v[14:17]
	s_setprio 0
	s_setprio 1
	v_mfma_f32_16x16x32_bf16 v[42:45], v[148:151], v[178:181], 0
	v_mfma_f32_16x16x32_bf16 v[38:41], v[170:173], v[178:181], 0
	v_mfma_f32_16x16x32_bf16 v[30:33], v[148:151], v[186:189], 0
	v_mfma_f32_16x16x32_bf16 v[26:29], v[170:173], v[186:189], 0
	v_mfma_f32_16x16x32_bf16 v[22:25], v[148:151], v[210:213], 0
	v_mfma_f32_16x16x32_bf16 v[10:13], v[170:173], v[210:213], 0
	v_mfma_f32_16x16x32_bf16 v[6:9], v[148:151], v[218:221], 0
	v_mfma_f32_16x16x32_bf16 v[2:5], v[170:173], v[218:221], 0
	s_setprio 0
	s_setprio 1
	v_mfma_f32_16x16x32_bf16 v[42:45], v[158:161], v[182:185], v[42:45]
	v_mfma_f32_16x16x32_bf16 v[38:41], v[174:177], v[182:185], v[38:41]
	v_mfma_f32_16x16x32_bf16 v[30:33], v[158:161], v[206:209], v[30:33]
	v_mfma_f32_16x16x32_bf16 v[26:29], v[174:177], v[206:209], v[26:29]
	v_mfma_f32_16x16x32_bf16 v[22:25], v[158:161], v[214:217], v[22:25]
	v_mfma_f32_16x16x32_bf16 v[10:13], v[174:177], v[214:217], v[10:13]
	v_mfma_f32_16x16x32_bf16 v[6:9], v[158:161], v[222:225], v[6:9]
	v_mfma_f32_16x16x32_bf16 v[2:5], v[174:177], v[222:225], v[2:5]
	s_setprio 0
	s_barrier
	s_add_i32 s73, 0, 0x18000
	s_add_i32 s74, 0, 0x1c000
	v_add_u32_e32 v144, s73, v155
	v_add_u32_e32 v152, s74, v155
	ds_read_b128 v[132:135], v144
	ds_read_b128 v[136:139], v144 offset:1024
	ds_read_b128 v[140:143], v144 offset:2048
	ds_read_b128 v[144:147], v144 offset:3072
	ds_read_b128 v[148:151], v152
	ds_read_b128 v[158:161], v152 offset:1024
	ds_read_b128 v[170:173], v152 offset:2048
	ds_read_b128 v[174:177], v152 offset:3072
	s_add_u32 s36, s36, s38
	s_addc_u32 s37, s37, s33
	s_mov_b32 m0, s43
	v_lshl_add_u64 v[152:153], s[36:37], 0, v[0:1]
	ds_read_b128 v[178:181], v157 offset:32768
	ds_read_b128 v[182:185], v157 offset:33792
	ds_read_b128 v[186:189], v157 offset:34816
	ds_read_b128 v[206:209], v157 offset:35840
	ds_read_b128 v[210:213], v157 offset:36864
	ds_read_b128 v[214:217], v157 offset:37888
	ds_read_b128 v[218:221], v157 offset:38912
	ds_read_b128 v[222:225], v157 offset:39936
	global_load_lds_dwordx4 v[152:153], off
	v_lshl_add_u64 v[152:153], s[36:37], 0, v[130:131]
	s_mov_b32 m0, s44
	s_nop 0
	global_load_lds_dwordx4 v[152:153], off
	s_waitcnt vmcnt(8)
	s_waitcnt lgkmcnt(0)
	s_barrier
	s_setprio 1
	s_waitcnt lgkmcnt(0)
	v_mfma_f32_16x16x32_bf16 v[126:129], v[132:135], v[178:181], v[126:129]
	v_mfma_f32_16x16x32_bf16 v[122:125], v[140:143], v[178:181], v[122:125]
	v_mfma_f32_16x16x32_bf16 v[118:121], v[132:135], v[186:189], v[118:121]
	v_mfma_f32_16x16x32_bf16 v[114:117], v[140:143], v[186:189], v[114:117]
	v_mfma_f32_16x16x32_bf16 v[110:113], v[132:135], v[210:213], v[110:113]
	v_mfma_f32_16x16x32_bf16 v[90:93], v[140:143], v[210:213], v[90:93]
	v_mfma_f32_16x16x32_bf16 v[86:89], v[132:135], v[218:221], v[86:89]
	v_mfma_f32_16x16x32_bf16 v[78:81], v[140:143], v[218:221], v[78:81]
	s_setprio 0
	s_setprio 1
	v_mfma_f32_16x16x32_bf16 v[126:129], v[136:139], v[182:185], v[126:129]
	v_mfma_f32_16x16x32_bf16 v[122:125], v[144:147], v[182:185], v[122:125]
	v_mfma_f32_16x16x32_bf16 v[118:121], v[136:139], v[206:209], v[118:121]
	v_mfma_f32_16x16x32_bf16 v[114:117], v[144:147], v[206:209], v[114:117]
	v_mfma_f32_16x16x32_bf16 v[110:113], v[136:139], v[214:217], v[110:113]
	v_mfma_f32_16x16x32_bf16 v[90:93], v[144:147], v[214:217], v[90:93]
	v_mfma_f32_16x16x32_bf16 v[86:89], v[136:139], v[222:225], v[86:89]
	v_mfma_f32_16x16x32_bf16 v[78:81], v[144:147], v[222:225], v[78:81]
	s_setprio 0
	s_setprio 1
	v_mfma_f32_16x16x32_bf16 v[106:109], v[148:151], v[178:181], v[106:109]
	v_mfma_f32_16x16x32_bf16 v[102:105], v[170:173], v[178:181], v[102:105]
	v_mfma_f32_16x16x32_bf16 v[98:101], v[148:151], v[186:189], v[98:101]
	v_mfma_f32_16x16x32_bf16 v[94:97], v[170:173], v[186:189], v[94:97]
	v_mfma_f32_16x16x32_bf16 v[82:85], v[148:151], v[210:213], v[82:85]
	v_mfma_f32_16x16x32_bf16 v[74:77], v[170:173], v[210:213], v[74:77]
	v_mfma_f32_16x16x32_bf16 v[70:73], v[148:151], v[218:221], v[70:73]
	v_mfma_f32_16x16x32_bf16 v[66:69], v[170:173], v[218:221], v[66:69]
	s_setprio 0
	s_setprio 1
	v_mfma_f32_16x16x32_bf16 v[106:109], v[158:161], v[182:185], v[106:109]
	v_mfma_f32_16x16x32_bf16 v[102:105], v[174:177], v[182:185], v[102:105]
	v_mfma_f32_16x16x32_bf16 v[98:101], v[158:161], v[206:209], v[98:101]
	v_mfma_f32_16x16x32_bf16 v[94:97], v[174:177], v[206:209], v[94:97]
	v_mfma_f32_16x16x32_bf16 v[82:85], v[158:161], v[214:217], v[82:85]
	v_mfma_f32_16x16x32_bf16 v[74:77], v[174:177], v[214:217], v[74:77]
	v_mfma_f32_16x16x32_bf16 v[70:73], v[158:161], v[222:225], v[70:73]
	v_mfma_f32_16x16x32_bf16 v[66:69], v[174:177], v[222:225], v[66:69]
	s_setprio 0
	s_barrier
; #define PG8_STAGE(bufoff, gbase, voff) do { _Pragma("unroll") for (int _i = 0; _i < 2; ++_i) \
;         __builtin_amdgcn_global_load_lds((const unsigned*)((const char*)(gbase) + (voff)[_i]), (LAS unsigned*)(lds + (bufoff) + ldsw + _i * 8192), 16, 0, 0); } while (0)
; #define PG8_LDA(dst, b, h) do { _Pragma("unroll") for (int m = 0; m < 4; ++m) _Pragma("unroll") for (int k = 0; k < 2; ++k) dst[m][k] = *(const LAS bf16x8*)(lds + PG8_SA(b, h) + aoff + m * 2048 + k * 1024); } while (0)
; #define PG8_MMA(ai, bj, At, Bt) do { __builtin_amdgcn_s_setprio(1); _Pragma("unroll") for (int m = 0; m < 4; ++m) _Pragma("unroll") for (int n = 0; n < 2; ++n) _Pragma("unroll") for (int k = 0; k < 2; ++k) \
;         acc[ai][bj][m][n] = __builtin_amdgcn_mfma_f32_16x16x32_bf16(Bt[n][k], At[m][k], acc[ai][bj][m][n], 0, 0, 0); __builtin_amdgcn_s_setprio(0); } while (0)
; #define PG8_WAIT_V(n) asm volatile("s_waitcnt vmcnt(" #n ")" ::: "memory")
; #define PG8_WAIT_L(n) asm volatile("s_waitcnt lgkmcnt(" #n ")" ::: "memory")
; #define PG8_BAR __builtin_amdgcn_s_barrier()
; #define PG8_SCHED __builtin_amdgcn_sched_barrier(0)
; template <class Epi, bool ALIGN_EPI = PG8_ALIGN, bool SP2 = PG8_SP2>
; __device__ __forceinline__ void gemm_phase(LAS unsigned char* lds, const Gemm g, const StaticOrder& S, const Epi& E) {
;     ...
;             PG8_LDA(At, 1, 1); PG8_STAGE(PG8_SB(1, 0), b3, voffB); PG8_STAGE(PG8_SB(1, 1), b3 + hstepB, voffB); PG8_STAGE(PG8_SA(1, 0), a3, voffA);
;             PG8_WAIT_V(8); PG8_WAIT_L(0); PG8_BAR; PG8_MMA(1, 0, At, B0); PG8_MMA(1, 1, At, B1); PG8_BAR; PG8_SCHED;
	s_add_u32 s34, s34, s52
	s_addc_u32 s35, s35, 0
	s_add_i32 s36, s73, s40
	v_lshl_add_u64 v[152:153], s[34:35], 0, v[0:1]
	s_mov_b32 m0, s36
	ds_read_b128 v[178:181], v157 offset:49152
	ds_read_b128 v[182:185], v157 offset:50176
	ds_read_b128 v[186:189], v157 offset:51200
	ds_read_b128 v[206:209], v157 offset:52224
	ds_read_b128 v[210:213], v157 offset:53248
	ds_read_b128 v[214:217], v157 offset:54272
	ds_read_b128 v[218:221], v157 offset:55296
	ds_read_b128 v[222:225], v157 offset:56320
	global_load_lds_dwordx4 v[152:153], off
	s_add_i32 m0, s36, 0x2000
	v_lshl_add_u64 v[152:153], s[34:35], 0, v[130:131]
	s_add_u32 s34, s34, s38
	s_addc_u32 s35, s35, s33
	s_add_i32 s36, s74, s40
	global_load_lds_dwordx4 v[152:153], off
	v_lshl_add_u64 v[152:153], s[34:35], 0, v[0:1]
	s_mov_b32 m0, s36
	s_nop 0
	global_load_lds_dwordx4 v[152:153], off
	v_lshl_add_u64 v[152:153], s[34:35], 0, v[130:131]
	s_add_i32 m0, s36, 0x2000
	s_nop 0
	global_load_lds_dwordx4 v[152:153], off
	v_lshl_add_u64 v[152:153], s[28:29], 0, v[0:1]
	s_mov_b32 m0, s53
	s_nop 0
	global_load_lds_dwordx4 v[152:153], off
	v_lshl_add_u64 v[152:153], s[28:29], 0, v[130:131]
	s_mov_b32 m0, s54
	s_nop 0
	global_load_lds_dwordx4 v[152:153], off
	s_waitcnt vmcnt(8)
	s_waitcnt lgkmcnt(0)
	s_barrier
	s_setprio 1
	s_waitcnt lgkmcnt(0)
	v_mfma_f32_16x16x32_bf16 v[62:65], v[132:135], v[178:181], v[62:65]
	v_mfma_f32_16x16x32_bf16 v[58:61], v[140:143], v[178:181], v[58:61]
	v_mfma_f32_16x16x32_bf16 v[54:57], v[132:135], v[186:189], v[54:57]
	v_mfma_f32_16x16x32_bf16 v[50:53], v[140:143], v[186:189], v[50:53]
	v_mfma_f32_16x16x32_bf16 v[46:49], v[132:135], v[210:213], v[46:49]
	v_mfma_f32_16x16x32_bf16 v[34:37], v[140:143], v[210:213], v[34:37]
	v_mfma_f32_16x16x32_bf16 v[18:21], v[132:135], v[218:221], v[18:21]
	v_mfma_f32_16x16x32_bf16 v[14:17], v[140:143], v[218:221], v[14:17]
	s_setprio 0
	s_setprio 1
	v_mfma_f32_16x16x32_bf16 v[62:65], v[136:139], v[182:185], v[62:65]
	v_mfma_f32_16x16x32_bf16 v[58:61], v[144:147], v[182:185], v[58:61]
	v_mfma_f32_16x16x32_bf16 v[54:57], v[136:139], v[206:209], v[54:57]
	v_mfma_f32_16x16x32_bf16 v[50:53], v[144:147], v[206:209], v[50:53]
	v_mfma_f32_16x16x32_bf16 v[46:49], v[136:139], v[214:217], v[46:49]
	v_mfma_f32_16x16x32_bf16 v[34:37], v[144:147], v[214:217], v[34:37]
	v_mfma_f32_16x16x32_bf16 v[18:21], v[136:139], v[222:225], v[18:21]
	v_mfma_f32_16x16x32_bf16 v[14:17], v[144:147], v[222:225], v[14:17]
	s_setprio 0
	s_setprio 1
	v_mfma_f32_16x16x32_bf16 v[42:45], v[148:151], v[178:181], v[42:45]
	v_mfma_f32_16x16x32_bf16 v[38:41], v[170:173], v[178:181], v[38:41]
	v_mfma_f32_16x16x32_bf16 v[30:33], v[148:151], v[186:189], v[30:33]
	v_mfma_f32_16x16x32_bf16 v[26:29], v[170:173], v[186:189], v[26:29]
	v_mfma_f32_16x16x32_bf16 v[22:25], v[148:151], v[210:213], v[22:25]
	v_mfma_f32_16x16x32_bf16 v[10:13], v[170:173], v[210:213], v[10:13]
	v_mfma_f32_16x16x32_bf16 v[6:9], v[148:151], v[218:221], v[6:9]
	v_mfma_f32_16x16x32_bf16 v[2:5], v[170:173], v[218:221], v[2:5]
	s_setprio 0
	s_setprio 1
	v_mfma_f32_16x16x32_bf16 v[42:45], v[158:161], v[182:185], v[42:45]
	v_mfma_f32_16x16x32_bf16 v[38:41], v[174:177], v[182:185], v[38:41]
	v_mfma_f32_16x16x32_bf16 v[30:33], v[158:161], v[206:209], v[30:33]
	v_mfma_f32_16x16x32_bf16 v[26:29], v[174:177], v[206:209], v[26:29]
	v_mfma_f32_16x16x32_bf16 v[22:25], v[158:161], v[214:217], v[22:25]
	v_mfma_f32_16x16x32_bf16 v[10:13], v[174:177], v[214:217], v[10:13]
	v_mfma_f32_16x16x32_bf16 v[6:9], v[158:161], v[222:225], v[6:9]
	v_mfma_f32_16x16x32_bf16 v[2:5], v[174:177], v[222:225], v[2:5]
	s_setprio 0
	s_barrier
	s_cmp_ge_u32 s30, s49
	s_mov_b64 s[28:29], s[30:31]
	s_branch .LBB0_583

; #define PG8_STAGE(bufoff, gbase, voff) do { _Pragma("unroll") for (int _i = 0; _i < 2; ++_i) \
;         __builtin_amdgcn_global_load_lds((const unsigned*)((const char*)(gbase) + (voff)[_i]), (LAS unsigned*)(lds + (bufoff) + ldsw + _i * 8192), 16, 0, 0); } while (0)
; #define PG8_LDA(dst, b, h) do { _Pragma("unroll") for (int m = 0; m < 4; ++m) _Pragma("unroll") for (int k = 0; k < 2; ++k) dst[m][k] = *(const LAS bf16x8*)(lds + PG8_SA(b, h) + aoff + m * 2048 + k * 1024); } while (0)
; #define PG8_LDB(dst, b, h) do { _Pragma("unroll") for (int n = 0; n < 2; ++n) _Pragma("unroll") for (int k = 0; k < 2; ++k) dst[n][k] = *(const LAS bf16x8*)(lds + PG8_SB(b, h) + boff + n * 2048 + k * 1024); } while (0)
; #define PG8_MMA(ai, bj, At, Bt) do { __builtin_amdgcn_s_setprio(1); _Pragma("unroll") for (int m = 0; m < 4; ++m) _Pragma("unroll") for (int n = 0; n < 2; ++n) _Pragma("unroll") for (int k = 0; k < 2; ++k) \
;         acc[ai][bj][m][n] = __builtin_amdgcn_mfma_f32_16x16x32_bf16(Bt[n][k], At[m][k], acc[ai][bj][m][n], 0, 0, 0); __builtin_amdgcn_s_setprio(0); } while (0)
; #define PG8_WAIT_V(n) asm volatile("s_waitcnt vmcnt(" #n ")" ::: "memory")
; #define PG8_WAIT_L(n) asm volatile("s_waitcnt lgkmcnt(" #n ")" ::: "memory")
; #define PG8_BAR __builtin_amdgcn_s_barrier()
; #define PG8_SCHED __builtin_amdgcn_sched_barrier(0)
; template <class Epi, bool ALIGN_EPI = PG8_ALIGN, bool SP2 = PG8_SP2>
; __device__ __forceinline__ void gemm_phase(LAS unsigned char* lds, const Gemm g, const StaticOrder& S, const Epi& E) {
;     ...
;             const bool last = (t == nt - 2);
;             const char* a1 = cA + (size_t)(t + 1) * kstepA;
;             const char* a2 = last ? nA : cA + (size_t)(t + 2) * kstepA; const char* b2 = last ? nB : cB + (size_t)(t + 2) * kstepB;
;             const char* a3 = a2 + kstepA; const char* b3 = b2 + kstepB;
;             if constexpr (SP2) {
;             PG8_LDB(B0, 0, 0); PG8_LDB(B1, 0, 1); PG8_SCHED; PG8_LDA(At, 0, 0); PG8_STAGE(PG8_SA(1, 1), a1 + hstepA, voffA);
;             PG8_WAIT_V(8); PG8_WAIT_L(0); PG8_BAR; PG8_MMA(0, 0, At, B0); PG8_MMA(0, 1, At, B1); PG8_BAR; PG8_SCHED;
;             PG8_LDA(At, 0, 1); PG8_STAGE(PG8_SB(0, 0), b2, voffB); PG8_STAGE(PG8_SB(0, 1), b2 + hstepB, voffB); PG8_STAGE(PG8_SA(0, 0), a2, voffA);
;             PG8_WAIT_V(8); PG8_WAIT_L(0); PG8_BAR; PG8_MMA(1, 0, At, B0); PG8_MMA(1, 1, At, B1); PG8_BAR; PG8_SCHED;
.LBB0_611:
	s_cmp_eq_u32 s47, -2
	s_cbranch_scc1 .Lfirst_iter_u611
	s_add_u32 s22, s20, 0xfffc0080
	s_addc_u32 s23, s21, -1
	s_add_i32 s48, 0, 0x10000
	s_cmp_eq_u32 s47, 12
	s_cselect_b32 s25, s13, s23
	s_cselect_b32 s24, s43, s22
	v_add_u32_e32 v0, s48, v141
	s_cselect_b32 s23, s11, s46
	s_cselect_b32 s22, s44, s45
	s_add_i32 s52, 0, 0x14000
	ds_read_b128 v[144:147], v0
	ds_read_b128 v[148:151], v0 offset:1024
	ds_read_b128 v[152:155], v0 offset:2048
	ds_read_b128 v[156:159], v0 offset:3072
	v_add_u32_e32 v0, s52, v141
	ds_read_b128 v[170:173], v0
	ds_read_b128 v[174:177], v0 offset:1024
	ds_read_b128 v[178:181], v0 offset:2048
	ds_read_b128 v[182:185], v0 offset:3072
	v_lshl_add_u64 v[160:161], s[20:21], 0, v[134:135]
	s_add_i32 m0, s34, 0xc000
	ds_read_b128 v[186:189], v142
	ds_read_b128 v[206:209], v142 offset:1024
	ds_read_b128 v[210:213], v142 offset:2048
	ds_read_b128 v[214:217], v142 offset:3072
	ds_read_b128 v[218:221], v142 offset:4096
	ds_read_b128 v[222:225], v142 offset:5120
	ds_read_b128 v[226:229], v142 offset:6144
	ds_read_b128 v[230:233], v142 offset:7168
	global_load_lds_dwordx4 v[160:161], off
	v_lshl_add_u64 v[160:161], s[20:21], 0, v[136:137]
	s_add_i32 m0, s34, 0xe000
	s_nop 0
	global_load_lds_dwordx4 v[160:161], off
	s_waitcnt vmcnt(8)
	s_waitcnt lgkmcnt(0)
	s_barrier
	s_setprio 1
	s_waitcnt lgkmcnt(0)
	v_mfma_f32_16x16x32_bf16 v[126:129], v[144:147], v[186:189], v[126:129]
	v_mfma_f32_16x16x32_bf16 v[118:121], v[152:155], v[186:189], v[118:121]
	v_mfma_f32_16x16x32_bf16 v[110:113], v[144:147], v[210:213], v[110:113]
	v_mfma_f32_16x16x32_bf16 v[102:105], v[152:155], v[210:213], v[102:105]
	v_mfma_f32_16x16x32_bf16 v[94:97], v[144:147], v[218:221], v[94:97]
	v_mfma_f32_16x16x32_bf16 v[86:89], v[152:155], v[218:221], v[86:89]
	v_mfma_f32_16x16x32_bf16 v[78:81], v[144:147], v[226:229], v[78:81]
	v_mfma_f32_16x16x32_bf16 v[70:73], v[152:155], v[226:229], v[70:73]
	s_setprio 0
	s_setprio 1
	v_mfma_f32_16x16x32_bf16 v[126:129], v[148:151], v[206:209], v[126:129]
	v_mfma_f32_16x16x32_bf16 v[118:121], v[156:159], v[206:209], v[118:121]
	v_mfma_f32_16x16x32_bf16 v[110:113], v[148:151], v[214:217], v[110:113]
	v_mfma_f32_16x16x32_bf16 v[102:105], v[156:159], v[214:217], v[102:105]
	v_mfma_f32_16x16x32_bf16 v[94:97], v[148:151], v[222:225], v[94:97]
	v_mfma_f32_16x16x32_bf16 v[86:89], v[156:159], v[222:225], v[86:89]
	v_mfma_f32_16x16x32_bf16 v[78:81], v[148:151], v[230:233], v[78:81]
	v_mfma_f32_16x16x32_bf16 v[70:73], v[156:159], v[230:233], v[70:73]
	s_setprio 0
	s_setprio 1
	v_mfma_f32_16x16x32_bf16 v[122:125], v[170:173], v[186:189], v[122:125]
	v_mfma_f32_16x16x32_bf16 v[114:117], v[178:181], v[186:189], v[114:117]
	v_mfma_f32_16x16x32_bf16 v[106:109], v[170:173], v[210:213], v[106:109]
	v_mfma_f32_16x16x32_bf16 v[98:101], v[178:181], v[210:213], v[98:101]
	v_mfma_f32_16x16x32_bf16 v[90:93], v[170:173], v[218:221], v[90:93]
	v_mfma_f32_16x16x32_bf16 v[82:85], v[178:181], v[218:221], v[82:85]
	v_mfma_f32_16x16x32_bf16 v[74:77], v[170:173], v[226:229], v[74:77]
	v_mfma_f32_16x16x32_bf16 v[66:69], v[178:181], v[226:229], v[66:69]
	s_setprio 0
	s_setprio 1
	v_mfma_f32_16x16x32_bf16 v[122:125], v[174:177], v[206:209], v[122:125]
	v_mfma_f32_16x16x32_bf16 v[114:117], v[182:185], v[206:209], v[114:117]
	v_mfma_f32_16x16x32_bf16 v[106:109], v[174:177], v[214:217], v[106:109]
	v_mfma_f32_16x16x32_bf16 v[98:101], v[182:185], v[214:217], v[98:101]
	v_mfma_f32_16x16x32_bf16 v[90:93], v[174:177], v[222:225], v[90:93]
	v_mfma_f32_16x16x32_bf16 v[82:85], v[182:185], v[222:225], v[82:85]
	v_mfma_f32_16x16x32_bf16 v[74:77], v[174:177], v[230:233], v[74:77]
	v_mfma_f32_16x16x32_bf16 v[66:69], v[182:185], v[230:233], v[66:69]
	s_setprio 0
	s_barrier
	s_add_i32 s48, s48, s33
	v_lshl_add_u64 v[160:161], s[22:23], 0, v[130:131]
	s_mov_b32 m0, s48
	ds_read_b128 v[186:189], v142 offset:16384
	ds_read_b128 v[206:209], v142 offset:17408
	ds_read_b128 v[210:213], v142 offset:18432
	ds_read_b128 v[214:217], v142 offset:19456
	ds_read_b128 v[218:221], v142 offset:20480
	ds_read_b128 v[222:225], v142 offset:21504
	ds_read_b128 v[226:229], v142 offset:22528
	ds_read_b128 v[230:233], v142 offset:23552
	global_load_lds_dwordx4 v[160:161], off
	s_add_i32 m0, s48, 0x2000
	s_add_u32 s48, s22, 0x40000
	v_lshl_add_u64 v[164:165], s[22:23], 0, v[132:133]
	s_addc_u32 s49, s23, 0
	s_add_i32 s52, s52, s33
	global_load_lds_dwordx4 v[164:165], off
	v_lshl_add_u64 v[166:167], s[48:49], 0, v[130:131]
	s_mov_b32 m0, s52
	v_lshl_add_u64 v[194:195], s[24:25], 0, v[132:133]
	global_load_lds_dwordx4 v[166:167], off
	v_lshl_add_u64 v[166:167], s[48:49], 0, v[132:133]
	s_add_i32 m0, s52, 0x2000
	s_nop 0
	global_load_lds_dwordx4 v[166:167], off
	v_lshl_add_u64 v[166:167], s[24:25], 0, v[130:131]
	s_mov_b32 m0, s34
	s_nop 0
	global_load_lds_dwordx4 v[166:167], off
	s_mov_b32 m0, s35
	s_nop 0
	global_load_lds_dwordx4 v[194:195], off
	s_waitcnt vmcnt(8)
	s_waitcnt lgkmcnt(0)
	s_barrier
; #define PG8_STAGE(bufoff, gbase, voff) do { _Pragma("unroll") for (int _i = 0; _i < 2; ++_i) \
;         __builtin_amdgcn_global_load_lds((const unsigned*)((const char*)(gbase) + (voff)[_i]), (LAS unsigned*)(lds + (bufoff) + ldsw + _i * 8192), 16, 0, 0); } while (0)
; #define PG8_LDA(dst, b, h) do { _Pragma("unroll") for (int m = 0; m < 4; ++m) _Pragma("unroll") for (int k = 0; k < 2; ++k) dst[m][k] = *(const LAS bf16x8*)(lds + PG8_SA(b, h) + aoff + m * 2048 + k * 1024); } while (0)
; #define PG8_LDB(dst, b, h) do { _Pragma("unroll") for (int n = 0; n < 2; ++n) _Pragma("unroll") for (int k = 0; k < 2; ++k) dst[n][k] = *(const LAS bf16x8*)(lds + PG8_SB(b, h) + boff + n * 2048 + k * 1024); } while (0)
; #define PG8_MMA(ai, bj, At, Bt) do { __builtin_amdgcn_s_setprio(1); _Pragma("unroll") for (int m = 0; m < 4; ++m) _Pragma("unroll") for (int n = 0; n < 2; ++n) _Pragma("unroll") for (int k = 0; k < 2; ++k) \
;         acc[ai][bj][m][n] = __builtin_amdgcn_mfma_f32_16x16x32_bf16(Bt[n][k], At[m][k], acc[ai][bj][m][n], 0, 0, 0); __builtin_amdgcn_s_setprio(0); } while (0)
; #define PG8_WAIT_V(n) asm volatile("s_waitcnt vmcnt(" #n ")" ::: "memory")
; #define PG8_WAIT_L(n) asm volatile("s_waitcnt lgkmcnt(" #n ")" ::: "memory")
; #define PG8_BAR __builtin_amdgcn_s_barrier()
; #define PG8_SCHED __builtin_amdgcn_sched_barrier(0)
; template <class Epi, bool ALIGN_EPI = PG8_ALIGN, bool SP2 = PG8_SP2>
; __device__ __forceinline__ void gemm_phase(LAS unsigned char* lds, const Gemm g, const StaticOrder& S, const Epi& E) {
;     ...
;             PG8_WAIT_V(8); PG8_WAIT_L(0); PG8_BAR; PG8_MMA(1, 0, At, B0); PG8_MMA(1, 1, At, B1); PG8_BAR; PG8_SCHED;
;             PG8_LDB(B0, 1, 0); PG8_LDB(B1, 1, 1); PG8_SCHED; PG8_LDA(At, 1, 0); PG8_STAGE(PG8_SA(0, 1), a2 + hstepA, voffA);
;             PG8_WAIT_V(8); PG8_WAIT_L(0); PG8_BAR; PG8_MMA(0, 0, At, B0); PG8_MMA(0, 1, At, B1); PG8_BAR; PG8_SCHED;
	s_setprio 1
	s_waitcnt lgkmcnt(0)
	v_mfma_f32_16x16x32_bf16 v[62:65], v[144:147], v[186:189], v[62:65]
	v_mfma_f32_16x16x32_bf16 v[54:57], v[152:155], v[186:189], v[54:57]
	v_mfma_f32_16x16x32_bf16 v[46:49], v[144:147], v[210:213], v[46:49]
	v_mfma_f32_16x16x32_bf16 v[38:41], v[152:155], v[210:213], v[38:41]
	v_mfma_f32_16x16x32_bf16 v[30:33], v[144:147], v[218:221], v[30:33]
	v_mfma_f32_16x16x32_bf16 v[22:25], v[152:155], v[218:221], v[22:25]
	v_mfma_f32_16x16x32_bf16 v[14:17], v[144:147], v[226:229], v[14:17]
	v_mfma_f32_16x16x32_bf16 v[6:9], v[152:155], v[226:229], v[6:9]
	s_setprio 0
	s_setprio 1
	v_mfma_f32_16x16x32_bf16 v[62:65], v[148:151], v[206:209], v[62:65]
	v_mfma_f32_16x16x32_bf16 v[54:57], v[156:159], v[206:209], v[54:57]
	v_mfma_f32_16x16x32_bf16 v[46:49], v[148:151], v[214:217], v[46:49]
	v_mfma_f32_16x16x32_bf16 v[38:41], v[156:159], v[214:217], v[38:41]
	v_mfma_f32_16x16x32_bf16 v[30:33], v[148:151], v[222:225], v[30:33]
	v_mfma_f32_16x16x32_bf16 v[22:25], v[156:159], v[222:225], v[22:25]
	v_mfma_f32_16x16x32_bf16 v[14:17], v[148:151], v[230:233], v[14:17]
	v_mfma_f32_16x16x32_bf16 v[6:9], v[156:159], v[230:233], v[6:9]
	s_setprio 0
	s_setprio 1
	v_mfma_f32_16x16x32_bf16 v[58:61], v[170:173], v[186:189], v[58:61]
	v_mfma_f32_16x16x32_bf16 v[50:53], v[178:181], v[186:189], v[50:53]
	v_mfma_f32_16x16x32_bf16 v[42:45], v[170:173], v[210:213], v[42:45]
	v_mfma_f32_16x16x32_bf16 v[34:37], v[178:181], v[210:213], v[34:37]
	v_mfma_f32_16x16x32_bf16 v[26:29], v[170:173], v[218:221], v[26:29]
	v_mfma_f32_16x16x32_bf16 v[18:21], v[178:181], v[218:221], v[18:21]
	v_mfma_f32_16x16x32_bf16 v[10:13], v[170:173], v[226:229], v[10:13]
	v_mfma_f32_16x16x32_bf16 v[2:5], v[178:181], v[226:229], v[2:5]
	s_setprio 0
	s_setprio 1
	v_mfma_f32_16x16x32_bf16 v[58:61], v[174:177], v[206:209], v[58:61]
	v_mfma_f32_16x16x32_bf16 v[50:53], v[182:185], v[206:209], v[50:53]
	v_mfma_f32_16x16x32_bf16 v[42:45], v[174:177], v[214:217], v[42:45]
	v_mfma_f32_16x16x32_bf16 v[34:37], v[182:185], v[214:217], v[34:37]
	v_mfma_f32_16x16x32_bf16 v[26:29], v[174:177], v[222:225], v[26:29]
	v_mfma_f32_16x16x32_bf16 v[18:21], v[182:185], v[222:225], v[18:21]
	v_mfma_f32_16x16x32_bf16 v[10:13], v[174:177], v[230:233], v[10:13]
	v_mfma_f32_16x16x32_bf16 v[2:5], v[182:185], v[230:233], v[2:5]
	s_setprio 0
	s_barrier
	s_add_i32 s48, 0, 0x18000
	v_add_u32_e32 v0, s48, v141
	s_add_i32 s49, 0, 0x1c000
	ds_read_b128 v[144:147], v0
	ds_read_b128 v[148:151], v0 offset:1024
	ds_read_b128 v[152:155], v0 offset:2048
	ds_read_b128 v[156:159], v0 offset:3072
	v_add_u32_e32 v0, s49, v141
	ds_read_b128 v[170:173], v0
	ds_read_b128 v[174:177], v0 offset:1024
	ds_read_b128 v[178:181], v0 offset:2048
	ds_read_b128 v[182:185], v0 offset:3072
	s_add_u32 s24, s24, 0x40000
	s_addc_u32 s25, s25, 0
	s_mov_b32 m0, s36
	v_lshl_add_u64 v[196:197], s[24:25], 0, v[130:131]
	ds_read_b128 v[186:189], v142 offset:32768
	ds_read_b128 v[206:209], v142 offset:33792
	ds_read_b128 v[210:213], v142 offset:34816
	ds_read_b128 v[214:217], v142 offset:35840
	ds_read_b128 v[218:221], v142 offset:36864
	ds_read_b128 v[222:225], v142 offset:37888
	ds_read_b128 v[226:229], v142 offset:38912
	ds_read_b128 v[230:233], v142 offset:39936
	global_load_lds_dwordx4 v[196:197], off
	v_lshl_add_u64 v[196:197], s[24:25], 0, v[132:133]
	s_mov_b32 m0, s37
	s_nop 0
	global_load_lds_dwordx4 v[196:197], off
	s_waitcnt vmcnt(8)
	s_waitcnt lgkmcnt(0)
	s_barrier
	s_setprio 1
	s_waitcnt lgkmcnt(0)
	v_mfma_f32_16x16x32_bf16 v[126:129], v[144:147], v[186:189], v[126:129]
	v_mfma_f32_16x16x32_bf16 v[118:121], v[152:155], v[186:189], v[118:121]
	v_mfma_f32_16x16x32_bf16 v[110:113], v[144:147], v[210:213], v[110:113]
	v_mfma_f32_16x16x32_bf16 v[102:105], v[152:155], v[210:213], v[102:105]
	v_mfma_f32_16x16x32_bf16 v[94:97], v[144:147], v[218:221], v[94:97]
	v_mfma_f32_16x16x32_bf16 v[86:89], v[152:155], v[218:221], v[86:89]
	v_mfma_f32_16x16x32_bf16 v[78:81], v[144:147], v[226:229], v[78:81]
	v_mfma_f32_16x16x32_bf16 v[70:73], v[152:155], v[226:229], v[70:73]
	s_setprio 0
	s_setprio 1
	v_mfma_f32_16x16x32_bf16 v[126:129], v[148:151], v[206:209], v[126:129]
	v_mfma_f32_16x16x32_bf16 v[118:121], v[156:159], v[206:209], v[118:121]
	v_mfma_f32_16x16x32_bf16 v[110:113], v[148:151], v[214:217], v[110:113]
	v_mfma_f32_16x16x32_bf16 v[102:105], v[156:159], v[214:217], v[102:105]
	v_mfma_f32_16x16x32_bf16 v[94:97], v[148:151], v[222:225], v[94:97]
	v_mfma_f32_16x16x32_bf16 v[86:89], v[156:159], v[222:225], v[86:89]
	v_mfma_f32_16x16x32_bf16 v[78:81], v[148:151], v[230:233], v[78:81]
	v_mfma_f32_16x16x32_bf16 v[70:73], v[156:159], v[230:233], v[70:73]
	s_setprio 0
	s_setprio 1
	v_mfma_f32_16x16x32_bf16 v[122:125], v[170:173], v[186:189], v[122:125]
	v_mfma_f32_16x16x32_bf16 v[114:117], v[178:181], v[186:189], v[114:117]
	v_mfma_f32_16x16x32_bf16 v[106:109], v[170:173], v[210:213], v[106:109]
	v_mfma_f32_16x16x32_bf16 v[98:101], v[178:181], v[210:213], v[98:101]
	v_mfma_f32_16x16x32_bf16 v[90:93], v[170:173], v[218:221], v[90:93]
	v_mfma_f32_16x16x32_bf16 v[82:85], v[178:181], v[218:221], v[82:85]
	v_mfma_f32_16x16x32_bf16 v[74:77], v[170:173], v[226:229], v[74:77]
	v_mfma_f32_16x16x32_bf16 v[66:69], v[178:181], v[226:229], v[66:69]
	s_setprio 0
	s_setprio 1
	v_mfma_f32_16x16x32_bf16 v[122:125], v[174:177], v[206:209], v[122:125]
	v_mfma_f32_16x16x32_bf16 v[114:117], v[182:185], v[206:209], v[114:117]
	v_mfma_f32_16x16x32_bf16 v[106:109], v[174:177], v[214:217], v[106:109]
	v_mfma_f32_16x16x32_bf16 v[98:101], v[182:185], v[214:217], v[98:101]
	v_mfma_f32_16x16x32_bf16 v[90:93], v[174:177], v[222:225], v[90:93]
	v_mfma_f32_16x16x32_bf16 v[82:85], v[182:185], v[222:225], v[82:85]
	v_mfma_f32_16x16x32_bf16 v[74:77], v[174:177], v[230:233], v[74:77]
	v_mfma_f32_16x16x32_bf16 v[66:69], v[182:185], v[230:233], v[66:69]
	s_setprio 0
	s_barrier
; #define PG8_STAGE(bufoff, gbase, voff) do { _Pragma("unroll") for (int _i = 0; _i < 2; ++_i) \
;         __builtin_amdgcn_global_load_lds((const unsigned*)((const char*)(gbase) + (voff)[_i]), (LAS unsigned*)(lds + (bufoff) + ldsw + _i * 8192), 16, 0, 0); } while (0)
; #define PG8_LDA(dst, b, h) do { _Pragma("unroll") for (int m = 0; m < 4; ++m) _Pragma("unroll") for (int k = 0; k < 2; ++k) dst[m][k] = *(const LAS bf16x8*)(lds + PG8_SA(b, h) + aoff + m * 2048 + k * 1024); } while (0)
; #define PG8_MMA(ai, bj, At, Bt) do { __builtin_amdgcn_s_setprio(1); _Pragma("unroll") for (int m = 0; m < 4; ++m) _Pragma("unroll") for (int n = 0; n < 2; ++n) _Pragma("unroll") for (int k = 0; k < 2; ++k) \
;         acc[ai][bj][m][n] = __builtin_amdgcn_mfma_f32_16x16x32_bf16(Bt[n][k], At[m][k], acc[ai][bj][m][n], 0, 0, 0); __builtin_amdgcn_s_setprio(0); } while (0)
; #define PG8_WAIT_V(n) asm volatile("s_waitcnt vmcnt(" #n ")" ::: "memory")
; #define PG8_WAIT_L(n) asm volatile("s_waitcnt lgkmcnt(" #n ")" ::: "memory")
; #define PG8_BAR __builtin_amdgcn_s_barrier()
; #define PG8_SCHED __builtin_amdgcn_sched_barrier(0)
; template <class Epi, bool ALIGN_EPI = PG8_ALIGN, bool SP2 = PG8_SP2>
; __device__ __forceinline__ void gemm_phase(LAS unsigned char* lds, const Gemm g, const StaticOrder& S, const Epi& E) {
;     ...
;             PG8_LDA(At, 1, 1); PG8_STAGE(PG8_SB(1, 0), b3, voffB); PG8_STAGE(PG8_SB(1, 1), b3 + hstepB, voffB); PG8_STAGE(PG8_SA(1, 0), a3, voffA);
;             PG8_WAIT_V(8); PG8_WAIT_L(0); PG8_BAR; PG8_MMA(1, 0, At, B0); PG8_MMA(1, 1, At, B1); PG8_BAR; PG8_SCHED;
	s_add_i32 s24, s48, s33
	v_lshl_add_u64 v[160:161], v[160:161], 0, s[50:51]
	s_mov_b32 m0, s24
	ds_read_b128 v[186:189], v142 offset:49152
	ds_read_b128 v[206:209], v142 offset:50176
	ds_read_b128 v[210:213], v142 offset:51200
	ds_read_b128 v[214:217], v142 offset:52224
	ds_read_b128 v[218:221], v142 offset:53248
	ds_read_b128 v[222:225], v142 offset:54272
	ds_read_b128 v[226:229], v142 offset:55296
	ds_read_b128 v[230:233], v142 offset:56320
	global_load_lds_dwordx4 v[160:161], off
	s_add_i32 m0, s24, 0x2000
	s_add_u32 s22, s22, 0x40080
	v_lshl_add_u64 v[160:161], v[164:165], 0, s[50:51]
	s_addc_u32 s23, s23, 0
	s_add_i32 s24, s49, s33
	global_load_lds_dwordx4 v[160:161], off
	v_lshl_add_u64 v[160:161], s[22:23], 0, v[130:131]
	s_mov_b32 m0, s24
	s_nop 0
	global_load_lds_dwordx4 v[160:161], off
	v_lshl_add_u64 v[160:161], s[22:23], 0, v[132:133]
	s_add_i32 m0, s24, 0x2000
	s_nop 0
	global_load_lds_dwordx4 v[160:161], off
	v_lshl_add_u64 v[160:161], v[166:167], 0, s[50:51]
	s_mov_b32 m0, s40
	s_nop 0
	global_load_lds_dwordx4 v[160:161], off
	v_lshl_add_u64 v[160:161], v[194:195], 0, s[50:51]
	s_mov_b32 m0, s41
	s_nop 0
	global_load_lds_dwordx4 v[160:161], off
	s_waitcnt vmcnt(8)
	s_waitcnt lgkmcnt(0)
	s_barrier
	s_setprio 1
	s_waitcnt lgkmcnt(0)
	v_mfma_f32_16x16x32_bf16 v[62:65], v[144:147], v[186:189], v[62:65]
	v_mfma_f32_16x16x32_bf16 v[54:57], v[152:155], v[186:189], v[54:57]
	v_mfma_f32_16x16x32_bf16 v[46:49], v[144:147], v[210:213], v[46:49]
	v_mfma_f32_16x16x32_bf16 v[38:41], v[152:155], v[210:213], v[38:41]
	v_mfma_f32_16x16x32_bf16 v[30:33], v[144:147], v[218:221], v[30:33]
	v_mfma_f32_16x16x32_bf16 v[22:25], v[152:155], v[218:221], v[22:25]
	v_mfma_f32_16x16x32_bf16 v[14:17], v[144:147], v[226:229], v[14:17]
	v_mfma_f32_16x16x32_bf16 v[6:9], v[152:155], v[226:229], v[6:9]
	s_setprio 0
	s_setprio 1
	v_mfma_f32_16x16x32_bf16 v[62:65], v[148:151], v[206:209], v[62:65]
	v_mfma_f32_16x16x32_bf16 v[54:57], v[156:159], v[206:209], v[54:57]
	v_mfma_f32_16x16x32_bf16 v[46:49], v[148:151], v[214:217], v[46:49]
	v_mfma_f32_16x16x32_bf16 v[38:41], v[156:159], v[214:217], v[38:41]
	v_mfma_f32_16x16x32_bf16 v[30:33], v[148:151], v[222:225], v[30:33]
	v_mfma_f32_16x16x32_bf16 v[22:25], v[156:159], v[222:225], v[22:25]
	v_mfma_f32_16x16x32_bf16 v[14:17], v[148:151], v[230:233], v[14:17]
	v_mfma_f32_16x16x32_bf16 v[6:9], v[156:159], v[230:233], v[6:9]
	s_setprio 0
	s_setprio 1
	v_mfma_f32_16x16x32_bf16 v[58:61], v[170:173], v[186:189], v[58:61]
	v_mfma_f32_16x16x32_bf16 v[50:53], v[178:181], v[186:189], v[50:53]
	v_mfma_f32_16x16x32_bf16 v[42:45], v[170:173], v[210:213], v[42:45]
	v_mfma_f32_16x16x32_bf16 v[34:37], v[178:181], v[210:213], v[34:37]
	v_mfma_f32_16x16x32_bf16 v[26:29], v[170:173], v[218:221], v[26:29]
	v_mfma_f32_16x16x32_bf16 v[18:21], v[178:181], v[218:221], v[18:21]
	v_mfma_f32_16x16x32_bf16 v[10:13], v[170:173], v[226:229], v[10:13]
	v_mfma_f32_16x16x32_bf16 v[2:5], v[178:181], v[226:229], v[2:5]
	s_setprio 0
	s_setprio 1
	v_mfma_f32_16x16x32_bf16 v[58:61], v[174:177], v[206:209], v[58:61]
	v_mfma_f32_16x16x32_bf16 v[50:53], v[182:185], v[206:209], v[50:53]
	v_mfma_f32_16x16x32_bf16 v[42:45], v[174:177], v[214:217], v[42:45]
	v_mfma_f32_16x16x32_bf16 v[34:37], v[182:185], v[214:217], v[34:37]
	v_mfma_f32_16x16x32_bf16 v[26:29], v[174:177], v[222:225], v[26:29]
	v_mfma_f32_16x16x32_bf16 v[18:21], v[182:185], v[222:225], v[18:21]
	v_mfma_f32_16x16x32_bf16 v[10:13], v[174:177], v[230:233], v[10:13]
	v_mfma_f32_16x16x32_bf16 v[2:5], v[182:185], v[230:233], v[2:5]
	s_setprio 0
	s_barrier
	s_add_i32 s47, s47, 2
	s_add_u32 s20, s20, 0x100
	s_addc_u32 s21, s21, 0
	s_add_u32 s45, s45, 0x100
	s_addc_u32 s46, s46, 0
	s_cmp_gt_u32 s47, 13
	s_cbranch_scc0 .LBB0_611
	s_and_b64 vcc, exec, s[8:9]
	s_cbranch_vccz .LBB0_614
	s_barrier

; #define PG8_STAGE(bufoff, gbase, voff) do { _Pragma("unroll") for (int _i = 0; _i < 2; ++_i) \
;         __builtin_amdgcn_global_load_lds((const unsigned*)((const char*)(gbase) + (voff)[_i]), (LAS unsigned*)(lds + (bufoff) + ldsw + _i * 8192), 16, 0, 0); } while (0)
; #define PG8_LDA(dst, b, h) do { _Pragma("unroll") for (int m = 0; m < 4; ++m) _Pragma("unroll") for (int k = 0; k < 2; ++k) dst[m][k] = *(const LAS bf16x8*)(lds + PG8_SA(b, h) + aoff + m * 2048 + k * 1024); } while (0)
; #define PG8_LDB(dst, b, h) do { _Pragma("unroll") for (int n = 0; n < 2; ++n) _Pragma("unroll") for (int k = 0; k < 2; ++k) dst[n][k] = *(const LAS bf16x8*)(lds + PG8_SB(b, h) + boff + n * 2048 + k * 1024); } while (0)
; #define PG8_MMA(ai, bj, At, Bt) do { __builtin_amdgcn_s_setprio(1); _Pragma("unroll") for (int m = 0; m < 4; ++m) _Pragma("unroll") for (int n = 0; n < 2; ++n) _Pragma("unroll") for (int k = 0; k < 2; ++k) \
;         acc[ai][bj][m][n] = __builtin_amdgcn_mfma_f32_16x16x32_bf16(Bt[n][k], At[m][k], acc[ai][bj][m][n], 0, 0, 0); __builtin_amdgcn_s_setprio(0); } while (0)
; #define PG8_WAIT_V(n) asm volatile("s_waitcnt vmcnt(" #n ")" ::: "memory")
; #define PG8_WAIT_L(n) asm volatile("s_waitcnt lgkmcnt(" #n ")" ::: "memory")
; #define PG8_BAR __builtin_amdgcn_s_barrier()
; #define PG8_SCHED __builtin_amdgcn_sched_barrier(0)
; template <class Epi, bool ALIGN_EPI = PG8_ALIGN, bool SP2 = PG8_SP2>
; __device__ __forceinline__ void gemm_phase(LAS unsigned char* lds, const Gemm g, const StaticOrder& S, const Epi& E) {
;     ...
;             const bool last = (t == nt - 2);
;             const char* a1 = cA + (size_t)(t + 1) * kstepA;
;             const char* a2 = last ? nA : cA + (size_t)(t + 2) * kstepA; const char* b2 = last ? nB : cB + (size_t)(t + 2) * kstepB;
;             const char* a3 = a2 + kstepA; const char* b3 = b2 + kstepB;
;             if constexpr (SP2) {
;             PG8_LDB(B0, 0, 0); PG8_LDB(B1, 0, 1); PG8_SCHED; PG8_LDA(At, 0, 0); PG8_STAGE(PG8_SA(1, 1), a1 + hstepA, voffA);
;             PG8_WAIT_V(8); PG8_WAIT_L(0); PG8_BAR; PG8_MMA(0, 0, At, B0); PG8_MMA(0, 1, At, B1); PG8_BAR; PG8_SCHED;
;             PG8_LDA(At, 0, 1); PG8_STAGE(PG8_SB(0, 0), b2, voffB); PG8_STAGE(PG8_SB(0, 1), b2 + hstepB, voffB); PG8_STAGE(PG8_SA(0, 0), a2, voffA);
;             PG8_WAIT_V(8); PG8_WAIT_L(0); PG8_BAR; PG8_MMA(1, 0, At, B0); PG8_MMA(1, 1, At, B1); PG8_BAR; PG8_SCHED;
.Lfirst_iter_u611:
	s_add_u32 s22, s20, 0xfffc0080
	s_addc_u32 s23, s21, -1
	s_add_i32 s48, 0, 0x10000
	s_cmp_eq_u32 s47, 12
	s_cselect_b32 s25, s13, s23
	s_cselect_b32 s24, s43, s22
	v_add_u32_e32 v0, s48, v141
	s_cselect_b32 s23, s11, s46
	s_cselect_b32 s22, s44, s45
	s_add_i32 s52, 0, 0x14000
	ds_read_b128 v[144:147], v0
	ds_read_b128 v[148:151], v0 offset:1024
	ds_read_b128 v[152:155], v0 offset:2048
	ds_read_b128 v[156:159], v0 offset:3072
	v_add_u32_e32 v0, s52, v141
	ds_read_b128 v[170:173], v0
	ds_read_b128 v[174:177], v0 offset:1024
	ds_read_b128 v[178:181], v0 offset:2048
	ds_read_b128 v[182:185], v0 offset:3072
	v_lshl_add_u64 v[160:161], s[20:21], 0, v[134:135]
	s_add_i32 m0, s34, 0xc000
	ds_read_b128 v[186:189], v142
	ds_read_b128 v[206:209], v142 offset:1024
	ds_read_b128 v[210:213], v142 offset:2048
	ds_read_b128 v[214:217], v142 offset:3072
	ds_read_b128 v[218:221], v142 offset:4096
	ds_read_b128 v[222:225], v142 offset:5120
	ds_read_b128 v[226:229], v142 offset:6144
	ds_read_b128 v[230:233], v142 offset:7168
	global_load_lds_dwordx4 v[160:161], off
	v_lshl_add_u64 v[160:161], s[20:21], 0, v[136:137]
	s_add_i32 m0, s34, 0xe000
	s_nop 0
	global_load_lds_dwordx4 v[160:161], off
	s_waitcnt vmcnt(8)
	s_waitcnt lgkmcnt(0)
	s_barrier
	s_setprio 1
	s_waitcnt lgkmcnt(0)
	v_mfma_f32_16x16x32_bf16 v[126:129], v[144:147], v[186:189], 0
	v_mfma_f32_16x16x32_bf16 v[118:121], v[152:155], v[186:189], 0
	v_mfma_f32_16x16x32_bf16 v[110:113], v[144:147], v[210:213], 0
	v_mfma_f32_16x16x32_bf16 v[102:105], v[152:155], v[210:213], 0
	v_mfma_f32_16x16x32_bf16 v[94:97], v[144:147], v[218:221], 0
	v_mfma_f32_16x16x32_bf16 v[86:89], v[152:155], v[218:221], 0
	v_mfma_f32_16x16x32_bf16 v[78:81], v[144:147], v[226:229], 0
	v_mfma_f32_16x16x32_bf16 v[70:73], v[152:155], v[226:229], 0
	s_setprio 0
	s_setprio 1
	v_mfma_f32_16x16x32_bf16 v[126:129], v[148:151], v[206:209], v[126:129]
	v_mfma_f32_16x16x32_bf16 v[118:121], v[156:159], v[206:209], v[118:121]
	v_mfma_f32_16x16x32_bf16 v[110:113], v[148:151], v[214:217], v[110:113]
	v_mfma_f32_16x16x32_bf16 v[102:105], v[156:159], v[214:217], v[102:105]
	v_mfma_f32_16x16x32_bf16 v[94:97], v[148:151], v[222:225], v[94:97]
	v_mfma_f32_16x16x32_bf16 v[86:89], v[156:159], v[222:225], v[86:89]
	v_mfma_f32_16x16x32_bf16 v[78:81], v[148:151], v[230:233], v[78:81]
	v_mfma_f32_16x16x32_bf16 v[70:73], v[156:159], v[230:233], v[70:73]
	s_setprio 0
	s_setprio 1
	v_mfma_f32_16x16x32_bf16 v[122:125], v[170:173], v[186:189], 0
	v_mfma_f32_16x16x32_bf16 v[114:117], v[178:181], v[186:189], 0
	v_mfma_f32_16x16x32_bf16 v[106:109], v[170:173], v[210:213], 0
	v_mfma_f32_16x16x32_bf16 v[98:101], v[178:181], v[210:213], 0
	v_mfma_f32_16x16x32_bf16 v[90:93], v[170:173], v[218:221], 0
	v_mfma_f32_16x16x32_bf16 v[82:85], v[178:181], v[218:221], 0
	v_mfma_f32_16x16x32_bf16 v[74:77], v[170:173], v[226:229], 0
	v_mfma_f32_16x16x32_bf16 v[66:69], v[178:181], v[226:229], 0
	s_setprio 0
	s_setprio 1
	v_mfma_f32_16x16x32_bf16 v[122:125], v[174:177], v[206:209], v[122:125]
	v_mfma_f32_16x16x32_bf16 v[114:117], v[182:185], v[206:209], v[114:117]
	v_mfma_f32_16x16x32_bf16 v[106:109], v[174:177], v[214:217], v[106:109]
	v_mfma_f32_16x16x32_bf16 v[98:101], v[182:185], v[214:217], v[98:101]
	v_mfma_f32_16x16x32_bf16 v[90:93], v[174:177], v[222:225], v[90:93]
	v_mfma_f32_16x16x32_bf16 v[82:85], v[182:185], v[222:225], v[82:85]
	v_mfma_f32_16x16x32_bf16 v[74:77], v[174:177], v[230:233], v[74:77]
	v_mfma_f32_16x16x32_bf16 v[66:69], v[182:185], v[230:233], v[66:69]
	s_setprio 0
	s_barrier
	s_add_i32 s48, s48, s33
	v_lshl_add_u64 v[160:161], s[22:23], 0, v[130:131]
	s_mov_b32 m0, s48
	ds_read_b128 v[186:189], v142 offset:16384
	ds_read_b128 v[206:209], v142 offset:17408
	ds_read_b128 v[210:213], v142 offset:18432
	ds_read_b128 v[214:217], v142 offset:19456
	ds_read_b128 v[218:221], v142 offset:20480
	ds_read_b128 v[222:225], v142 offset:21504
	ds_read_b128 v[226:229], v142 offset:22528
	ds_read_b128 v[230:233], v142 offset:23552
	global_load_lds_dwordx4 v[160:161], off
	s_add_i32 m0, s48, 0x2000
	s_add_u32 s48, s22, 0x40000
	v_lshl_add_u64 v[164:165], s[22:23], 0, v[132:133]
	s_addc_u32 s49, s23, 0
	s_add_i32 s52, s52, s33
	global_load_lds_dwordx4 v[164:165], off
	v_lshl_add_u64 v[166:167], s[48:49], 0, v[130:131]
	s_mov_b32 m0, s52
	v_lshl_add_u64 v[194:195], s[24:25], 0, v[132:133]
	global_load_lds_dwordx4 v[166:167], off
	v_lshl_add_u64 v[166:167], s[48:49], 0, v[132:133]
	s_add_i32 m0, s52, 0x2000
	s_nop 0
	global_load_lds_dwordx4 v[166:167], off
	v_lshl_add_u64 v[166:167], s[24:25], 0, v[130:131]
	s_mov_b32 m0, s34
	s_nop 0
	global_load_lds_dwordx4 v[166:167], off
	s_mov_b32 m0, s35
	s_nop 0
	global_load_lds_dwordx4 v[194:195], off
	s_waitcnt vmcnt(8)
	s_waitcnt lgkmcnt(0)
	s_barrier
; #define PG8_STAGE(bufoff, gbase, voff) do { _Pragma("unroll") for (int _i = 0; _i < 2; ++_i) \
;         __builtin_amdgcn_global_load_lds((const unsigned*)((const char*)(gbase) + (voff)[_i]), (LAS unsigned*)(lds + (bufoff) + ldsw + _i * 8192), 16, 0, 0); } while (0)
; #define PG8_LDA(dst, b, h) do { _Pragma("unroll") for (int m = 0; m < 4; ++m) _Pragma("unroll") for (int k = 0; k < 2; ++k) dst[m][k] = *(const LAS bf16x8*)(lds + PG8_SA(b, h) + aoff + m * 2048 + k * 1024); } while (0)
; #define PG8_LDB(dst, b, h) do { _Pragma("unroll") for (int n = 0; n < 2; ++n) _Pragma("unroll") for (int k = 0; k < 2; ++k) dst[n][k] = *(const LAS bf16x8*)(lds + PG8_SB(b, h) + boff + n * 2048 + k * 1024); } while (0)
; #define PG8_MMA(ai, bj, At, Bt) do { __builtin_amdgcn_s_setprio(1); _Pragma("unroll") for (int m = 0; m < 4; ++m) _Pragma("unroll") for (int n = 0; n < 2; ++n) _Pragma("unroll") for (int k = 0; k < 2; ++k) \
;         acc[ai][bj][m][n] = __builtin_amdgcn_mfma_f32_16x16x32_bf16(Bt[n][k], At[m][k], acc[ai][bj][m][n], 0, 0, 0); __builtin_amdgcn_s_setprio(0); } while (0)
; #define PG8_WAIT_V(n) asm volatile("s_waitcnt vmcnt(" #n ")" ::: "memory")
; #define PG8_WAIT_L(n) asm volatile("s_waitcnt lgkmcnt(" #n ")" ::: "memory")
; #define PG8_BAR __builtin_amdgcn_s_barrier()
; #define PG8_SCHED __builtin_amdgcn_sched_barrier(0)
; template <class Epi, bool ALIGN_EPI = PG8_ALIGN, bool SP2 = PG8_SP2>
; __device__ __forceinline__ void gemm_phase(LAS unsigned char* lds, const Gemm g, const StaticOrder& S, const Epi& E) {
;     ...
;             PG8_WAIT_V(8); PG8_WAIT_L(0); PG8_BAR; PG8_MMA(1, 0, At, B0); PG8_MMA(1, 1, At, B1); PG8_BAR; PG8_SCHED;
;             PG8_LDB(B0, 1, 0); PG8_LDB(B1, 1, 1); PG8_SCHED; PG8_LDA(At, 1, 0); PG8_STAGE(PG8_SA(0, 1), a2 + hstepA, voffA);
;             PG8_WAIT_V(8); PG8_WAIT_L(0); PG8_BAR; PG8_MMA(0, 0, At, B0); PG8_MMA(0, 1, At, B1); PG8_BAR; PG8_SCHED;
	s_setprio 1
	s_waitcnt lgkmcnt(0)
	v_mfma_f32_16x16x32_bf16 v[62:65], v[144:147], v[186:189], 0
	v_mfma_f32_16x16x32_bf16 v[54:57], v[152:155], v[186:189], 0
	v_mfma_f32_16x16x32_bf16 v[46:49], v[144:147], v[210:213], 0
	v_mfma_f32_16x16x32_bf16 v[38:41], v[152:155], v[210:213], 0
	v_mfma_f32_16x16x32_bf16 v[30:33], v[144:147], v[218:221], 0
	v_mfma_f32_16x16x32_bf16 v[22:25], v[152:155], v[218:221], 0
	v_mfma_f32_16x16x32_bf16 v[14:17], v[144:147], v[226:229], 0
	v_mfma_f32_16x16x32_bf16 v[6:9], v[152:155], v[226:229], 0
	s_setprio 0
	s_setprio 1
	v_mfma_f32_16x16x32_bf16 v[62:65], v[148:151], v[206:209], v[62:65]
	v_mfma_f32_16x16x32_bf16 v[54:57], v[156:159], v[206:209], v[54:57]
	v_mfma_f32_16x16x32_bf16 v[46:49], v[148:151], v[214:217], v[46:49]
	v_mfma_f32_16x16x32_bf16 v[38:41], v[156:159], v[214:217], v[38:41]
	v_mfma_f32_16x16x32_bf16 v[30:33], v[148:151], v[222:225], v[30:33]
	v_mfma_f32_16x16x32_bf16 v[22:25], v[156:159], v[222:225], v[22:25]
	v_mfma_f32_16x16x32_bf16 v[14:17], v[148:151], v[230:233], v[14:17]
	v_mfma_f32_16x16x32_bf16 v[6:9], v[156:159], v[230:233], v[6:9]
	s_setprio 0
	s_setprio 1
	v_mfma_f32_16x16x32_bf16 v[58:61], v[170:173], v[186:189], 0
	v_mfma_f32_16x16x32_bf16 v[50:53], v[178:181], v[186:189], 0
	v_mfma_f32_16x16x32_bf16 v[42:45], v[170:173], v[210:213], 0
	v_mfma_f32_16x16x32_bf16 v[34:37], v[178:181], v[210:213], 0
	v_mfma_f32_16x16x32_bf16 v[26:29], v[170:173], v[218:221], 0
	v_mfma_f32_16x16x32_bf16 v[18:21], v[178:181], v[218:221], 0
	v_mfma_f32_16x16x32_bf16 v[10:13], v[170:173], v[226:229], 0
	v_mfma_f32_16x16x32_bf16 v[2:5], v[178:181], v[226:229], 0
	s_setprio 0
	s_setprio 1
	v_mfma_f32_16x16x32_bf16 v[58:61], v[174:177], v[206:209], v[58:61]
	v_mfma_f32_16x16x32_bf16 v[50:53], v[182:185], v[206:209], v[50:53]
	v_mfma_f32_16x16x32_bf16 v[42:45], v[174:177], v[214:217], v[42:45]
	v_mfma_f32_16x16x32_bf16 v[34:37], v[182:185], v[214:217], v[34:37]
	v_mfma_f32_16x16x32_bf16 v[26:29], v[174:177], v[222:225], v[26:29]
	v_mfma_f32_16x16x32_bf16 v[18:21], v[182:185], v[222:225], v[18:21]
	v_mfma_f32_16x16x32_bf16 v[10:13], v[174:177], v[230:233], v[10:13]
	v_mfma_f32_16x16x32_bf16 v[2:5], v[182:185], v[230:233], v[2:5]
	s_setprio 0
	s_barrier
	s_add_i32 s48, 0, 0x18000
	v_add_u32_e32 v0, s48, v141
	s_add_i32 s49, 0, 0x1c000
	ds_read_b128 v[144:147], v0
	ds_read_b128 v[148:151], v0 offset:1024
	ds_read_b128 v[152:155], v0 offset:2048
	ds_read_b128 v[156:159], v0 offset:3072
	v_add_u32_e32 v0, s49, v141
	ds_read_b128 v[170:173], v0
	ds_read_b128 v[174:177], v0 offset:1024
	ds_read_b128 v[178:181], v0 offset:2048
	ds_read_b128 v[182:185], v0 offset:3072
	s_add_u32 s24, s24, 0x40000
	s_addc_u32 s25, s25, 0
	s_mov_b32 m0, s36
	v_lshl_add_u64 v[196:197], s[24:25], 0, v[130:131]
	ds_read_b128 v[186:189], v142 offset:32768
	ds_read_b128 v[206:209], v142 offset:33792
	ds_read_b128 v[210:213], v142 offset:34816
	ds_read_b128 v[214:217], v142 offset:35840
	ds_read_b128 v[218:221], v142 offset:36864
	ds_read_b128 v[222:225], v142 offset:37888
	ds_read_b128 v[226:229], v142 offset:38912
	ds_read_b128 v[230:233], v142 offset:39936
	global_load_lds_dwordx4 v[196:197], off
	v_lshl_add_u64 v[196:197], s[24:25], 0, v[132:133]
	s_mov_b32 m0, s37
	s_nop 0
	global_load_lds_dwordx4 v[196:197], off
	s_waitcnt vmcnt(8)
	s_waitcnt lgkmcnt(0)
	s_barrier
	s_setprio 1
	s_waitcnt lgkmcnt(0)
	v_mfma_f32_16x16x32_bf16 v[126:129], v[144:147], v[186:189], v[126:129]
	v_mfma_f32_16x16x32_bf16 v[118:121], v[152:155], v[186:189], v[118:121]
	v_mfma_f32_16x16x32_bf16 v[110:113], v[144:147], v[210:213], v[110:113]
	v_mfma_f32_16x16x32_bf16 v[102:105], v[152:155], v[210:213], v[102:105]
	v_mfma_f32_16x16x32_bf16 v[94:97], v[144:147], v[218:221], v[94:97]
	v_mfma_f32_16x16x32_bf16 v[86:89], v[152:155], v[218:221], v[86:89]
	v_mfma_f32_16x16x32_bf16 v[78:81], v[144:147], v[226:229], v[78:81]
	v_mfma_f32_16x16x32_bf16 v[70:73], v[152:155], v[226:229], v[70:73]
	s_setprio 0
	s_setprio 1
	v_mfma_f32_16x16x32_bf16 v[126:129], v[148:151], v[206:209], v[126:129]
	v_mfma_f32_16x16x32_bf16 v[118:121], v[156:159], v[206:209], v[118:121]
	v_mfma_f32_16x16x32_bf16 v[110:113], v[148:151], v[214:217], v[110:113]
	v_mfma_f32_16x16x32_bf16 v[102:105], v[156:159], v[214:217], v[102:105]
	v_mfma_f32_16x16x32_bf16 v[94:97], v[148:151], v[222:225], v[94:97]
	v_mfma_f32_16x16x32_bf16 v[86:89], v[156:159], v[222:225], v[86:89]
	v_mfma_f32_16x16x32_bf16 v[78:81], v[148:151], v[230:233], v[78:81]
	v_mfma_f32_16x16x32_bf16 v[70:73], v[156:159], v[230:233], v[70:73]
	s_setprio 0
	s_setprio 1
	v_mfma_f32_16x16x32_bf16 v[122:125], v[170:173], v[186:189], v[122:125]
	v_mfma_f32_16x16x32_bf16 v[114:117], v[178:181], v[186:189], v[114:117]
	v_mfma_f32_16x16x32_bf16 v[106:109], v[170:173], v[210:213], v[106:109]
	v_mfma_f32_16x16x32_bf16 v[98:101], v[178:181], v[210:213], v[98:101]
	v_mfma_f32_16x16x32_bf16 v[90:93], v[170:173], v[218:221], v[90:93]
	v_mfma_f32_16x16x32_bf16 v[82:85], v[178:181], v[218:221], v[82:85]
	v_mfma_f32_16x16x32_bf16 v[74:77], v[170:173], v[226:229], v[74:77]
	v_mfma_f32_16x16x32_bf16 v[66:69], v[178:181], v[226:229], v[66:69]
	s_setprio 0
	s_setprio 1
	v_mfma_f32_16x16x32_bf16 v[122:125], v[174:177], v[206:209], v[122:125]
	v_mfma_f32_16x16x32_bf16 v[114:117], v[182:185], v[206:209], v[114:117]
	v_mfma_f32_16x16x32_bf16 v[106:109], v[174:177], v[214:217], v[106:109]
	v_mfma_f32_16x16x32_bf16 v[98:101], v[182:185], v[214:217], v[98:101]
	v_mfma_f32_16x16x32_bf16 v[90:93], v[174:177], v[222:225], v[90:93]
	v_mfma_f32_16x16x32_bf16 v[82:85], v[182:185], v[222:225], v[82:85]
	v_mfma_f32_16x16x32_bf16 v[74:77], v[174:177], v[230:233], v[74:77]
	v_mfma_f32_16x16x32_bf16 v[66:69], v[182:185], v[230:233], v[66:69]
	s_setprio 0
	s_barrier
; #define PG8_STAGE(bufoff, gbase, voff) do { _Pragma("unroll") for (int _i = 0; _i < 2; ++_i) \
;         __builtin_amdgcn_global_load_lds((const unsigned*)((const char*)(gbase) + (voff)[_i]), (LAS unsigned*)(lds + (bufoff) + ldsw + _i * 8192), 16, 0, 0); } while (0)
; #define PG8_LDA(dst, b, h) do { _Pragma("unroll") for (int m = 0; m < 4; ++m) _Pragma("unroll") for (int k = 0; k < 2; ++k) dst[m][k] = *(const LAS bf16x8*)(lds + PG8_SA(b, h) + aoff + m * 2048 + k * 1024); } while (0)
; #define PG8_MMA(ai, bj, At, Bt) do { __builtin_amdgcn_s_setprio(1); _Pragma("unroll") for (int m = 0; m < 4; ++m) _Pragma("unroll") for (int n = 0; n < 2; ++n) _Pragma("unroll") for (int k = 0; k < 2; ++k) \
;         acc[ai][bj][m][n] = __builtin_amdgcn_mfma_f32_16x16x32_bf16(Bt[n][k], At[m][k], acc[ai][bj][m][n], 0, 0, 0); __builtin_amdgcn_s_setprio(0); } while (0)
; #define PG8_WAIT_V(n) asm volatile("s_waitcnt vmcnt(" #n ")" ::: "memory")
; #define PG8_WAIT_L(n) asm volatile("s_waitcnt lgkmcnt(" #n ")" ::: "memory")
; #define PG8_BAR __builtin_amdgcn_s_barrier()
; #define PG8_SCHED __builtin_amdgcn_sched_barrier(0)
; template <class Epi, bool ALIGN_EPI = PG8_ALIGN, bool SP2 = PG8_SP2>
; __device__ __forceinline__ void gemm_phase(LAS unsigned char* lds, const Gemm g, const StaticOrder& S, const Epi& E) {
;     ...
;             PG8_LDA(At, 1, 1); PG8_STAGE(PG8_SB(1, 0), b3, voffB); PG8_STAGE(PG8_SB(1, 1), b3 + hstepB, voffB); PG8_STAGE(PG8_SA(1, 0), a3, voffA);
;             PG8_WAIT_V(8); PG8_WAIT_L(0); PG8_BAR; PG8_MMA(1, 0, At, B0); PG8_MMA(1, 1, At, B1); PG8_BAR; PG8_SCHED;
	s_add_i32 s24, s48, s33
	v_lshl_add_u64 v[160:161], v[160:161], 0, s[50:51]
	s_mov_b32 m0, s24
	ds_read_b128 v[186:189], v142 offset:49152
	ds_read_b128 v[206:209], v142 offset:50176
	ds_read_b128 v[210:213], v142 offset:51200
	ds_read_b128 v[214:217], v142 offset:52224
	ds_read_b128 v[218:221], v142 offset:53248
	ds_read_b128 v[222:225], v142 offset:54272
	ds_read_b128 v[226:229], v142 offset:55296
	ds_read_b128 v[230:233], v142 offset:56320
	global_load_lds_dwordx4 v[160:161], off
	s_add_i32 m0, s24, 0x2000
	s_add_u32 s22, s22, 0x40080
	v_lshl_add_u64 v[160:161], v[164:165], 0, s[50:51]
	s_addc_u32 s23, s23, 0
	s_add_i32 s24, s49, s33
	global_load_lds_dwordx4 v[160:161], off
	v_lshl_add_u64 v[160:161], s[22:23], 0, v[130:131]
	s_mov_b32 m0, s24
	s_nop 0
	global_load_lds_dwordx4 v[160:161], off
	v_lshl_add_u64 v[160:161], s[22:23], 0, v[132:133]
	s_add_i32 m0, s24, 0x2000
	s_nop 0
	global_load_lds_dwordx4 v[160:161], off
	v_lshl_add_u64 v[160:161], v[166:167], 0, s[50:51]
	s_mov_b32 m0, s40
	s_nop 0
	global_load_lds_dwordx4 v[160:161], off
	v_lshl_add_u64 v[160:161], v[194:195], 0, s[50:51]
	s_mov_b32 m0, s41
	s_nop 0
	global_load_lds_dwordx4 v[160:161], off
	s_waitcnt vmcnt(8)
	s_waitcnt lgkmcnt(0)
	s_barrier
	s_setprio 1
	s_waitcnt lgkmcnt(0)
	v_mfma_f32_16x16x32_bf16 v[62:65], v[144:147], v[186:189], v[62:65]
	v_mfma_f32_16x16x32_bf16 v[54:57], v[152:155], v[186:189], v[54:57]
	v_mfma_f32_16x16x32_bf16 v[46:49], v[144:147], v[210:213], v[46:49]
	v_mfma_f32_16x16x32_bf16 v[38:41], v[152:155], v[210:213], v[38:41]
	v_mfma_f32_16x16x32_bf16 v[30:33], v[144:147], v[218:221], v[30:33]
	v_mfma_f32_16x16x32_bf16 v[22:25], v[152:155], v[218:221], v[22:25]
	v_mfma_f32_16x16x32_bf16 v[14:17], v[144:147], v[226:229], v[14:17]
	v_mfma_f32_16x16x32_bf16 v[6:9], v[152:155], v[226:229], v[6:9]
	s_setprio 0
	s_setprio 1
	v_mfma_f32_16x16x32_bf16 v[62:65], v[148:151], v[206:209], v[62:65]
	v_mfma_f32_16x16x32_bf16 v[54:57], v[156:159], v[206:209], v[54:57]
	v_mfma_f32_16x16x32_bf16 v[46:49], v[148:151], v[214:217], v[46:49]
	v_mfma_f32_16x16x32_bf16 v[38:41], v[156:159], v[214:217], v[38:41]
	v_mfma_f32_16x16x32_bf16 v[30:33], v[148:151], v[222:225], v[30:33]
	v_mfma_f32_16x16x32_bf16 v[22:25], v[156:159], v[222:225], v[22:25]
	v_mfma_f32_16x16x32_bf16 v[14:17], v[148:151], v[230:233], v[14:17]
	v_mfma_f32_16x16x32_bf16 v[6:9], v[156:159], v[230:233], v[6:9]
	s_setprio 0
	s_setprio 1
	v_mfma_f32_16x16x32_bf16 v[58:61], v[170:173], v[186:189], v[58:61]
	v_mfma_f32_16x16x32_bf16 v[50:53], v[178:181], v[186:189], v[50:53]
	v_mfma_f32_16x16x32_bf16 v[42:45], v[170:173], v[210:213], v[42:45]
	v_mfma_f32_16x16x32_bf16 v[34:37], v[178:181], v[210:213], v[34:37]
	v_mfma_f32_16x16x32_bf16 v[26:29], v[170:173], v[218:221], v[26:29]
	v_mfma_f32_16x16x32_bf16 v[18:21], v[178:181], v[218:221], v[18:21]
	v_mfma_f32_16x16x32_bf16 v[10:13], v[170:173], v[226:229], v[10:13]
	v_mfma_f32_16x16x32_bf16 v[2:5], v[178:181], v[226:229], v[2:5]
	s_setprio 0
	s_setprio 1
	v_mfma_f32_16x16x32_bf16 v[58:61], v[174:177], v[206:209], v[58:61]
	v_mfma_f32_16x16x32_bf16 v[50:53], v[182:185], v[206:209], v[50:53]
	v_mfma_f32_16x16x32_bf16 v[42:45], v[174:177], v[214:217], v[42:45]
	v_mfma_f32_16x16x32_bf16 v[34:37], v[182:185], v[214:217], v[34:37]
	v_mfma_f32_16x16x32_bf16 v[26:29], v[174:177], v[222:225], v[26:29]
	v_mfma_f32_16x16x32_bf16 v[18:21], v[182:185], v[222:225], v[18:21]
	v_mfma_f32_16x16x32_bf16 v[10:13], v[174:177], v[230:233], v[10:13]
	v_mfma_f32_16x16x32_bf16 v[2:5], v[182:185], v[230:233], v[2:5]
	s_setprio 0
	s_barrier
	s_add_i32 s47, s47, 2
	s_add_u32 s20, s20, 0x100
	s_addc_u32 s21, s21, 0
	s_add_u32 s45, s45, 0x100
	s_addc_u32 s46, s46, 0
	s_cmp_gt_u32 s47, 13
	s_branch .LBB0_611
